# early-arrive: MMA segment closing s_barrier moved before its last 4 MFMAs, trailing MFMAs at s_setprio 3 (all 12 GEMM K-loops)
# baseline (speedup 1.0000x reference)
.LBB0_120:
	ds_read_b128 v[128:131], v178
	ds_read_b128 v[132:135], v178 offset:1024
	ds_read_b128 v[154:157], v178 offset:2048
	ds_read_b128 v[158:161], v178 offset:3072
	ds_read_b128 v[162:165], v179
	ds_read_b128 v[166:169], v179 offset:1024
	ds_read_b128 v[182:185], v179 offset:2048
	ds_read_b128 v[186:189], v179 offset:3072
	s_add_u32 s67, s88, 0xfffc0080
	s_addc_u32 s68, s89, -1
	s_cmp_eq_u32 s66, 12
	s_cselect_b32 s93, s52, s68
	s_cselect_b32 s92, s53, s67
	s_cselect_b32 s91, s56, s59
	s_cselect_b32 s90, s57, s58
	v_lshl_add_u64 v[170:171], s[88:89], 0, v[144:145]
	s_add_i32 m0, s17, 0xc000
	ds_read_b128 v[190:193], v180
	ds_read_b128 v[194:197], v180 offset:1024
	ds_read_b128 v[198:201], v180 offset:2048
	ds_read_b128 v[202:205], v180 offset:3072
	ds_read_b128 v[206:209], v180 offset:4096
	ds_read_b128 v[210:213], v180 offset:5120
	ds_read_b128 v[214:217], v180 offset:6144
	ds_read_b128 v[218:221], v180 offset:7168
	global_load_lds_dwordx4 v[170:171], off
	v_lshl_add_u64 v[170:171], s[88:89], 0, v[148:149]
	s_add_i32 m0, s17, 0xe000
	s_nop 0
	global_load_lds_dwordx4 v[170:171], off
	s_waitcnt vmcnt(8)
	s_waitcnt lgkmcnt(0)
	s_barrier
	s_setprio 1
	s_waitcnt lgkmcnt(0)
	v_mfma_f32_16x16x32_bf16 v[124:127], v[128:131], v[190:193], v[124:127]
	v_mfma_f32_16x16x32_bf16 v[116:119], v[154:157], v[190:193], v[116:119]
	v_mfma_f32_16x16x32_bf16 v[108:111], v[128:131], v[198:201], v[108:111]
	v_mfma_f32_16x16x32_bf16 v[100:103], v[154:157], v[198:201], v[100:103]
	v_mfma_f32_16x16x32_bf16 v[92:95], v[128:131], v[206:209], v[92:95]
	v_mfma_f32_16x16x32_bf16 v[84:87], v[154:157], v[206:209], v[84:87]
	v_mfma_f32_16x16x32_bf16 v[76:79], v[128:131], v[214:217], v[76:79]
	v_mfma_f32_16x16x32_bf16 v[68:71], v[154:157], v[214:217], v[68:71]
	v_mfma_f32_16x16x32_bf16 v[124:127], v[132:135], v[194:197], v[124:127]
	v_mfma_f32_16x16x32_bf16 v[116:119], v[158:161], v[194:197], v[116:119]
	v_mfma_f32_16x16x32_bf16 v[108:111], v[132:135], v[202:205], v[108:111]
	v_mfma_f32_16x16x32_bf16 v[100:103], v[158:161], v[202:205], v[100:103]
	v_mfma_f32_16x16x32_bf16 v[92:95], v[132:135], v[210:213], v[92:95]
	v_mfma_f32_16x16x32_bf16 v[84:87], v[158:161], v[210:213], v[84:87]
	v_mfma_f32_16x16x32_bf16 v[76:79], v[132:135], v[218:221], v[76:79]
	v_mfma_f32_16x16x32_bf16 v[68:71], v[158:161], v[218:221], v[68:71]
	s_setprio 0
	s_setprio 1
	v_mfma_f32_16x16x32_bf16 v[120:123], v[162:165], v[190:193], v[120:123]
	v_mfma_f32_16x16x32_bf16 v[112:115], v[182:185], v[190:193], v[112:115]
	v_mfma_f32_16x16x32_bf16 v[104:107], v[162:165], v[198:201], v[104:107]
	v_mfma_f32_16x16x32_bf16 v[96:99], v[182:185], v[198:201], v[96:99]
	v_mfma_f32_16x16x32_bf16 v[88:91], v[162:165], v[206:209], v[88:91]
	v_mfma_f32_16x16x32_bf16 v[80:83], v[182:185], v[206:209], v[80:83]
	v_mfma_f32_16x16x32_bf16 v[72:75], v[162:165], v[214:217], v[72:75]
	v_mfma_f32_16x16x32_bf16 v[64:67], v[182:185], v[214:217], v[64:67]
	v_mfma_f32_16x16x32_bf16 v[120:123], v[166:169], v[194:197], v[120:123]
	v_mfma_f32_16x16x32_bf16 v[112:115], v[186:189], v[194:197], v[112:115]
	v_mfma_f32_16x16x32_bf16 v[104:107], v[166:169], v[202:205], v[104:107]
	v_mfma_f32_16x16x32_bf16 v[96:99], v[186:189], v[202:205], v[96:99]
	s_setprio 3
	s_barrier
	v_mfma_f32_16x16x32_bf16 v[88:91], v[166:169], v[210:213], v[88:91]
	v_mfma_f32_16x16x32_bf16 v[80:83], v[186:189], v[210:213], v[80:83]
	v_mfma_f32_16x16x32_bf16 v[72:75], v[166:169], v[218:221], v[72:75]
	v_mfma_f32_16x16x32_bf16 v[64:67], v[186:189], v[218:221], v[64:67]
	s_setprio 0
	s_add_i32 s67, s25, s16
	v_lshl_add_u64 v[170:171], s[90:91], 0, v[140:141]
	s_mov_b32 m0, s67
	ds_read_b128 v[190:193], v180 offset:16384
	ds_read_b128 v[194:197], v180 offset:17408
	ds_read_b128 v[198:201], v180 offset:18432
	ds_read_b128 v[202:205], v180 offset:19456
	ds_read_b128 v[206:209], v180 offset:20480
	ds_read_b128 v[210:213], v180 offset:21504
	ds_read_b128 v[214:217], v180 offset:22528
	ds_read_b128 v[218:221], v180 offset:23552
	global_load_lds_dwordx4 v[170:171], off
	s_add_i32 m0, s67, 0x2000
	s_add_u32 s68, s90, 0x40000
	v_lshl_add_u64 v[222:223], s[90:91], 0, v[136:137]
	s_addc_u32 s69, s91, 0
	s_add_i32 s67, s26, s16
	global_load_lds_dwordx4 v[222:223], off
	v_lshl_add_u64 v[224:225], s[68:69], 0, v[140:141]
	s_mov_b32 m0, s67
	v_lshl_add_u64 v[226:227], s[92:93], 0, v[138:139]
	global_load_lds_dwordx4 v[224:225], off
	v_lshl_add_u64 v[224:225], s[68:69], 0, v[136:137]
	s_add_i32 m0, s67, 0x2000
	s_nop 0
	global_load_lds_dwordx4 v[224:225], off
	v_lshl_add_u64 v[224:225], s[92:93], 0, v[142:143]
	s_mov_b32 m0, s17
	s_nop 0
	global_load_lds_dwordx4 v[224:225], off
	s_mov_b32 m0, s18
	s_nop 0
	global_load_lds_dwordx4 v[226:227], off
	s_waitcnt vmcnt(8)
	s_waitcnt lgkmcnt(0)
	s_barrier
	s_setprio 1
	s_waitcnt lgkmcnt(0)
	v_mfma_f32_16x16x32_bf16 v[60:63], v[128:131], v[190:193], v[60:63]
	v_mfma_f32_16x16x32_bf16 v[52:55], v[154:157], v[190:193], v[52:55]
	v_mfma_f32_16x16x32_bf16 v[44:47], v[128:131], v[198:201], v[44:47]
	v_mfma_f32_16x16x32_bf16 v[36:39], v[154:157], v[198:201], v[36:39]
	v_mfma_f32_16x16x32_bf16 v[28:31], v[128:131], v[206:209], v[28:31]
	v_mfma_f32_16x16x32_bf16 v[20:23], v[154:157], v[206:209], v[20:23]
	v_mfma_f32_16x16x32_bf16 v[12:15], v[128:131], v[214:217], v[12:15]
	v_mfma_f32_16x16x32_bf16 v[4:7], v[154:157], v[214:217], v[4:7]
	v_mfma_f32_16x16x32_bf16 v[60:63], v[132:135], v[194:197], v[60:63]
	v_mfma_f32_16x16x32_bf16 v[52:55], v[158:161], v[194:197], v[52:55]
	v_mfma_f32_16x16x32_bf16 v[44:47], v[132:135], v[202:205], v[44:47]
	v_mfma_f32_16x16x32_bf16 v[36:39], v[158:161], v[202:205], v[36:39]
	v_mfma_f32_16x16x32_bf16 v[28:31], v[132:135], v[210:213], v[28:31]
	v_mfma_f32_16x16x32_bf16 v[20:23], v[158:161], v[210:213], v[20:23]
	v_mfma_f32_16x16x32_bf16 v[12:15], v[132:135], v[218:221], v[12:15]
	v_mfma_f32_16x16x32_bf16 v[4:7], v[158:161], v[218:221], v[4:7]
	s_setprio 0
	s_setprio 1
	v_mfma_f32_16x16x32_bf16 v[56:59], v[162:165], v[190:193], v[56:59]
	v_mfma_f32_16x16x32_bf16 v[48:51], v[182:185], v[190:193], v[48:51]
	v_mfma_f32_16x16x32_bf16 v[40:43], v[162:165], v[198:201], v[40:43]
	v_mfma_f32_16x16x32_bf16 v[32:35], v[182:185], v[198:201], v[32:35]
	v_mfma_f32_16x16x32_bf16 v[24:27], v[162:165], v[206:209], v[24:27]
	v_mfma_f32_16x16x32_bf16 v[16:19], v[182:185], v[206:209], v[16:19]
	v_mfma_f32_16x16x32_bf16 v[8:11], v[162:165], v[214:217], v[8:11]
	v_mfma_f32_16x16x32_bf16 v[0:3], v[182:185], v[214:217], v[0:3]
	v_mfma_f32_16x16x32_bf16 v[56:59], v[166:169], v[194:197], v[56:59]
	v_mfma_f32_16x16x32_bf16 v[48:51], v[186:189], v[194:197], v[48:51]
	v_mfma_f32_16x16x32_bf16 v[40:43], v[166:169], v[202:205], v[40:43]
	v_mfma_f32_16x16x32_bf16 v[32:35], v[186:189], v[202:205], v[32:35]
	s_setprio 3
	s_barrier
	v_mfma_f32_16x16x32_bf16 v[24:27], v[166:169], v[210:213], v[24:27]
	v_mfma_f32_16x16x32_bf16 v[16:19], v[186:189], v[210:213], v[16:19]
	v_mfma_f32_16x16x32_bf16 v[8:11], v[166:169], v[218:221], v[8:11]
	v_mfma_f32_16x16x32_bf16 v[0:3], v[186:189], v[218:221], v[0:3]
	s_setprio 0
	s_add_i32 s67, 0, 0x18000
	s_add_i32 s73, 0, 0x1c000
	v_add_u32_e32 v158, s67, v175
	v_add_u32_e32 v186, s73, v175
	ds_read_b128 v[128:131], v158
	ds_read_b128 v[132:135], v158 offset:1024
	ds_read_b128 v[154:157], v158 offset:2048
	ds_read_b128 v[158:161], v158 offset:3072
	ds_read_b128 v[162:165], v186
	ds_read_b128 v[166:169], v186 offset:1024
	ds_read_b128 v[182:185], v186 offset:2048
	ds_read_b128 v[186:189], v186 offset:3072
	s_add_u32 s68, s92, 0x40000
	s_addc_u32 s69, s93, 0
	s_mov_b32 m0, s19
	v_lshl_add_u64 v[228:229], s[68:69], 0, v[142:143]
	ds_read_b128 v[190:193], v180 offset:32768
	ds_read_b128 v[194:197], v180 offset:33792
	ds_read_b128 v[198:201], v180 offset:34816
	ds_read_b128 v[202:205], v180 offset:35840
	ds_read_b128 v[206:209], v180 offset:36864
	ds_read_b128 v[210:213], v180 offset:37888
	ds_read_b128 v[214:217], v180 offset:38912
	ds_read_b128 v[218:221], v180 offset:39936
	global_load_lds_dwordx4 v[228:229], off
	v_lshl_add_u64 v[228:229], s[68:69], 0, v[138:139]
	s_mov_b32 m0, s20
	s_nop 0
	global_load_lds_dwordx4 v[228:229], off
	s_waitcnt vmcnt(8)
	s_waitcnt lgkmcnt(0)
	s_barrier
	s_setprio 1
	s_waitcnt lgkmcnt(0)
	v_mfma_f32_16x16x32_bf16 v[124:127], v[128:131], v[190:193], v[124:127]
	v_mfma_f32_16x16x32_bf16 v[116:119], v[154:157], v[190:193], v[116:119]
	v_mfma_f32_16x16x32_bf16 v[108:111], v[128:131], v[198:201], v[108:111]
	v_mfma_f32_16x16x32_bf16 v[100:103], v[154:157], v[198:201], v[100:103]
	v_mfma_f32_16x16x32_bf16 v[92:95], v[128:131], v[206:209], v[92:95]
	v_mfma_f32_16x16x32_bf16 v[84:87], v[154:157], v[206:209], v[84:87]
	v_mfma_f32_16x16x32_bf16 v[76:79], v[128:131], v[214:217], v[76:79]
	v_mfma_f32_16x16x32_bf16 v[68:71], v[154:157], v[214:217], v[68:71]
	v_mfma_f32_16x16x32_bf16 v[124:127], v[132:135], v[194:197], v[124:127]
	v_mfma_f32_16x16x32_bf16 v[116:119], v[158:161], v[194:197], v[116:119]
	v_mfma_f32_16x16x32_bf16 v[108:111], v[132:135], v[202:205], v[108:111]
	v_mfma_f32_16x16x32_bf16 v[100:103], v[158:161], v[202:205], v[100:103]
	v_mfma_f32_16x16x32_bf16 v[92:95], v[132:135], v[210:213], v[92:95]
	v_mfma_f32_16x16x32_bf16 v[84:87], v[158:161], v[210:213], v[84:87]
	v_mfma_f32_16x16x32_bf16 v[76:79], v[132:135], v[218:221], v[76:79]
	v_mfma_f32_16x16x32_bf16 v[68:71], v[158:161], v[218:221], v[68:71]
	s_setprio 0
	s_setprio 1
	v_mfma_f32_16x16x32_bf16 v[120:123], v[162:165], v[190:193], v[120:123]
	v_mfma_f32_16x16x32_bf16 v[112:115], v[182:185], v[190:193], v[112:115]
	v_mfma_f32_16x16x32_bf16 v[104:107], v[162:165], v[198:201], v[104:107]
	v_mfma_f32_16x16x32_bf16 v[96:99], v[182:185], v[198:201], v[96:99]
	v_mfma_f32_16x16x32_bf16 v[88:91], v[162:165], v[206:209], v[88:91]
	v_mfma_f32_16x16x32_bf16 v[80:83], v[182:185], v[206:209], v[80:83]
	v_mfma_f32_16x16x32_bf16 v[72:75], v[162:165], v[214:217], v[72:75]
	v_mfma_f32_16x16x32_bf16 v[64:67], v[182:185], v[214:217], v[64:67]
	v_mfma_f32_16x16x32_bf16 v[120:123], v[166:169], v[194:197], v[120:123]
	v_mfma_f32_16x16x32_bf16 v[112:115], v[186:189], v[194:197], v[112:115]
	v_mfma_f32_16x16x32_bf16 v[104:107], v[166:169], v[202:205], v[104:107]
	v_mfma_f32_16x16x32_bf16 v[96:99], v[186:189], v[202:205], v[96:99]
	s_setprio 3
	s_barrier
	v_mfma_f32_16x16x32_bf16 v[88:91], v[166:169], v[210:213], v[88:91]
	v_mfma_f32_16x16x32_bf16 v[80:83], v[186:189], v[210:213], v[80:83]
	v_mfma_f32_16x16x32_bf16 v[72:75], v[166:169], v[218:221], v[72:75]
	v_mfma_f32_16x16x32_bf16 v[64:67], v[186:189], v[218:221], v[64:67]
	s_setprio 0
	s_add_i32 s67, s67, s16
	v_lshl_add_u64 v[170:171], v[170:171], 0, s[74:75]
	s_mov_b32 m0, s67
	ds_read_b128 v[190:193], v180 offset:49152
	ds_read_b128 v[194:197], v180 offset:50176
	ds_read_b128 v[198:201], v180 offset:51200
	ds_read_b128 v[202:205], v180 offset:52224
	ds_read_b128 v[206:209], v180 offset:53248
	ds_read_b128 v[210:213], v180 offset:54272
	ds_read_b128 v[214:217], v180 offset:55296
	ds_read_b128 v[218:221], v180 offset:56320
	global_load_lds_dwordx4 v[170:171], off
	s_add_i32 m0, s67, 0x2000
	s_add_u32 s68, s90, 0x40080
	v_lshl_add_u64 v[170:171], v[222:223], 0, s[74:75]
	s_addc_u32 s69, s91, 0
	s_add_i32 s67, s73, s16
	global_load_lds_dwordx4 v[170:171], off
	v_lshl_add_u64 v[170:171], s[68:69], 0, v[140:141]
	s_mov_b32 m0, s67
	s_nop 0
	global_load_lds_dwordx4 v[170:171], off
	v_lshl_add_u64 v[170:171], s[68:69], 0, v[136:137]
	s_add_i32 m0, s67, 0x2000
	s_nop 0
	global_load_lds_dwordx4 v[170:171], off
	v_lshl_add_u64 v[170:171], v[224:225], 0, s[74:75]
	s_mov_b32 m0, s23
	s_nop 0
	global_load_lds_dwordx4 v[170:171], off
	v_lshl_add_u64 v[170:171], v[226:227], 0, s[74:75]
	s_mov_b32 m0, s24
	s_nop 0
	global_load_lds_dwordx4 v[170:171], off
	s_waitcnt vmcnt(8)
	s_waitcnt lgkmcnt(0)
	s_barrier
	s_setprio 1
	s_waitcnt lgkmcnt(0)
	v_mfma_f32_16x16x32_bf16 v[60:63], v[128:131], v[190:193], v[60:63]
	v_mfma_f32_16x16x32_bf16 v[52:55], v[154:157], v[190:193], v[52:55]
	v_mfma_f32_16x16x32_bf16 v[44:47], v[128:131], v[198:201], v[44:47]
	v_mfma_f32_16x16x32_bf16 v[36:39], v[154:157], v[198:201], v[36:39]
	v_mfma_f32_16x16x32_bf16 v[28:31], v[128:131], v[206:209], v[28:31]
	v_mfma_f32_16x16x32_bf16 v[20:23], v[154:157], v[206:209], v[20:23]
	v_mfma_f32_16x16x32_bf16 v[12:15], v[128:131], v[214:217], v[12:15]
	v_mfma_f32_16x16x32_bf16 v[4:7], v[154:157], v[214:217], v[4:7]
	v_mfma_f32_16x16x32_bf16 v[60:63], v[132:135], v[194:197], v[60:63]
	v_mfma_f32_16x16x32_bf16 v[52:55], v[158:161], v[194:197], v[52:55]
	v_mfma_f32_16x16x32_bf16 v[44:47], v[132:135], v[202:205], v[44:47]
	v_mfma_f32_16x16x32_bf16 v[36:39], v[158:161], v[202:205], v[36:39]
	v_mfma_f32_16x16x32_bf16 v[28:31], v[132:135], v[210:213], v[28:31]
	v_mfma_f32_16x16x32_bf16 v[20:23], v[158:161], v[210:213], v[20:23]
	v_mfma_f32_16x16x32_bf16 v[12:15], v[132:135], v[218:221], v[12:15]
	v_mfma_f32_16x16x32_bf16 v[4:7], v[158:161], v[218:221], v[4:7]
	s_setprio 0
	s_setprio 1
	v_mfma_f32_16x16x32_bf16 v[56:59], v[162:165], v[190:193], v[56:59]
	v_mfma_f32_16x16x32_bf16 v[48:51], v[182:185], v[190:193], v[48:51]
	v_mfma_f32_16x16x32_bf16 v[40:43], v[162:165], v[198:201], v[40:43]
	v_mfma_f32_16x16x32_bf16 v[32:35], v[182:185], v[198:201], v[32:35]
	v_mfma_f32_16x16x32_bf16 v[24:27], v[162:165], v[206:209], v[24:27]
	v_mfma_f32_16x16x32_bf16 v[16:19], v[182:185], v[206:209], v[16:19]
	v_mfma_f32_16x16x32_bf16 v[8:11], v[162:165], v[214:217], v[8:11]
	v_mfma_f32_16x16x32_bf16 v[0:3], v[182:185], v[214:217], v[0:3]
	v_mfma_f32_16x16x32_bf16 v[56:59], v[166:169], v[194:197], v[56:59]
	v_mfma_f32_16x16x32_bf16 v[48:51], v[186:189], v[194:197], v[48:51]
	v_mfma_f32_16x16x32_bf16 v[40:43], v[166:169], v[202:205], v[40:43]
	v_mfma_f32_16x16x32_bf16 v[32:35], v[186:189], v[202:205], v[32:35]
	s_setprio 3
	s_barrier
	v_mfma_f32_16x16x32_bf16 v[24:27], v[166:169], v[210:213], v[24:27]
	v_mfma_f32_16x16x32_bf16 v[16:19], v[186:189], v[210:213], v[16:19]
	v_mfma_f32_16x16x32_bf16 v[8:11], v[166:169], v[218:221], v[8:11]
	v_mfma_f32_16x16x32_bf16 v[0:3], v[186:189], v[218:221], v[0:3]
	s_setprio 0
	s_add_i32 s66, s66, 2
	s_add_u32 s88, s88, 0x100
	s_addc_u32 s89, s89, 0
	s_add_u32 s58, s58, 0x100
	s_addc_u32 s59, s59, 0
	s_cmp_gt_u32 s66, 13
	s_cbranch_scc0 .LBB0_120
	s_and_b64 vcc, exec, s[76:77]
	s_cbranch_vccz .LBB0_123
	s_barrier

.LBB0_272:
	ds_read_b128 v[120:123], v245
	ds_read_b128 v[124:127], v245 offset:1024
	ds_read_b128 v[128:131], v245 offset:2048
	ds_read_b128 v[132:135], v245 offset:3072
	ds_read_b128 v[144:147], v246
	ds_read_b128 v[148:151], v246 offset:1024
	ds_read_b128 v[152:155], v246 offset:2048
	ds_read_b128 v[156:159], v246 offset:3072
	s_add_u32 s59, s86, 0xfff50080
	s_addc_u32 s66, s87, -1
	s_cmp_eq_u32 s58, 40
	s_cselect_b32 s91, s11, s66
	s_cselect_b32 s90, s10, s59
	s_cselect_b32 s89, s85, s57
	s_cselect_b32 s88, s84, s56
	v_lshl_add_u64 v[204:205], s[86:87], 0, v[200:201]
	s_add_i32 m0, s16, 0xc000
	ds_read_b128 v[160:163], v247
	ds_read_b128 v[164:167], v247 offset:1024
	ds_read_b128 v[168:171], v247 offset:2048
	ds_read_b128 v[172:175], v247 offset:3072
	ds_read_b128 v[176:179], v247 offset:4096
	ds_read_b128 v[180:183], v247 offset:5120
	ds_read_b128 v[184:187], v247 offset:6144
	ds_read_b128 v[188:191], v247 offset:7168
	global_load_lds_dwordx4 v[204:205], off
	v_lshl_add_u64 v[204:205], s[86:87], 0, v[202:203]
	s_add_i32 m0, s16, 0xe000
	s_nop 0
	global_load_lds_dwordx4 v[204:205], off
	s_waitcnt vmcnt(8)
	s_waitcnt lgkmcnt(0)
	s_barrier
	s_setprio 1
	s_waitcnt lgkmcnt(0)
	v_mfma_f32_16x16x32_bf16 v[140:143], v[120:123], v[160:163], v[140:143]
	v_mfma_f32_16x16x32_bf16 v[136:139], v[128:131], v[160:163], v[136:139]
	v_mfma_f32_16x16x32_bf16 v[108:111], v[120:123], v[168:171], v[108:111]
	v_mfma_f32_16x16x32_bf16 v[104:107], v[128:131], v[168:171], v[104:107]
	v_mfma_f32_16x16x32_bf16 v[92:95], v[120:123], v[176:179], v[92:95]
	v_mfma_f32_16x16x32_bf16 v[88:91], v[128:131], v[176:179], v[88:91]
	v_mfma_f32_16x16x32_bf16 v[76:79], v[120:123], v[184:187], v[76:79]
	v_mfma_f32_16x16x32_bf16 v[72:75], v[128:131], v[184:187], v[72:75]
	v_mfma_f32_16x16x32_bf16 v[140:143], v[124:127], v[164:167], v[140:143]
	v_mfma_f32_16x16x32_bf16 v[136:139], v[132:135], v[164:167], v[136:139]
	v_mfma_f32_16x16x32_bf16 v[108:111], v[124:127], v[172:175], v[108:111]
	v_mfma_f32_16x16x32_bf16 v[104:107], v[132:135], v[172:175], v[104:107]
	v_mfma_f32_16x16x32_bf16 v[92:95], v[124:127], v[180:183], v[92:95]
	v_mfma_f32_16x16x32_bf16 v[88:91], v[132:135], v[180:183], v[88:91]
	v_mfma_f32_16x16x32_bf16 v[76:79], v[124:127], v[188:191], v[76:79]
	v_mfma_f32_16x16x32_bf16 v[72:75], v[132:135], v[188:191], v[72:75]
	s_setprio 0
	s_setprio 1
	v_mfma_f32_16x16x32_bf16 v[116:119], v[144:147], v[160:163], v[116:119]
	v_mfma_f32_16x16x32_bf16 v[112:115], v[152:155], v[160:163], v[112:115]
	v_mfma_f32_16x16x32_bf16 v[100:103], v[144:147], v[168:171], v[100:103]
	v_mfma_f32_16x16x32_bf16 v[96:99], v[152:155], v[168:171], v[96:99]
	v_mfma_f32_16x16x32_bf16 v[84:87], v[144:147], v[176:179], v[84:87]
	v_mfma_f32_16x16x32_bf16 v[80:83], v[152:155], v[176:179], v[80:83]
	v_mfma_f32_16x16x32_bf16 v[68:71], v[144:147], v[184:187], v[68:71]
	v_mfma_f32_16x16x32_bf16 v[64:67], v[152:155], v[184:187], v[64:67]
	v_mfma_f32_16x16x32_bf16 v[116:119], v[148:151], v[164:167], v[116:119]
	v_mfma_f32_16x16x32_bf16 v[112:115], v[156:159], v[164:167], v[112:115]
	v_mfma_f32_16x16x32_bf16 v[100:103], v[148:151], v[172:175], v[100:103]
	v_mfma_f32_16x16x32_bf16 v[96:99], v[156:159], v[172:175], v[96:99]
	s_setprio 3
	s_barrier
	v_mfma_f32_16x16x32_bf16 v[84:87], v[148:151], v[180:183], v[84:87]
	v_mfma_f32_16x16x32_bf16 v[80:83], v[156:159], v[180:183], v[80:83]
	v_mfma_f32_16x16x32_bf16 v[68:71], v[148:151], v[188:191], v[68:71]
	v_mfma_f32_16x16x32_bf16 v[64:67], v[156:159], v[188:191], v[64:67]
	s_setprio 0
	s_add_i32 s59, s26, s15
	v_lshl_add_u64 v[204:205], s[88:89], 0, v[194:195]
	s_mov_b32 m0, s59
	ds_read_b128 v[160:163], v247 offset:16384
	ds_read_b128 v[164:167], v247 offset:17408
	ds_read_b128 v[168:171], v247 offset:18432
	ds_read_b128 v[172:175], v247 offset:19456
	ds_read_b128 v[176:179], v247 offset:20480
	ds_read_b128 v[180:183], v247 offset:21504
	ds_read_b128 v[184:187], v247 offset:22528
	ds_read_b128 v[188:191], v247 offset:23552
	global_load_lds_dwordx4 v[204:205], off
	s_add_i32 m0, s59, 0x2000
	s_add_u32 s66, s88, 0xb0000
	v_lshl_add_u64 v[206:207], s[88:89], 0, v[198:199]
	s_addc_u32 s67, s89, 0
	s_add_i32 s59, s27, s15
	global_load_lds_dwordx4 v[206:207], off
	v_lshl_add_u64 v[208:209], s[66:67], 0, v[194:195]
	s_mov_b32 m0, s59
	v_lshl_add_u64 v[210:211], s[90:91], 0, v[196:197]
	global_load_lds_dwordx4 v[208:209], off
	v_lshl_add_u64 v[208:209], s[66:67], 0, v[198:199]
	s_add_i32 m0, s59, 0x2000
	s_nop 0
	global_load_lds_dwordx4 v[208:209], off
	v_lshl_add_u64 v[208:209], s[90:91], 0, v[192:193]
	s_mov_b32 m0, s16
	s_nop 0
	global_load_lds_dwordx4 v[208:209], off
	s_mov_b32 m0, s17
	s_nop 0
	global_load_lds_dwordx4 v[210:211], off
	s_waitcnt vmcnt(8)
	s_waitcnt lgkmcnt(0)
	s_barrier
	s_setprio 1
	s_waitcnt lgkmcnt(0)
	v_mfma_f32_16x16x32_bf16 v[60:63], v[120:123], v[160:163], v[60:63]
	v_mfma_f32_16x16x32_bf16 v[56:59], v[128:131], v[160:163], v[56:59]
	v_mfma_f32_16x16x32_bf16 v[44:47], v[120:123], v[168:171], v[44:47]
	v_mfma_f32_16x16x32_bf16 v[40:43], v[128:131], v[168:171], v[40:43]
	v_mfma_f32_16x16x32_bf16 v[28:31], v[120:123], v[176:179], v[28:31]
	v_mfma_f32_16x16x32_bf16 v[24:27], v[128:131], v[176:179], v[24:27]
	v_mfma_f32_16x16x32_bf16 v[12:15], v[120:123], v[184:187], v[12:15]
	v_mfma_f32_16x16x32_bf16 v[8:11], v[128:131], v[184:187], v[8:11]
	v_mfma_f32_16x16x32_bf16 v[60:63], v[124:127], v[164:167], v[60:63]
	v_mfma_f32_16x16x32_bf16 v[56:59], v[132:135], v[164:167], v[56:59]
	v_mfma_f32_16x16x32_bf16 v[44:47], v[124:127], v[172:175], v[44:47]
	v_mfma_f32_16x16x32_bf16 v[40:43], v[132:135], v[172:175], v[40:43]
	v_mfma_f32_16x16x32_bf16 v[28:31], v[124:127], v[180:183], v[28:31]
	v_mfma_f32_16x16x32_bf16 v[24:27], v[132:135], v[180:183], v[24:27]
	v_mfma_f32_16x16x32_bf16 v[12:15], v[124:127], v[188:191], v[12:15]
	v_mfma_f32_16x16x32_bf16 v[8:11], v[132:135], v[188:191], v[8:11]
	s_setprio 0
	s_setprio 1
	v_mfma_f32_16x16x32_bf16 v[52:55], v[144:147], v[160:163], v[52:55]
	v_mfma_f32_16x16x32_bf16 v[48:51], v[152:155], v[160:163], v[48:51]
	v_mfma_f32_16x16x32_bf16 v[36:39], v[144:147], v[168:171], v[36:39]
	v_mfma_f32_16x16x32_bf16 v[32:35], v[152:155], v[168:171], v[32:35]
	v_mfma_f32_16x16x32_bf16 v[20:23], v[144:147], v[176:179], v[20:23]
	v_mfma_f32_16x16x32_bf16 v[16:19], v[152:155], v[176:179], v[16:19]
	v_mfma_f32_16x16x32_bf16 v[4:7], v[144:147], v[184:187], v[4:7]
	v_mfma_f32_16x16x32_bf16 v[0:3], v[152:155], v[184:187], v[0:3]
	v_mfma_f32_16x16x32_bf16 v[52:55], v[148:151], v[164:167], v[52:55]
	v_mfma_f32_16x16x32_bf16 v[48:51], v[156:159], v[164:167], v[48:51]
	v_mfma_f32_16x16x32_bf16 v[36:39], v[148:151], v[172:175], v[36:39]
	v_mfma_f32_16x16x32_bf16 v[32:35], v[156:159], v[172:175], v[32:35]
	s_setprio 3
	s_barrier
	v_mfma_f32_16x16x32_bf16 v[20:23], v[148:151], v[180:183], v[20:23]
	v_mfma_f32_16x16x32_bf16 v[16:19], v[156:159], v[180:183], v[16:19]
	v_mfma_f32_16x16x32_bf16 v[4:7], v[148:151], v[188:191], v[4:7]
	v_mfma_f32_16x16x32_bf16 v[0:3], v[156:159], v[188:191], v[0:3]
	s_setprio 0
	s_add_i32 s59, 0, 0x18000
	s_add_i32 s68, 0, 0x1c000
	v_add_u32_e32 v132, s59, v243
	v_add_u32_e32 v156, s68, v243
	ds_read_b128 v[120:123], v132
	ds_read_b128 v[124:127], v132 offset:1024
	ds_read_b128 v[128:131], v132 offset:2048
	ds_read_b128 v[132:135], v132 offset:3072
	ds_read_b128 v[144:147], v156
	ds_read_b128 v[148:151], v156 offset:1024
	ds_read_b128 v[152:155], v156 offset:2048
	ds_read_b128 v[156:159], v156 offset:3072
	s_add_u32 s66, s90, 0xb0000
	s_addc_u32 s67, s91, 0
	s_mov_b32 m0, s18
	v_lshl_add_u64 v[212:213], s[66:67], 0, v[192:193]
	ds_read_b128 v[160:163], v247 offset:32768
	ds_read_b128 v[164:167], v247 offset:33792
	ds_read_b128 v[168:171], v247 offset:34816
	ds_read_b128 v[172:175], v247 offset:35840
	ds_read_b128 v[176:179], v247 offset:36864
	ds_read_b128 v[180:183], v247 offset:37888
	ds_read_b128 v[184:187], v247 offset:38912
	ds_read_b128 v[188:191], v247 offset:39936
	global_load_lds_dwordx4 v[212:213], off
	v_lshl_add_u64 v[212:213], s[66:67], 0, v[196:197]
	s_mov_b32 m0, s19
	s_nop 0
	global_load_lds_dwordx4 v[212:213], off
	s_waitcnt vmcnt(8)
	s_waitcnt lgkmcnt(0)
	s_barrier
	s_setprio 1
	s_waitcnt lgkmcnt(0)
	v_mfma_f32_16x16x32_bf16 v[140:143], v[120:123], v[160:163], v[140:143]
	v_mfma_f32_16x16x32_bf16 v[136:139], v[128:131], v[160:163], v[136:139]
	v_mfma_f32_16x16x32_bf16 v[108:111], v[120:123], v[168:171], v[108:111]
	v_mfma_f32_16x16x32_bf16 v[104:107], v[128:131], v[168:171], v[104:107]
	v_mfma_f32_16x16x32_bf16 v[92:95], v[120:123], v[176:179], v[92:95]
	v_mfma_f32_16x16x32_bf16 v[88:91], v[128:131], v[176:179], v[88:91]
	v_mfma_f32_16x16x32_bf16 v[76:79], v[120:123], v[184:187], v[76:79]
	v_mfma_f32_16x16x32_bf16 v[72:75], v[128:131], v[184:187], v[72:75]
	v_mfma_f32_16x16x32_bf16 v[140:143], v[124:127], v[164:167], v[140:143]
	v_mfma_f32_16x16x32_bf16 v[136:139], v[132:135], v[164:167], v[136:139]
	v_mfma_f32_16x16x32_bf16 v[108:111], v[124:127], v[172:175], v[108:111]
	v_mfma_f32_16x16x32_bf16 v[104:107], v[132:135], v[172:175], v[104:107]
	v_mfma_f32_16x16x32_bf16 v[92:95], v[124:127], v[180:183], v[92:95]
	v_mfma_f32_16x16x32_bf16 v[88:91], v[132:135], v[180:183], v[88:91]
	v_mfma_f32_16x16x32_bf16 v[76:79], v[124:127], v[188:191], v[76:79]
	v_mfma_f32_16x16x32_bf16 v[72:75], v[132:135], v[188:191], v[72:75]
	s_setprio 0
	s_setprio 1
	v_mfma_f32_16x16x32_bf16 v[116:119], v[144:147], v[160:163], v[116:119]
	v_mfma_f32_16x16x32_bf16 v[112:115], v[152:155], v[160:163], v[112:115]
	v_mfma_f32_16x16x32_bf16 v[100:103], v[144:147], v[168:171], v[100:103]
	v_mfma_f32_16x16x32_bf16 v[96:99], v[152:155], v[168:171], v[96:99]
	v_mfma_f32_16x16x32_bf16 v[84:87], v[144:147], v[176:179], v[84:87]
	v_mfma_f32_16x16x32_bf16 v[80:83], v[152:155], v[176:179], v[80:83]
	v_mfma_f32_16x16x32_bf16 v[68:71], v[144:147], v[184:187], v[68:71]
	v_mfma_f32_16x16x32_bf16 v[64:67], v[152:155], v[184:187], v[64:67]
	v_mfma_f32_16x16x32_bf16 v[116:119], v[148:151], v[164:167], v[116:119]
	v_mfma_f32_16x16x32_bf16 v[112:115], v[156:159], v[164:167], v[112:115]
	v_mfma_f32_16x16x32_bf16 v[100:103], v[148:151], v[172:175], v[100:103]
	v_mfma_f32_16x16x32_bf16 v[96:99], v[156:159], v[172:175], v[96:99]
	s_setprio 3
	s_barrier
	v_mfma_f32_16x16x32_bf16 v[84:87], v[148:151], v[180:183], v[84:87]
	v_mfma_f32_16x16x32_bf16 v[80:83], v[156:159], v[180:183], v[80:83]
	v_mfma_f32_16x16x32_bf16 v[68:71], v[148:151], v[188:191], v[68:71]
	v_mfma_f32_16x16x32_bf16 v[64:67], v[156:159], v[188:191], v[64:67]
	s_setprio 0
	s_add_i32 s59, s59, s15
	v_lshl_add_u64 v[204:205], v[204:205], 0, s[80:81]
	s_mov_b32 m0, s59
	ds_read_b128 v[160:163], v247 offset:49152
	ds_read_b128 v[164:167], v247 offset:50176
	ds_read_b128 v[168:171], v247 offset:51200
	ds_read_b128 v[172:175], v247 offset:52224
	ds_read_b128 v[176:179], v247 offset:53248
	ds_read_b128 v[180:183], v247 offset:54272
	ds_read_b128 v[184:187], v247 offset:55296
	ds_read_b128 v[188:191], v247 offset:56320
	global_load_lds_dwordx4 v[204:205], off
	s_add_i32 m0, s59, 0x2000
	s_add_u32 s66, s88, 0xb0080
	v_lshl_add_u64 v[204:205], v[206:207], 0, s[80:81]
	s_addc_u32 s67, s89, 0
	s_add_i32 s59, s68, s15
	global_load_lds_dwordx4 v[204:205], off
	v_lshl_add_u64 v[204:205], s[66:67], 0, v[194:195]
	s_mov_b32 m0, s59
	s_nop 0
	global_load_lds_dwordx4 v[204:205], off
	v_lshl_add_u64 v[204:205], s[66:67], 0, v[198:199]
	s_add_i32 m0, s59, 0x2000
	s_nop 0
	global_load_lds_dwordx4 v[204:205], off
	v_lshl_add_u64 v[204:205], v[208:209], 0, s[80:81]
	s_mov_b32 m0, s21
	s_nop 0
	global_load_lds_dwordx4 v[204:205], off
	v_lshl_add_u64 v[204:205], v[210:211], 0, s[80:81]
	s_mov_b32 m0, s22
	s_nop 0
	global_load_lds_dwordx4 v[204:205], off
	s_waitcnt vmcnt(8)
	s_waitcnt lgkmcnt(0)
	s_barrier
	s_setprio 1
	s_waitcnt lgkmcnt(0)
	v_mfma_f32_16x16x32_bf16 v[60:63], v[120:123], v[160:163], v[60:63]
	v_mfma_f32_16x16x32_bf16 v[56:59], v[128:131], v[160:163], v[56:59]
	v_mfma_f32_16x16x32_bf16 v[44:47], v[120:123], v[168:171], v[44:47]
	v_mfma_f32_16x16x32_bf16 v[40:43], v[128:131], v[168:171], v[40:43]
	v_mfma_f32_16x16x32_bf16 v[28:31], v[120:123], v[176:179], v[28:31]
	v_mfma_f32_16x16x32_bf16 v[24:27], v[128:131], v[176:179], v[24:27]
	v_mfma_f32_16x16x32_bf16 v[12:15], v[120:123], v[184:187], v[12:15]
	v_mfma_f32_16x16x32_bf16 v[8:11], v[128:131], v[184:187], v[8:11]
	v_mfma_f32_16x16x32_bf16 v[60:63], v[124:127], v[164:167], v[60:63]
	v_mfma_f32_16x16x32_bf16 v[56:59], v[132:135], v[164:167], v[56:59]
	v_mfma_f32_16x16x32_bf16 v[44:47], v[124:127], v[172:175], v[44:47]
	v_mfma_f32_16x16x32_bf16 v[40:43], v[132:135], v[172:175], v[40:43]
	v_mfma_f32_16x16x32_bf16 v[28:31], v[124:127], v[180:183], v[28:31]
	v_mfma_f32_16x16x32_bf16 v[24:27], v[132:135], v[180:183], v[24:27]
	v_mfma_f32_16x16x32_bf16 v[12:15], v[124:127], v[188:191], v[12:15]
	v_mfma_f32_16x16x32_bf16 v[8:11], v[132:135], v[188:191], v[8:11]
	s_setprio 0
	s_setprio 1
	v_mfma_f32_16x16x32_bf16 v[52:55], v[144:147], v[160:163], v[52:55]
	v_mfma_f32_16x16x32_bf16 v[48:51], v[152:155], v[160:163], v[48:51]
	v_mfma_f32_16x16x32_bf16 v[36:39], v[144:147], v[168:171], v[36:39]
	v_mfma_f32_16x16x32_bf16 v[32:35], v[152:155], v[168:171], v[32:35]
	v_mfma_f32_16x16x32_bf16 v[20:23], v[144:147], v[176:179], v[20:23]
	v_mfma_f32_16x16x32_bf16 v[16:19], v[152:155], v[176:179], v[16:19]
	v_mfma_f32_16x16x32_bf16 v[4:7], v[144:147], v[184:187], v[4:7]
	v_mfma_f32_16x16x32_bf16 v[0:3], v[152:155], v[184:187], v[0:3]
	v_mfma_f32_16x16x32_bf16 v[52:55], v[148:151], v[164:167], v[52:55]
	v_mfma_f32_16x16x32_bf16 v[48:51], v[156:159], v[164:167], v[48:51]
	v_mfma_f32_16x16x32_bf16 v[36:39], v[148:151], v[172:175], v[36:39]
	v_mfma_f32_16x16x32_bf16 v[32:35], v[156:159], v[172:175], v[32:35]
	s_setprio 3
	s_barrier
	v_mfma_f32_16x16x32_bf16 v[20:23], v[148:151], v[180:183], v[20:23]
	v_mfma_f32_16x16x32_bf16 v[16:19], v[156:159], v[180:183], v[16:19]
	v_mfma_f32_16x16x32_bf16 v[4:7], v[148:151], v[188:191], v[4:7]
	v_mfma_f32_16x16x32_bf16 v[0:3], v[156:159], v[188:191], v[0:3]
	s_setprio 0
	s_add_i32 s58, s58, 2
	s_add_u32 s86, s86, 0x100
	s_addc_u32 s87, s87, 0
	s_add_u32 s56, s56, 0x100
	s_addc_u32 s57, s57, 0
	s_cmp_gt_u32 s58, 41
	s_cbranch_scc0 .LBB0_272
	s_and_b64 vcc, exec, s[82:83]
	s_cbranch_vccz .LBB0_275
	s_barrier

.LBB0_429:
	ds_read_b128 v[128:131], v203
	ds_read_b128 v[132:135], v203 offset:1024
	ds_read_b128 v[136:139], v203 offset:2048
	ds_read_b128 v[164:167], v203 offset:3072
	ds_read_b128 v[168:171], v204
	ds_read_b128 v[172:175], v204 offset:1024
	ds_read_b128 v[176:179], v204 offset:2048
	ds_read_b128 v[180:183], v204 offset:3072
	s_add_u32 s6, s88, 0xfffc0080
	s_addc_u32 s7, s89, -1
	s_cmp_eq_u32 s21, 12
	s_cselect_b32 vcc_hi, s15, s7
	s_cselect_b32 vcc_lo, s16, s6
	s_cselect_b32 s7, s17, s20
	s_cselect_b32 s6, s18, s19
	v_lshl_add_u64 v[196:197], s[88:89], 0, v[156:157]
	s_add_i32 m0, s58, 0xc000
	ds_read_b128 v[184:187], v205
	ds_read_b128 v[188:191], v205 offset:1024
	ds_read_b128 v[192:195], v205 offset:2048
	ds_read_b128 v[212:215], v205 offset:3072
	ds_read_b128 v[216:219], v205 offset:4096
	ds_read_b128 v[220:223], v205 offset:5120
	ds_read_b128 v[224:227], v205 offset:6144
	ds_read_b128 v[228:231], v205 offset:7168
	global_load_lds_dwordx4 v[196:197], off
	v_lshl_add_u64 v[196:197], s[88:89], 0, v[158:159]
	s_add_i32 m0, s58, 0xe000
	s_nop 0
	global_load_lds_dwordx4 v[196:197], off
	s_waitcnt vmcnt(8)
	s_waitcnt lgkmcnt(0)
	s_barrier
	s_setprio 1
	s_waitcnt lgkmcnt(0)
	v_mfma_f32_16x16x32_bf16 v[124:127], v[128:131], v[184:187], v[124:127]
	v_mfma_f32_16x16x32_bf16 v[116:119], v[136:139], v[184:187], v[116:119]
	v_mfma_f32_16x16x32_bf16 v[108:111], v[128:131], v[192:195], v[108:111]
	v_mfma_f32_16x16x32_bf16 v[100:103], v[136:139], v[192:195], v[100:103]
	v_mfma_f32_16x16x32_bf16 v[92:95], v[128:131], v[216:219], v[92:95]
	v_mfma_f32_16x16x32_bf16 v[84:87], v[136:139], v[216:219], v[84:87]
	v_mfma_f32_16x16x32_bf16 v[76:79], v[128:131], v[224:227], v[76:79]
	v_mfma_f32_16x16x32_bf16 v[68:71], v[136:139], v[224:227], v[68:71]
	v_mfma_f32_16x16x32_bf16 v[124:127], v[132:135], v[188:191], v[124:127]
	v_mfma_f32_16x16x32_bf16 v[116:119], v[164:167], v[188:191], v[116:119]
	v_mfma_f32_16x16x32_bf16 v[108:111], v[132:135], v[212:215], v[108:111]
	v_mfma_f32_16x16x32_bf16 v[100:103], v[164:167], v[212:215], v[100:103]
	v_mfma_f32_16x16x32_bf16 v[92:95], v[132:135], v[220:223], v[92:95]
	v_mfma_f32_16x16x32_bf16 v[84:87], v[164:167], v[220:223], v[84:87]
	v_mfma_f32_16x16x32_bf16 v[76:79], v[132:135], v[228:231], v[76:79]
	v_mfma_f32_16x16x32_bf16 v[68:71], v[164:167], v[228:231], v[68:71]
	s_setprio 0
	s_setprio 1
	v_mfma_f32_16x16x32_bf16 v[120:123], v[168:171], v[184:187], v[120:123]
	v_mfma_f32_16x16x32_bf16 v[112:115], v[176:179], v[184:187], v[112:115]
	v_mfma_f32_16x16x32_bf16 v[104:107], v[168:171], v[192:195], v[104:107]
	v_mfma_f32_16x16x32_bf16 v[96:99], v[176:179], v[192:195], v[96:99]
	v_mfma_f32_16x16x32_bf16 v[88:91], v[168:171], v[216:219], v[88:91]
	v_mfma_f32_16x16x32_bf16 v[80:83], v[176:179], v[216:219], v[80:83]
	v_mfma_f32_16x16x32_bf16 v[72:75], v[168:171], v[224:227], v[72:75]
	v_mfma_f32_16x16x32_bf16 v[64:67], v[176:179], v[224:227], v[64:67]
	v_mfma_f32_16x16x32_bf16 v[120:123], v[172:175], v[188:191], v[120:123]
	v_mfma_f32_16x16x32_bf16 v[112:115], v[180:183], v[188:191], v[112:115]
	v_mfma_f32_16x16x32_bf16 v[104:107], v[172:175], v[212:215], v[104:107]
	v_mfma_f32_16x16x32_bf16 v[96:99], v[180:183], v[212:215], v[96:99]
	s_setprio 3
	s_barrier
	v_mfma_f32_16x16x32_bf16 v[88:91], v[172:175], v[220:223], v[88:91]
	v_mfma_f32_16x16x32_bf16 v[80:83], v[180:183], v[220:223], v[80:83]
	v_mfma_f32_16x16x32_bf16 v[72:75], v[172:175], v[228:231], v[72:75]
	v_mfma_f32_16x16x32_bf16 v[64:67], v[180:183], v[228:231], v[64:67]
	s_setprio 0
	s_add_i32 s22, s76, s57
	v_lshl_add_u64 v[196:197], s[6:7], 0, v[142:143]
	s_mov_b32 m0, s22
	ds_read_b128 v[184:187], v205 offset:16384
	ds_read_b128 v[188:191], v205 offset:17408
	ds_read_b128 v[192:195], v205 offset:18432
	ds_read_b128 v[212:215], v205 offset:19456
	ds_read_b128 v[216:219], v205 offset:20480
	ds_read_b128 v[220:223], v205 offset:21504
	ds_read_b128 v[224:227], v205 offset:22528
	ds_read_b128 v[228:231], v205 offset:23552
	global_load_lds_dwordx4 v[196:197], off
	s_add_i32 m0, s22, 0x2000
	s_add_u32 s22, s6, 0x40000
	v_lshl_add_u64 v[232:233], s[6:7], 0, v[146:147]
	s_addc_u32 s23, s7, 0
	s_add_i32 s24, s77, s57
	global_load_lds_dwordx4 v[232:233], off
	v_lshl_add_u64 v[234:235], s[22:23], 0, v[142:143]
	s_mov_b32 m0, s24
	v_lshl_add_u64 v[236:237], vcc, 0, v[144:145]
	global_load_lds_dwordx4 v[234:235], off
	v_lshl_add_u64 v[234:235], s[22:23], 0, v[146:147]
	s_add_i32 m0, s24, 0x2000
	s_nop 0
	global_load_lds_dwordx4 v[234:235], off
	v_lshl_add_u64 v[234:235], vcc, 0, v[140:141]
	s_mov_b32 m0, s58
	s_nop 0
	global_load_lds_dwordx4 v[234:235], off
	s_mov_b32 m0, s59
	s_nop 0
	global_load_lds_dwordx4 v[236:237], off
	s_waitcnt vmcnt(8)
	s_waitcnt lgkmcnt(0)
	s_barrier
	s_setprio 1
	s_waitcnt lgkmcnt(0)
	v_mfma_f32_16x16x32_bf16 v[60:63], v[128:131], v[184:187], v[60:63]
	v_mfma_f32_16x16x32_bf16 v[52:55], v[136:139], v[184:187], v[52:55]
	v_mfma_f32_16x16x32_bf16 v[44:47], v[128:131], v[192:195], v[44:47]
	v_mfma_f32_16x16x32_bf16 v[36:39], v[136:139], v[192:195], v[36:39]
	v_mfma_f32_16x16x32_bf16 v[28:31], v[128:131], v[216:219], v[28:31]
	v_mfma_f32_16x16x32_bf16 v[20:23], v[136:139], v[216:219], v[20:23]
	v_mfma_f32_16x16x32_bf16 v[12:15], v[128:131], v[224:227], v[12:15]
	v_mfma_f32_16x16x32_bf16 v[4:7], v[136:139], v[224:227], v[4:7]
	v_mfma_f32_16x16x32_bf16 v[60:63], v[132:135], v[188:191], v[60:63]
	v_mfma_f32_16x16x32_bf16 v[52:55], v[164:167], v[188:191], v[52:55]
	v_mfma_f32_16x16x32_bf16 v[44:47], v[132:135], v[212:215], v[44:47]
	v_mfma_f32_16x16x32_bf16 v[36:39], v[164:167], v[212:215], v[36:39]
	v_mfma_f32_16x16x32_bf16 v[28:31], v[132:135], v[220:223], v[28:31]
	v_mfma_f32_16x16x32_bf16 v[20:23], v[164:167], v[220:223], v[20:23]
	v_mfma_f32_16x16x32_bf16 v[12:15], v[132:135], v[228:231], v[12:15]
	v_mfma_f32_16x16x32_bf16 v[4:7], v[164:167], v[228:231], v[4:7]
	s_setprio 0
	s_setprio 1
	v_mfma_f32_16x16x32_bf16 v[56:59], v[168:171], v[184:187], v[56:59]
	v_mfma_f32_16x16x32_bf16 v[48:51], v[176:179], v[184:187], v[48:51]
	v_mfma_f32_16x16x32_bf16 v[40:43], v[168:171], v[192:195], v[40:43]
	v_mfma_f32_16x16x32_bf16 v[32:35], v[176:179], v[192:195], v[32:35]
	v_mfma_f32_16x16x32_bf16 v[24:27], v[168:171], v[216:219], v[24:27]
	v_mfma_f32_16x16x32_bf16 v[16:19], v[176:179], v[216:219], v[16:19]
	v_mfma_f32_16x16x32_bf16 v[8:11], v[168:171], v[224:227], v[8:11]
	v_mfma_f32_16x16x32_bf16 v[0:3], v[176:179], v[224:227], v[0:3]
	v_mfma_f32_16x16x32_bf16 v[56:59], v[172:175], v[188:191], v[56:59]
	v_mfma_f32_16x16x32_bf16 v[48:51], v[180:183], v[188:191], v[48:51]
	v_mfma_f32_16x16x32_bf16 v[40:43], v[172:175], v[212:215], v[40:43]
	v_mfma_f32_16x16x32_bf16 v[32:35], v[180:183], v[212:215], v[32:35]
	s_setprio 3
	s_barrier
	v_mfma_f32_16x16x32_bf16 v[24:27], v[172:175], v[220:223], v[24:27]
	v_mfma_f32_16x16x32_bf16 v[16:19], v[180:183], v[220:223], v[16:19]
	v_mfma_f32_16x16x32_bf16 v[8:11], v[172:175], v[228:231], v[8:11]
	v_mfma_f32_16x16x32_bf16 v[0:3], v[180:183], v[228:231], v[0:3]
	s_setprio 0
	s_add_i32 s24, 0, 0x18000
	v_add_u32_e32 v150, s24, v200
	s_add_i32 s25, 0, 0x1c000
	ds_read_b128 v[128:131], v150
	ds_read_b128 v[132:135], v150 offset:1024
	ds_read_b128 v[136:139], v150 offset:2048
	ds_read_b128 v[164:167], v150 offset:3072
	v_add_u32_e32 v150, s25, v200
	ds_read_b128 v[168:171], v150
	ds_read_b128 v[172:175], v150 offset:1024
	ds_read_b128 v[176:179], v150 offset:2048
	ds_read_b128 v[180:183], v150 offset:3072
	s_add_u32 s22, vcc_lo, 0x40000
	s_addc_u32 s23, vcc_hi, 0
	s_mov_b32 m0, s66
	v_lshl_add_u64 v[238:239], s[22:23], 0, v[140:141]
	ds_read_b128 v[184:187], v205 offset:32768
	ds_read_b128 v[188:191], v205 offset:33792
	ds_read_b128 v[192:195], v205 offset:34816
	ds_read_b128 v[212:215], v205 offset:35840
	ds_read_b128 v[216:219], v205 offset:36864
	ds_read_b128 v[220:223], v205 offset:37888
	ds_read_b128 v[224:227], v205 offset:38912
	ds_read_b128 v[228:231], v205 offset:39936
	global_load_lds_dwordx4 v[238:239], off
	v_lshl_add_u64 v[238:239], s[22:23], 0, v[144:145]
	s_mov_b32 m0, s67
	s_nop 0
	global_load_lds_dwordx4 v[238:239], off
	s_waitcnt vmcnt(8)
	s_waitcnt lgkmcnt(0)
	s_barrier
	s_setprio 1
	s_waitcnt lgkmcnt(0)
	v_mfma_f32_16x16x32_bf16 v[124:127], v[128:131], v[184:187], v[124:127]
	v_mfma_f32_16x16x32_bf16 v[116:119], v[136:139], v[184:187], v[116:119]
	v_mfma_f32_16x16x32_bf16 v[108:111], v[128:131], v[192:195], v[108:111]
	v_mfma_f32_16x16x32_bf16 v[100:103], v[136:139], v[192:195], v[100:103]
	v_mfma_f32_16x16x32_bf16 v[92:95], v[128:131], v[216:219], v[92:95]
	v_mfma_f32_16x16x32_bf16 v[84:87], v[136:139], v[216:219], v[84:87]
	v_mfma_f32_16x16x32_bf16 v[76:79], v[128:131], v[224:227], v[76:79]
	v_mfma_f32_16x16x32_bf16 v[68:71], v[136:139], v[224:227], v[68:71]
	v_mfma_f32_16x16x32_bf16 v[124:127], v[132:135], v[188:191], v[124:127]
	v_mfma_f32_16x16x32_bf16 v[116:119], v[164:167], v[188:191], v[116:119]
	v_mfma_f32_16x16x32_bf16 v[108:111], v[132:135], v[212:215], v[108:111]
	v_mfma_f32_16x16x32_bf16 v[100:103], v[164:167], v[212:215], v[100:103]
	v_mfma_f32_16x16x32_bf16 v[92:95], v[132:135], v[220:223], v[92:95]
	v_mfma_f32_16x16x32_bf16 v[84:87], v[164:167], v[220:223], v[84:87]
	v_mfma_f32_16x16x32_bf16 v[76:79], v[132:135], v[228:231], v[76:79]
	v_mfma_f32_16x16x32_bf16 v[68:71], v[164:167], v[228:231], v[68:71]
	s_setprio 0
	s_setprio 1
	v_mfma_f32_16x16x32_bf16 v[120:123], v[168:171], v[184:187], v[120:123]
	v_mfma_f32_16x16x32_bf16 v[112:115], v[176:179], v[184:187], v[112:115]
	v_mfma_f32_16x16x32_bf16 v[104:107], v[168:171], v[192:195], v[104:107]
	v_mfma_f32_16x16x32_bf16 v[96:99], v[176:179], v[192:195], v[96:99]
	v_mfma_f32_16x16x32_bf16 v[88:91], v[168:171], v[216:219], v[88:91]
	v_mfma_f32_16x16x32_bf16 v[80:83], v[176:179], v[216:219], v[80:83]
	v_mfma_f32_16x16x32_bf16 v[72:75], v[168:171], v[224:227], v[72:75]
	v_mfma_f32_16x16x32_bf16 v[64:67], v[176:179], v[224:227], v[64:67]
	v_mfma_f32_16x16x32_bf16 v[120:123], v[172:175], v[188:191], v[120:123]
	v_mfma_f32_16x16x32_bf16 v[112:115], v[180:183], v[188:191], v[112:115]
	v_mfma_f32_16x16x32_bf16 v[104:107], v[172:175], v[212:215], v[104:107]
	v_mfma_f32_16x16x32_bf16 v[96:99], v[180:183], v[212:215], v[96:99]
	s_setprio 3
	s_barrier
	v_mfma_f32_16x16x32_bf16 v[88:91], v[172:175], v[220:223], v[88:91]
	v_mfma_f32_16x16x32_bf16 v[80:83], v[180:183], v[220:223], v[80:83]
	v_mfma_f32_16x16x32_bf16 v[72:75], v[172:175], v[228:231], v[72:75]
	v_mfma_f32_16x16x32_bf16 v[64:67], v[180:183], v[228:231], v[64:67]
	s_setprio 0
	s_add_i32 s22, s24, s57
	v_lshl_add_u64 v[196:197], v[196:197], 0, s[80:81]
	s_mov_b32 m0, s22
	ds_read_b128 v[184:187], v205 offset:49152
	ds_read_b128 v[188:191], v205 offset:50176
	ds_read_b128 v[192:195], v205 offset:51200
	ds_read_b128 v[212:215], v205 offset:52224
	ds_read_b128 v[216:219], v205 offset:53248
	ds_read_b128 v[220:223], v205 offset:54272
	ds_read_b128 v[224:227], v205 offset:55296
	ds_read_b128 v[228:231], v205 offset:56320
	global_load_lds_dwordx4 v[196:197], off
	s_add_i32 m0, s22, 0x2000
	s_add_u32 s6, s6, 0x40080
	v_lshl_add_u64 v[196:197], v[232:233], 0, s[80:81]
	s_addc_u32 s7, s7, 0
	s_add_i32 s22, s25, s57
	global_load_lds_dwordx4 v[196:197], off
	v_lshl_add_u64 v[196:197], s[6:7], 0, v[142:143]
	s_mov_b32 m0, s22
	s_nop 0
	global_load_lds_dwordx4 v[196:197], off
	v_lshl_add_u64 v[196:197], s[6:7], 0, v[146:147]
	s_add_i32 m0, s22, 0x2000
	s_nop 0
	global_load_lds_dwordx4 v[196:197], off
	v_lshl_add_u64 v[196:197], v[234:235], 0, s[80:81]
	s_mov_b32 m0, s93
	s_nop 0
	global_load_lds_dwordx4 v[196:197], off
	v_lshl_add_u64 v[196:197], v[236:237], 0, s[80:81]
	s_mov_b32 m0, s69
	s_nop 0
	global_load_lds_dwordx4 v[196:197], off
	s_waitcnt vmcnt(8)
	s_waitcnt lgkmcnt(0)
	s_barrier
	s_setprio 1
	s_waitcnt lgkmcnt(0)
	v_mfma_f32_16x16x32_bf16 v[60:63], v[128:131], v[184:187], v[60:63]
	v_mfma_f32_16x16x32_bf16 v[52:55], v[136:139], v[184:187], v[52:55]
	v_mfma_f32_16x16x32_bf16 v[44:47], v[128:131], v[192:195], v[44:47]
	v_mfma_f32_16x16x32_bf16 v[36:39], v[136:139], v[192:195], v[36:39]
	v_mfma_f32_16x16x32_bf16 v[28:31], v[128:131], v[216:219], v[28:31]
	v_mfma_f32_16x16x32_bf16 v[20:23], v[136:139], v[216:219], v[20:23]
	v_mfma_f32_16x16x32_bf16 v[12:15], v[128:131], v[224:227], v[12:15]
	v_mfma_f32_16x16x32_bf16 v[4:7], v[136:139], v[224:227], v[4:7]
	v_mfma_f32_16x16x32_bf16 v[60:63], v[132:135], v[188:191], v[60:63]
	v_mfma_f32_16x16x32_bf16 v[52:55], v[164:167], v[188:191], v[52:55]
	v_mfma_f32_16x16x32_bf16 v[44:47], v[132:135], v[212:215], v[44:47]
	v_mfma_f32_16x16x32_bf16 v[36:39], v[164:167], v[212:215], v[36:39]
	v_mfma_f32_16x16x32_bf16 v[28:31], v[132:135], v[220:223], v[28:31]
	v_mfma_f32_16x16x32_bf16 v[20:23], v[164:167], v[220:223], v[20:23]
	v_mfma_f32_16x16x32_bf16 v[12:15], v[132:135], v[228:231], v[12:15]
	v_mfma_f32_16x16x32_bf16 v[4:7], v[164:167], v[228:231], v[4:7]
	s_setprio 0
	s_setprio 1
	v_mfma_f32_16x16x32_bf16 v[56:59], v[168:171], v[184:187], v[56:59]
	v_mfma_f32_16x16x32_bf16 v[48:51], v[176:179], v[184:187], v[48:51]
	v_mfma_f32_16x16x32_bf16 v[40:43], v[168:171], v[192:195], v[40:43]
	v_mfma_f32_16x16x32_bf16 v[32:35], v[176:179], v[192:195], v[32:35]
	v_mfma_f32_16x16x32_bf16 v[24:27], v[168:171], v[216:219], v[24:27]
	v_mfma_f32_16x16x32_bf16 v[16:19], v[176:179], v[216:219], v[16:19]
	v_mfma_f32_16x16x32_bf16 v[8:11], v[168:171], v[224:227], v[8:11]
	v_mfma_f32_16x16x32_bf16 v[0:3], v[176:179], v[224:227], v[0:3]
	v_mfma_f32_16x16x32_bf16 v[56:59], v[172:175], v[188:191], v[56:59]
	v_mfma_f32_16x16x32_bf16 v[48:51], v[180:183], v[188:191], v[48:51]
	v_mfma_f32_16x16x32_bf16 v[40:43], v[172:175], v[212:215], v[40:43]
	v_mfma_f32_16x16x32_bf16 v[32:35], v[180:183], v[212:215], v[32:35]
	s_setprio 3
	s_barrier
	v_mfma_f32_16x16x32_bf16 v[24:27], v[172:175], v[220:223], v[24:27]
	v_mfma_f32_16x16x32_bf16 v[16:19], v[180:183], v[220:223], v[16:19]
	v_mfma_f32_16x16x32_bf16 v[8:11], v[172:175], v[228:231], v[8:11]
	v_mfma_f32_16x16x32_bf16 v[0:3], v[180:183], v[228:231], v[0:3]
	s_setprio 0
	s_add_i32 s21, s21, 2
	s_add_u32 s88, s88, 0x100
	s_addc_u32 s89, s89, 0
	s_add_u32 s19, s19, 0x100
	s_addc_u32 s20, s20, 0
	s_cmp_gt_u32 s21, 13
	s_cbranch_scc0 .LBB0_429
	s_and_b64 vcc, exec, s[82:83]
	s_cbranch_vccz .LBB0_432
	s_barrier

.LBB0_993:
	ds_read_b128 v[120:123], v245
	ds_read_b128 v[124:127], v245 offset:1024
	ds_read_b128 v[128:131], v245 offset:2048
	ds_read_b128 v[132:135], v245 offset:3072
	ds_read_b128 v[144:147], v246
	ds_read_b128 v[148:151], v246 offset:1024
	ds_read_b128 v[152:155], v246 offset:2048
	ds_read_b128 v[156:159], v246 offset:3072
	s_add_u32 s59, s82, 0xfffc0080
	s_addc_u32 s66, s83, -1
	s_cmp_eq_u32 s58, 12
	s_cselect_b32 s87, s53, s66
	s_cselect_b32 s86, s54, s59
	s_cselect_b32 s85, s51, s57
	s_cselect_b32 s84, s55, s56
	v_lshl_add_u64 v[204:205], s[82:83], 0, v[200:201]
	s_add_i32 m0, s16, 0xc000
	ds_read_b128 v[160:163], v247
	ds_read_b128 v[164:167], v247 offset:1024
	ds_read_b128 v[168:171], v247 offset:2048
	ds_read_b128 v[172:175], v247 offset:3072
	ds_read_b128 v[176:179], v247 offset:4096
	ds_read_b128 v[180:183], v247 offset:5120
	ds_read_b128 v[184:187], v247 offset:6144
	ds_read_b128 v[188:191], v247 offset:7168
	global_load_lds_dwordx4 v[204:205], off
	v_lshl_add_u64 v[204:205], s[82:83], 0, v[202:203]
	s_add_i32 m0, s16, 0xe000
	s_nop 0
	global_load_lds_dwordx4 v[204:205], off
	s_waitcnt vmcnt(8)
	s_waitcnt lgkmcnt(0)
	s_barrier
	s_setprio 1
	s_waitcnt lgkmcnt(0)
	v_mfma_f32_16x16x32_bf16 v[140:143], v[120:123], v[160:163], v[140:143]
	v_mfma_f32_16x16x32_bf16 v[136:139], v[128:131], v[160:163], v[136:139]
	v_mfma_f32_16x16x32_bf16 v[108:111], v[120:123], v[168:171], v[108:111]
	v_mfma_f32_16x16x32_bf16 v[104:107], v[128:131], v[168:171], v[104:107]
	v_mfma_f32_16x16x32_bf16 v[92:95], v[120:123], v[176:179], v[92:95]
	v_mfma_f32_16x16x32_bf16 v[88:91], v[128:131], v[176:179], v[88:91]
	v_mfma_f32_16x16x32_bf16 v[76:79], v[120:123], v[184:187], v[76:79]
	v_mfma_f32_16x16x32_bf16 v[72:75], v[128:131], v[184:187], v[72:75]
	v_mfma_f32_16x16x32_bf16 v[140:143], v[124:127], v[164:167], v[140:143]
	v_mfma_f32_16x16x32_bf16 v[136:139], v[132:135], v[164:167], v[136:139]
	v_mfma_f32_16x16x32_bf16 v[108:111], v[124:127], v[172:175], v[108:111]
	v_mfma_f32_16x16x32_bf16 v[104:107], v[132:135], v[172:175], v[104:107]
	v_mfma_f32_16x16x32_bf16 v[92:95], v[124:127], v[180:183], v[92:95]
	v_mfma_f32_16x16x32_bf16 v[88:91], v[132:135], v[180:183], v[88:91]
	v_mfma_f32_16x16x32_bf16 v[76:79], v[124:127], v[188:191], v[76:79]
	v_mfma_f32_16x16x32_bf16 v[72:75], v[132:135], v[188:191], v[72:75]
	s_setprio 0
	s_setprio 1
	v_mfma_f32_16x16x32_bf16 v[116:119], v[144:147], v[160:163], v[116:119]
	v_mfma_f32_16x16x32_bf16 v[112:115], v[152:155], v[160:163], v[112:115]
	v_mfma_f32_16x16x32_bf16 v[100:103], v[144:147], v[168:171], v[100:103]
	v_mfma_f32_16x16x32_bf16 v[96:99], v[152:155], v[168:171], v[96:99]
	v_mfma_f32_16x16x32_bf16 v[84:87], v[144:147], v[176:179], v[84:87]
	v_mfma_f32_16x16x32_bf16 v[80:83], v[152:155], v[176:179], v[80:83]
	v_mfma_f32_16x16x32_bf16 v[68:71], v[144:147], v[184:187], v[68:71]
	v_mfma_f32_16x16x32_bf16 v[64:67], v[152:155], v[184:187], v[64:67]
	v_mfma_f32_16x16x32_bf16 v[116:119], v[148:151], v[164:167], v[116:119]
	v_mfma_f32_16x16x32_bf16 v[112:115], v[156:159], v[164:167], v[112:115]
	v_mfma_f32_16x16x32_bf16 v[100:103], v[148:151], v[172:175], v[100:103]
	v_mfma_f32_16x16x32_bf16 v[96:99], v[156:159], v[172:175], v[96:99]
	s_setprio 3
	s_barrier
	v_mfma_f32_16x16x32_bf16 v[84:87], v[148:151], v[180:183], v[84:87]
	v_mfma_f32_16x16x32_bf16 v[80:83], v[156:159], v[180:183], v[80:83]
	v_mfma_f32_16x16x32_bf16 v[68:71], v[148:151], v[188:191], v[68:71]
	v_mfma_f32_16x16x32_bf16 v[64:67], v[156:159], v[188:191], v[64:67]
	s_setprio 0
	s_add_i32 s59, s26, s15
	v_lshl_add_u64 v[204:205], s[84:85], 0, v[194:195]
	s_mov_b32 m0, s59
	ds_read_b128 v[160:163], v247 offset:16384
	ds_read_b128 v[164:167], v247 offset:17408
	ds_read_b128 v[168:171], v247 offset:18432
	ds_read_b128 v[172:175], v247 offset:19456
	ds_read_b128 v[176:179], v247 offset:20480
	ds_read_b128 v[180:183], v247 offset:21504
	ds_read_b128 v[184:187], v247 offset:22528
	ds_read_b128 v[188:191], v247 offset:23552
	global_load_lds_dwordx4 v[204:205], off
	s_add_i32 m0, s59, 0x2000
	s_add_u32 s66, s84, 0x40000
	v_lshl_add_u64 v[206:207], s[84:85], 0, v[198:199]
	s_addc_u32 s67, s85, 0
	s_add_i32 s59, s27, s15
	global_load_lds_dwordx4 v[206:207], off
	v_lshl_add_u64 v[208:209], s[66:67], 0, v[194:195]
	s_mov_b32 m0, s59
	v_lshl_add_u64 v[210:211], s[86:87], 0, v[196:197]
	global_load_lds_dwordx4 v[208:209], off
	v_lshl_add_u64 v[208:209], s[66:67], 0, v[198:199]
	s_add_i32 m0, s59, 0x2000
	s_nop 0
	global_load_lds_dwordx4 v[208:209], off
	v_lshl_add_u64 v[208:209], s[86:87], 0, v[192:193]
	s_mov_b32 m0, s16
	s_nop 0
	global_load_lds_dwordx4 v[208:209], off
	s_mov_b32 m0, s17
	s_nop 0
	global_load_lds_dwordx4 v[210:211], off
	s_waitcnt vmcnt(8)
	s_waitcnt lgkmcnt(0)
	s_barrier
	s_setprio 1
	s_waitcnt lgkmcnt(0)
	v_mfma_f32_16x16x32_bf16 v[60:63], v[120:123], v[160:163], v[60:63]
	v_mfma_f32_16x16x32_bf16 v[56:59], v[128:131], v[160:163], v[56:59]
	v_mfma_f32_16x16x32_bf16 v[44:47], v[120:123], v[168:171], v[44:47]
	v_mfma_f32_16x16x32_bf16 v[40:43], v[128:131], v[168:171], v[40:43]
	v_mfma_f32_16x16x32_bf16 v[28:31], v[120:123], v[176:179], v[28:31]
	v_mfma_f32_16x16x32_bf16 v[24:27], v[128:131], v[176:179], v[24:27]
	v_mfma_f32_16x16x32_bf16 v[12:15], v[120:123], v[184:187], v[12:15]
	v_mfma_f32_16x16x32_bf16 v[8:11], v[128:131], v[184:187], v[8:11]
	v_mfma_f32_16x16x32_bf16 v[60:63], v[124:127], v[164:167], v[60:63]
	v_mfma_f32_16x16x32_bf16 v[56:59], v[132:135], v[164:167], v[56:59]
	v_mfma_f32_16x16x32_bf16 v[44:47], v[124:127], v[172:175], v[44:47]
	v_mfma_f32_16x16x32_bf16 v[40:43], v[132:135], v[172:175], v[40:43]
	v_mfma_f32_16x16x32_bf16 v[28:31], v[124:127], v[180:183], v[28:31]
	v_mfma_f32_16x16x32_bf16 v[24:27], v[132:135], v[180:183], v[24:27]
	v_mfma_f32_16x16x32_bf16 v[12:15], v[124:127], v[188:191], v[12:15]
	v_mfma_f32_16x16x32_bf16 v[8:11], v[132:135], v[188:191], v[8:11]
	s_setprio 0
	s_setprio 1
	v_mfma_f32_16x16x32_bf16 v[52:55], v[144:147], v[160:163], v[52:55]
	v_mfma_f32_16x16x32_bf16 v[48:51], v[152:155], v[160:163], v[48:51]
	v_mfma_f32_16x16x32_bf16 v[36:39], v[144:147], v[168:171], v[36:39]
	v_mfma_f32_16x16x32_bf16 v[32:35], v[152:155], v[168:171], v[32:35]
	v_mfma_f32_16x16x32_bf16 v[20:23], v[144:147], v[176:179], v[20:23]
	v_mfma_f32_16x16x32_bf16 v[16:19], v[152:155], v[176:179], v[16:19]
	v_mfma_f32_16x16x32_bf16 v[4:7], v[144:147], v[184:187], v[4:7]
	v_mfma_f32_16x16x32_bf16 v[0:3], v[152:155], v[184:187], v[0:3]
	v_mfma_f32_16x16x32_bf16 v[52:55], v[148:151], v[164:167], v[52:55]
	v_mfma_f32_16x16x32_bf16 v[48:51], v[156:159], v[164:167], v[48:51]
	v_mfma_f32_16x16x32_bf16 v[36:39], v[148:151], v[172:175], v[36:39]
	v_mfma_f32_16x16x32_bf16 v[32:35], v[156:159], v[172:175], v[32:35]
	s_setprio 3
	s_barrier
	v_mfma_f32_16x16x32_bf16 v[20:23], v[148:151], v[180:183], v[20:23]
	v_mfma_f32_16x16x32_bf16 v[16:19], v[156:159], v[180:183], v[16:19]
	v_mfma_f32_16x16x32_bf16 v[4:7], v[148:151], v[188:191], v[4:7]
	v_mfma_f32_16x16x32_bf16 v[0:3], v[156:159], v[188:191], v[0:3]
	s_setprio 0
	s_add_i32 s59, 0, 0x18000
	s_add_i32 s68, 0, 0x1c000
	v_add_u32_e32 v132, s59, v243
	v_add_u32_e32 v156, s68, v243
	ds_read_b128 v[120:123], v132
	ds_read_b128 v[124:127], v132 offset:1024
	ds_read_b128 v[128:131], v132 offset:2048
	ds_read_b128 v[132:135], v132 offset:3072
	ds_read_b128 v[144:147], v156
	ds_read_b128 v[148:151], v156 offset:1024
	ds_read_b128 v[152:155], v156 offset:2048
	ds_read_b128 v[156:159], v156 offset:3072
	s_add_u32 s66, s86, 0x40000
	s_addc_u32 s67, s87, 0
	s_mov_b32 m0, s18
	v_lshl_add_u64 v[212:213], s[66:67], 0, v[192:193]
	ds_read_b128 v[160:163], v247 offset:32768
	ds_read_b128 v[164:167], v247 offset:33792
	ds_read_b128 v[168:171], v247 offset:34816
	ds_read_b128 v[172:175], v247 offset:35840
	ds_read_b128 v[176:179], v247 offset:36864
	ds_read_b128 v[180:183], v247 offset:37888
	ds_read_b128 v[184:187], v247 offset:38912
	ds_read_b128 v[188:191], v247 offset:39936
	global_load_lds_dwordx4 v[212:213], off
	v_lshl_add_u64 v[212:213], s[66:67], 0, v[196:197]
	s_mov_b32 m0, s19
	s_nop 0
	global_load_lds_dwordx4 v[212:213], off
	s_waitcnt vmcnt(8)
	s_waitcnt lgkmcnt(0)
	s_barrier
	s_setprio 1
	s_waitcnt lgkmcnt(0)
	v_mfma_f32_16x16x32_bf16 v[140:143], v[120:123], v[160:163], v[140:143]
	v_mfma_f32_16x16x32_bf16 v[136:139], v[128:131], v[160:163], v[136:139]
	v_mfma_f32_16x16x32_bf16 v[108:111], v[120:123], v[168:171], v[108:111]
	v_mfma_f32_16x16x32_bf16 v[104:107], v[128:131], v[168:171], v[104:107]
	v_mfma_f32_16x16x32_bf16 v[92:95], v[120:123], v[176:179], v[92:95]
	v_mfma_f32_16x16x32_bf16 v[88:91], v[128:131], v[176:179], v[88:91]
	v_mfma_f32_16x16x32_bf16 v[76:79], v[120:123], v[184:187], v[76:79]
	v_mfma_f32_16x16x32_bf16 v[72:75], v[128:131], v[184:187], v[72:75]
	v_mfma_f32_16x16x32_bf16 v[140:143], v[124:127], v[164:167], v[140:143]
	v_mfma_f32_16x16x32_bf16 v[136:139], v[132:135], v[164:167], v[136:139]
	v_mfma_f32_16x16x32_bf16 v[108:111], v[124:127], v[172:175], v[108:111]
	v_mfma_f32_16x16x32_bf16 v[104:107], v[132:135], v[172:175], v[104:107]
	v_mfma_f32_16x16x32_bf16 v[92:95], v[124:127], v[180:183], v[92:95]
	v_mfma_f32_16x16x32_bf16 v[88:91], v[132:135], v[180:183], v[88:91]
	v_mfma_f32_16x16x32_bf16 v[76:79], v[124:127], v[188:191], v[76:79]
	v_mfma_f32_16x16x32_bf16 v[72:75], v[132:135], v[188:191], v[72:75]
	s_setprio 0
	s_setprio 1
	v_mfma_f32_16x16x32_bf16 v[116:119], v[144:147], v[160:163], v[116:119]
	v_mfma_f32_16x16x32_bf16 v[112:115], v[152:155], v[160:163], v[112:115]
	v_mfma_f32_16x16x32_bf16 v[100:103], v[144:147], v[168:171], v[100:103]
	v_mfma_f32_16x16x32_bf16 v[96:99], v[152:155], v[168:171], v[96:99]
	v_mfma_f32_16x16x32_bf16 v[84:87], v[144:147], v[176:179], v[84:87]
	v_mfma_f32_16x16x32_bf16 v[80:83], v[152:155], v[176:179], v[80:83]
	v_mfma_f32_16x16x32_bf16 v[68:71], v[144:147], v[184:187], v[68:71]
	v_mfma_f32_16x16x32_bf16 v[64:67], v[152:155], v[184:187], v[64:67]
	v_mfma_f32_16x16x32_bf16 v[116:119], v[148:151], v[164:167], v[116:119]
	v_mfma_f32_16x16x32_bf16 v[112:115], v[156:159], v[164:167], v[112:115]
	v_mfma_f32_16x16x32_bf16 v[100:103], v[148:151], v[172:175], v[100:103]
	v_mfma_f32_16x16x32_bf16 v[96:99], v[156:159], v[172:175], v[96:99]
	s_setprio 3
	s_barrier
	v_mfma_f32_16x16x32_bf16 v[84:87], v[148:151], v[180:183], v[84:87]
	v_mfma_f32_16x16x32_bf16 v[80:83], v[156:159], v[180:183], v[80:83]
	v_mfma_f32_16x16x32_bf16 v[68:71], v[148:151], v[188:191], v[68:71]
	v_mfma_f32_16x16x32_bf16 v[64:67], v[156:159], v[188:191], v[64:67]
	s_setprio 0
	s_add_i32 s59, s59, s15
	v_lshl_add_u64 v[204:205], v[204:205], 0, s[46:47]
	s_mov_b32 m0, s59
	ds_read_b128 v[160:163], v247 offset:49152
	ds_read_b128 v[164:167], v247 offset:50176
	ds_read_b128 v[168:171], v247 offset:51200
	ds_read_b128 v[172:175], v247 offset:52224
	ds_read_b128 v[176:179], v247 offset:53248
	ds_read_b128 v[180:183], v247 offset:54272
	ds_read_b128 v[184:187], v247 offset:55296
	ds_read_b128 v[188:191], v247 offset:56320
	global_load_lds_dwordx4 v[204:205], off
	s_add_i32 m0, s59, 0x2000
	s_add_u32 s66, s84, 0x40080
	v_lshl_add_u64 v[204:205], v[206:207], 0, s[46:47]
	s_addc_u32 s67, s85, 0
	s_add_i32 s59, s68, s15
	global_load_lds_dwordx4 v[204:205], off
	v_lshl_add_u64 v[204:205], s[66:67], 0, v[194:195]
	s_mov_b32 m0, s59
	s_nop 0
	global_load_lds_dwordx4 v[204:205], off
	v_lshl_add_u64 v[204:205], s[66:67], 0, v[198:199]
	s_add_i32 m0, s59, 0x2000
	s_nop 0
	global_load_lds_dwordx4 v[204:205], off
	v_lshl_add_u64 v[204:205], v[208:209], 0, s[46:47]
	s_mov_b32 m0, s21
	s_nop 0
	global_load_lds_dwordx4 v[204:205], off
	v_lshl_add_u64 v[204:205], v[210:211], 0, s[46:47]
	s_mov_b32 m0, s22
	s_nop 0
	global_load_lds_dwordx4 v[204:205], off
	s_waitcnt vmcnt(8)
	s_waitcnt lgkmcnt(0)
	s_barrier
	s_setprio 1
	s_waitcnt lgkmcnt(0)
	v_mfma_f32_16x16x32_bf16 v[60:63], v[120:123], v[160:163], v[60:63]
	v_mfma_f32_16x16x32_bf16 v[56:59], v[128:131], v[160:163], v[56:59]
	v_mfma_f32_16x16x32_bf16 v[44:47], v[120:123], v[168:171], v[44:47]
	v_mfma_f32_16x16x32_bf16 v[40:43], v[128:131], v[168:171], v[40:43]
	v_mfma_f32_16x16x32_bf16 v[28:31], v[120:123], v[176:179], v[28:31]
	v_mfma_f32_16x16x32_bf16 v[24:27], v[128:131], v[176:179], v[24:27]
	v_mfma_f32_16x16x32_bf16 v[12:15], v[120:123], v[184:187], v[12:15]
	v_mfma_f32_16x16x32_bf16 v[8:11], v[128:131], v[184:187], v[8:11]
	v_mfma_f32_16x16x32_bf16 v[60:63], v[124:127], v[164:167], v[60:63]
	v_mfma_f32_16x16x32_bf16 v[56:59], v[132:135], v[164:167], v[56:59]
	v_mfma_f32_16x16x32_bf16 v[44:47], v[124:127], v[172:175], v[44:47]
	v_mfma_f32_16x16x32_bf16 v[40:43], v[132:135], v[172:175], v[40:43]
	v_mfma_f32_16x16x32_bf16 v[28:31], v[124:127], v[180:183], v[28:31]
	v_mfma_f32_16x16x32_bf16 v[24:27], v[132:135], v[180:183], v[24:27]
	v_mfma_f32_16x16x32_bf16 v[12:15], v[124:127], v[188:191], v[12:15]
	v_mfma_f32_16x16x32_bf16 v[8:11], v[132:135], v[188:191], v[8:11]
	s_setprio 0
	s_setprio 1
	v_mfma_f32_16x16x32_bf16 v[52:55], v[144:147], v[160:163], v[52:55]
	v_mfma_f32_16x16x32_bf16 v[48:51], v[152:155], v[160:163], v[48:51]
	v_mfma_f32_16x16x32_bf16 v[36:39], v[144:147], v[168:171], v[36:39]
	v_mfma_f32_16x16x32_bf16 v[32:35], v[152:155], v[168:171], v[32:35]
	v_mfma_f32_16x16x32_bf16 v[20:23], v[144:147], v[176:179], v[20:23]
	v_mfma_f32_16x16x32_bf16 v[16:19], v[152:155], v[176:179], v[16:19]
	v_mfma_f32_16x16x32_bf16 v[4:7], v[144:147], v[184:187], v[4:7]
	v_mfma_f32_16x16x32_bf16 v[0:3], v[152:155], v[184:187], v[0:3]
	v_mfma_f32_16x16x32_bf16 v[52:55], v[148:151], v[164:167], v[52:55]
	v_mfma_f32_16x16x32_bf16 v[48:51], v[156:159], v[164:167], v[48:51]
	v_mfma_f32_16x16x32_bf16 v[36:39], v[148:151], v[172:175], v[36:39]
	v_mfma_f32_16x16x32_bf16 v[32:35], v[156:159], v[172:175], v[32:35]
	s_setprio 3
	s_barrier
	v_mfma_f32_16x16x32_bf16 v[20:23], v[148:151], v[180:183], v[20:23]
	v_mfma_f32_16x16x32_bf16 v[16:19], v[156:159], v[180:183], v[16:19]
	v_mfma_f32_16x16x32_bf16 v[4:7], v[148:151], v[188:191], v[4:7]
	v_mfma_f32_16x16x32_bf16 v[0:3], v[156:159], v[188:191], v[0:3]
	s_setprio 0
	s_add_i32 s58, s58, 2
	s_add_u32 s82, s82, 0x100
	s_addc_u32 s83, s83, 0
	s_add_u32 s56, s56, 0x100
	s_addc_u32 s57, s57, 0
	s_cmp_gt_u32 s58, 13
	s_cbranch_scc0 .LBB0_993
	s_and_b64 vcc, exec, s[48:49]
	s_cbranch_vccz .LBB0_996
	s_barrier

.LBB0_1148:
	ds_read_b128 v[146:149], v174
	ds_read_b128 v[150:153], v174 offset:1024
	ds_read_b128 v[154:157], v174 offset:2048
	ds_read_b128 v[158:161], v174 offset:3072
	ds_read_b128 v[162:165], v175
	ds_read_b128 v[178:181], v175 offset:1024
	ds_read_b128 v[182:185], v175 offset:2048
	ds_read_b128 v[186:189], v175 offset:3072
	s_add_u32 s67, s78, 0xfffc0080
	s_addc_u32 s68, s79, -1
	s_cmp_eq_u32 s66, 12
	s_cselect_b32 s83, s49, s68
	s_cselect_b32 s82, s54, s67
	s_cselect_b32 s81, s47, s59
	s_cselect_b32 s80, s55, s58
	v_lshl_add_u64 v[166:167], s[78:79], 0, v[136:137]
	s_add_i32 m0, s17, 0xc000
	ds_read_b128 v[190:193], v176
	ds_read_b128 v[194:197], v176 offset:1024
	ds_read_b128 v[198:201], v176 offset:2048
	ds_read_b128 v[202:205], v176 offset:3072
	ds_read_b128 v[206:209], v176 offset:4096
	ds_read_b128 v[210:213], v176 offset:5120
	ds_read_b128 v[214:217], v176 offset:6144
	ds_read_b128 v[218:221], v176 offset:7168
	global_load_lds_dwordx4 v[166:167], off
	v_lshl_add_u64 v[166:167], s[78:79], 0, v[140:141]
	s_add_i32 m0, s17, 0xe000
	s_nop 0
	global_load_lds_dwordx4 v[166:167], off
	s_waitcnt vmcnt(8)
	s_waitcnt lgkmcnt(0)
	s_barrier
	s_setprio 1
	s_waitcnt lgkmcnt(0)
	v_mfma_f32_16x16x32_bf16 v[124:127], v[146:149], v[190:193], v[124:127]
	v_mfma_f32_16x16x32_bf16 v[116:119], v[154:157], v[190:193], v[116:119]
	v_mfma_f32_16x16x32_bf16 v[108:111], v[146:149], v[198:201], v[108:111]
	v_mfma_f32_16x16x32_bf16 v[100:103], v[154:157], v[198:201], v[100:103]
	v_mfma_f32_16x16x32_bf16 v[92:95], v[146:149], v[206:209], v[92:95]
	v_mfma_f32_16x16x32_bf16 v[84:87], v[154:157], v[206:209], v[84:87]
	v_mfma_f32_16x16x32_bf16 v[76:79], v[146:149], v[214:217], v[76:79]
	v_mfma_f32_16x16x32_bf16 v[68:71], v[154:157], v[214:217], v[68:71]
	v_mfma_f32_16x16x32_bf16 v[124:127], v[150:153], v[194:197], v[124:127]
	v_mfma_f32_16x16x32_bf16 v[116:119], v[158:161], v[194:197], v[116:119]
	v_mfma_f32_16x16x32_bf16 v[108:111], v[150:153], v[202:205], v[108:111]
	v_mfma_f32_16x16x32_bf16 v[100:103], v[158:161], v[202:205], v[100:103]
	v_mfma_f32_16x16x32_bf16 v[92:95], v[150:153], v[210:213], v[92:95]
	v_mfma_f32_16x16x32_bf16 v[84:87], v[158:161], v[210:213], v[84:87]
	v_mfma_f32_16x16x32_bf16 v[76:79], v[150:153], v[218:221], v[76:79]
	v_mfma_f32_16x16x32_bf16 v[68:71], v[158:161], v[218:221], v[68:71]
	s_setprio 0
	s_setprio 1
	v_mfma_f32_16x16x32_bf16 v[120:123], v[162:165], v[190:193], v[120:123]
	v_mfma_f32_16x16x32_bf16 v[112:115], v[182:185], v[190:193], v[112:115]
	v_mfma_f32_16x16x32_bf16 v[104:107], v[162:165], v[198:201], v[104:107]
	v_mfma_f32_16x16x32_bf16 v[96:99], v[182:185], v[198:201], v[96:99]
	v_mfma_f32_16x16x32_bf16 v[88:91], v[162:165], v[206:209], v[88:91]
	v_mfma_f32_16x16x32_bf16 v[80:83], v[182:185], v[206:209], v[80:83]
	v_mfma_f32_16x16x32_bf16 v[72:75], v[162:165], v[214:217], v[72:75]
	v_mfma_f32_16x16x32_bf16 v[64:67], v[182:185], v[214:217], v[64:67]
	v_mfma_f32_16x16x32_bf16 v[120:123], v[178:181], v[194:197], v[120:123]
	v_mfma_f32_16x16x32_bf16 v[112:115], v[186:189], v[194:197], v[112:115]
	v_mfma_f32_16x16x32_bf16 v[104:107], v[178:181], v[202:205], v[104:107]
	v_mfma_f32_16x16x32_bf16 v[96:99], v[186:189], v[202:205], v[96:99]
	s_setprio 3
	s_barrier
	v_mfma_f32_16x16x32_bf16 v[88:91], v[178:181], v[210:213], v[88:91]
	v_mfma_f32_16x16x32_bf16 v[80:83], v[186:189], v[210:213], v[80:83]
	v_mfma_f32_16x16x32_bf16 v[72:75], v[178:181], v[218:221], v[72:75]
	v_mfma_f32_16x16x32_bf16 v[64:67], v[186:189], v[218:221], v[64:67]
	s_setprio 0
	s_add_i32 s67, s25, s16
	v_lshl_add_u64 v[166:167], s[80:81], 0, v[132:133]
	s_mov_b32 m0, s67
	ds_read_b128 v[190:193], v176 offset:16384
	ds_read_b128 v[194:197], v176 offset:17408
	ds_read_b128 v[198:201], v176 offset:18432
	ds_read_b128 v[202:205], v176 offset:19456
	ds_read_b128 v[206:209], v176 offset:20480
	ds_read_b128 v[210:213], v176 offset:21504
	ds_read_b128 v[214:217], v176 offset:22528
	ds_read_b128 v[218:221], v176 offset:23552
	global_load_lds_dwordx4 v[166:167], off
	s_add_i32 m0, s67, 0x2000
	s_add_u32 s68, s80, 0x40000
	v_lshl_add_u64 v[222:223], s[80:81], 0, v[128:129]
	s_addc_u32 s69, s81, 0
	s_add_i32 s67, s26, s16
	global_load_lds_dwordx4 v[222:223], off
	v_lshl_add_u64 v[224:225], s[68:69], 0, v[132:133]
	s_mov_b32 m0, s67
	v_lshl_add_u64 v[226:227], s[82:83], 0, v[130:131]
	global_load_lds_dwordx4 v[224:225], off
	v_lshl_add_u64 v[224:225], s[68:69], 0, v[128:129]
	s_add_i32 m0, s67, 0x2000
	s_nop 0
	global_load_lds_dwordx4 v[224:225], off
	v_lshl_add_u64 v[224:225], s[82:83], 0, v[134:135]
	s_mov_b32 m0, s17
	s_nop 0
	global_load_lds_dwordx4 v[224:225], off
	s_mov_b32 m0, s18
	s_nop 0
	global_load_lds_dwordx4 v[226:227], off
	s_waitcnt vmcnt(8)
	s_waitcnt lgkmcnt(0)
	s_barrier
	s_setprio 1
	s_waitcnt lgkmcnt(0)
	v_mfma_f32_16x16x32_bf16 v[60:63], v[146:149], v[190:193], v[60:63]
	v_mfma_f32_16x16x32_bf16 v[52:55], v[154:157], v[190:193], v[52:55]
	v_mfma_f32_16x16x32_bf16 v[44:47], v[146:149], v[198:201], v[44:47]
	v_mfma_f32_16x16x32_bf16 v[36:39], v[154:157], v[198:201], v[36:39]
	v_mfma_f32_16x16x32_bf16 v[28:31], v[146:149], v[206:209], v[28:31]
	v_mfma_f32_16x16x32_bf16 v[20:23], v[154:157], v[206:209], v[20:23]
	v_mfma_f32_16x16x32_bf16 v[12:15], v[146:149], v[214:217], v[12:15]
	v_mfma_f32_16x16x32_bf16 v[4:7], v[154:157], v[214:217], v[4:7]
	v_mfma_f32_16x16x32_bf16 v[60:63], v[150:153], v[194:197], v[60:63]
	v_mfma_f32_16x16x32_bf16 v[52:55], v[158:161], v[194:197], v[52:55]
	v_mfma_f32_16x16x32_bf16 v[44:47], v[150:153], v[202:205], v[44:47]
	v_mfma_f32_16x16x32_bf16 v[36:39], v[158:161], v[202:205], v[36:39]
	v_mfma_f32_16x16x32_bf16 v[28:31], v[150:153], v[210:213], v[28:31]
	v_mfma_f32_16x16x32_bf16 v[20:23], v[158:161], v[210:213], v[20:23]
	v_mfma_f32_16x16x32_bf16 v[12:15], v[150:153], v[218:221], v[12:15]
	v_mfma_f32_16x16x32_bf16 v[4:7], v[158:161], v[218:221], v[4:7]
	s_setprio 0
	s_setprio 1
	v_mfma_f32_16x16x32_bf16 v[56:59], v[162:165], v[190:193], v[56:59]
	v_mfma_f32_16x16x32_bf16 v[48:51], v[182:185], v[190:193], v[48:51]
	v_mfma_f32_16x16x32_bf16 v[40:43], v[162:165], v[198:201], v[40:43]
	v_mfma_f32_16x16x32_bf16 v[32:35], v[182:185], v[198:201], v[32:35]
	v_mfma_f32_16x16x32_bf16 v[24:27], v[162:165], v[206:209], v[24:27]
	v_mfma_f32_16x16x32_bf16 v[16:19], v[182:185], v[206:209], v[16:19]
	v_mfma_f32_16x16x32_bf16 v[8:11], v[162:165], v[214:217], v[8:11]
	v_mfma_f32_16x16x32_bf16 v[0:3], v[182:185], v[214:217], v[0:3]
	v_mfma_f32_16x16x32_bf16 v[56:59], v[178:181], v[194:197], v[56:59]
	v_mfma_f32_16x16x32_bf16 v[48:51], v[186:189], v[194:197], v[48:51]
	v_mfma_f32_16x16x32_bf16 v[40:43], v[178:181], v[202:205], v[40:43]
	v_mfma_f32_16x16x32_bf16 v[32:35], v[186:189], v[202:205], v[32:35]
	s_setprio 3
	s_barrier
	v_mfma_f32_16x16x32_bf16 v[24:27], v[178:181], v[210:213], v[24:27]
	v_mfma_f32_16x16x32_bf16 v[16:19], v[186:189], v[210:213], v[16:19]
	v_mfma_f32_16x16x32_bf16 v[8:11], v[178:181], v[218:221], v[8:11]
	v_mfma_f32_16x16x32_bf16 v[0:3], v[186:189], v[218:221], v[0:3]
	s_setprio 0
	s_add_i32 s67, 0, 0x18000
	s_add_i32 s73, 0, 0x1c000
	v_add_u32_e32 v158, s67, v171
	v_add_u32_e32 v186, s73, v171
	ds_read_b128 v[146:149], v158
	ds_read_b128 v[150:153], v158 offset:1024
	ds_read_b128 v[154:157], v158 offset:2048
	ds_read_b128 v[158:161], v158 offset:3072
	ds_read_b128 v[162:165], v186
	ds_read_b128 v[178:181], v186 offset:1024
	ds_read_b128 v[182:185], v186 offset:2048
	ds_read_b128 v[186:189], v186 offset:3072
	s_add_u32 s68, s82, 0x40000
	s_addc_u32 s69, s83, 0
	s_mov_b32 m0, s19
	v_lshl_add_u64 v[228:229], s[68:69], 0, v[134:135]
	ds_read_b128 v[190:193], v176 offset:32768
	ds_read_b128 v[194:197], v176 offset:33792
	ds_read_b128 v[198:201], v176 offset:34816
	ds_read_b128 v[202:205], v176 offset:35840
	ds_read_b128 v[206:209], v176 offset:36864
	ds_read_b128 v[210:213], v176 offset:37888
	ds_read_b128 v[214:217], v176 offset:38912
	ds_read_b128 v[218:221], v176 offset:39936
	global_load_lds_dwordx4 v[228:229], off
	v_lshl_add_u64 v[228:229], s[68:69], 0, v[130:131]
	s_mov_b32 m0, s20
	s_nop 0
	global_load_lds_dwordx4 v[228:229], off
	s_waitcnt vmcnt(8)
	s_waitcnt lgkmcnt(0)
	s_barrier
	s_setprio 1
	s_waitcnt lgkmcnt(0)
	v_mfma_f32_16x16x32_bf16 v[124:127], v[146:149], v[190:193], v[124:127]
	v_mfma_f32_16x16x32_bf16 v[116:119], v[154:157], v[190:193], v[116:119]
	v_mfma_f32_16x16x32_bf16 v[108:111], v[146:149], v[198:201], v[108:111]
	v_mfma_f32_16x16x32_bf16 v[100:103], v[154:157], v[198:201], v[100:103]
	v_mfma_f32_16x16x32_bf16 v[92:95], v[146:149], v[206:209], v[92:95]
	v_mfma_f32_16x16x32_bf16 v[84:87], v[154:157], v[206:209], v[84:87]
	v_mfma_f32_16x16x32_bf16 v[76:79], v[146:149], v[214:217], v[76:79]
	v_mfma_f32_16x16x32_bf16 v[68:71], v[154:157], v[214:217], v[68:71]
	v_mfma_f32_16x16x32_bf16 v[124:127], v[150:153], v[194:197], v[124:127]
	v_mfma_f32_16x16x32_bf16 v[116:119], v[158:161], v[194:197], v[116:119]
	v_mfma_f32_16x16x32_bf16 v[108:111], v[150:153], v[202:205], v[108:111]
	v_mfma_f32_16x16x32_bf16 v[100:103], v[158:161], v[202:205], v[100:103]
	v_mfma_f32_16x16x32_bf16 v[92:95], v[150:153], v[210:213], v[92:95]
	v_mfma_f32_16x16x32_bf16 v[84:87], v[158:161], v[210:213], v[84:87]
	v_mfma_f32_16x16x32_bf16 v[76:79], v[150:153], v[218:221], v[76:79]
	v_mfma_f32_16x16x32_bf16 v[68:71], v[158:161], v[218:221], v[68:71]
	s_setprio 0
	s_setprio 1
	v_mfma_f32_16x16x32_bf16 v[120:123], v[162:165], v[190:193], v[120:123]
	v_mfma_f32_16x16x32_bf16 v[112:115], v[182:185], v[190:193], v[112:115]
	v_mfma_f32_16x16x32_bf16 v[104:107], v[162:165], v[198:201], v[104:107]
	v_mfma_f32_16x16x32_bf16 v[96:99], v[182:185], v[198:201], v[96:99]
	v_mfma_f32_16x16x32_bf16 v[88:91], v[162:165], v[206:209], v[88:91]
	v_mfma_f32_16x16x32_bf16 v[80:83], v[182:185], v[206:209], v[80:83]
	v_mfma_f32_16x16x32_bf16 v[72:75], v[162:165], v[214:217], v[72:75]
	v_mfma_f32_16x16x32_bf16 v[64:67], v[182:185], v[214:217], v[64:67]
	v_mfma_f32_16x16x32_bf16 v[120:123], v[178:181], v[194:197], v[120:123]
	v_mfma_f32_16x16x32_bf16 v[112:115], v[186:189], v[194:197], v[112:115]
	v_mfma_f32_16x16x32_bf16 v[104:107], v[178:181], v[202:205], v[104:107]
	v_mfma_f32_16x16x32_bf16 v[96:99], v[186:189], v[202:205], v[96:99]
	s_setprio 3
	s_barrier
	v_mfma_f32_16x16x32_bf16 v[88:91], v[178:181], v[210:213], v[88:91]
	v_mfma_f32_16x16x32_bf16 v[80:83], v[186:189], v[210:213], v[80:83]
	v_mfma_f32_16x16x32_bf16 v[72:75], v[178:181], v[218:221], v[72:75]
	v_mfma_f32_16x16x32_bf16 v[64:67], v[186:189], v[218:221], v[64:67]
	s_setprio 0
	s_add_i32 s67, s67, s16
	v_lshl_add_u64 v[166:167], v[166:167], 0, s[10:11]
	s_mov_b32 m0, s67
	ds_read_b128 v[190:193], v176 offset:49152
	ds_read_b128 v[194:197], v176 offset:50176
	ds_read_b128 v[198:201], v176 offset:51200
	ds_read_b128 v[202:205], v176 offset:52224
	ds_read_b128 v[206:209], v176 offset:53248
	ds_read_b128 v[210:213], v176 offset:54272
	ds_read_b128 v[214:217], v176 offset:55296
	ds_read_b128 v[218:221], v176 offset:56320
	global_load_lds_dwordx4 v[166:167], off
	s_add_i32 m0, s67, 0x2000
	s_add_u32 s68, s80, 0x40080
	v_lshl_add_u64 v[166:167], v[222:223], 0, s[10:11]
	s_addc_u32 s69, s81, 0
	s_add_i32 s67, s73, s16
	global_load_lds_dwordx4 v[166:167], off
	v_lshl_add_u64 v[166:167], s[68:69], 0, v[132:133]
	s_mov_b32 m0, s67
	s_nop 0
	global_load_lds_dwordx4 v[166:167], off
	v_lshl_add_u64 v[166:167], s[68:69], 0, v[128:129]
	s_add_i32 m0, s67, 0x2000
	s_nop 0
	global_load_lds_dwordx4 v[166:167], off
	v_lshl_add_u64 v[166:167], v[224:225], 0, s[10:11]
	s_mov_b32 m0, s23
	s_nop 0
	global_load_lds_dwordx4 v[166:167], off
	v_lshl_add_u64 v[166:167], v[226:227], 0, s[10:11]
	s_mov_b32 m0, s24
	s_nop 0
	global_load_lds_dwordx4 v[166:167], off
	s_waitcnt vmcnt(8)
	s_waitcnt lgkmcnt(0)
	s_barrier
	s_setprio 1
	s_waitcnt lgkmcnt(0)
	v_mfma_f32_16x16x32_bf16 v[60:63], v[146:149], v[190:193], v[60:63]
	v_mfma_f32_16x16x32_bf16 v[52:55], v[154:157], v[190:193], v[52:55]
	v_mfma_f32_16x16x32_bf16 v[44:47], v[146:149], v[198:201], v[44:47]
	v_mfma_f32_16x16x32_bf16 v[36:39], v[154:157], v[198:201], v[36:39]
	v_mfma_f32_16x16x32_bf16 v[28:31], v[146:149], v[206:209], v[28:31]
	v_mfma_f32_16x16x32_bf16 v[20:23], v[154:157], v[206:209], v[20:23]
	v_mfma_f32_16x16x32_bf16 v[12:15], v[146:149], v[214:217], v[12:15]
	v_mfma_f32_16x16x32_bf16 v[4:7], v[154:157], v[214:217], v[4:7]
	v_mfma_f32_16x16x32_bf16 v[60:63], v[150:153], v[194:197], v[60:63]
	v_mfma_f32_16x16x32_bf16 v[52:55], v[158:161], v[194:197], v[52:55]
	v_mfma_f32_16x16x32_bf16 v[44:47], v[150:153], v[202:205], v[44:47]
	v_mfma_f32_16x16x32_bf16 v[36:39], v[158:161], v[202:205], v[36:39]
	v_mfma_f32_16x16x32_bf16 v[28:31], v[150:153], v[210:213], v[28:31]
	v_mfma_f32_16x16x32_bf16 v[20:23], v[158:161], v[210:213], v[20:23]
	v_mfma_f32_16x16x32_bf16 v[12:15], v[150:153], v[218:221], v[12:15]
	v_mfma_f32_16x16x32_bf16 v[4:7], v[158:161], v[218:221], v[4:7]
	s_setprio 0
	s_setprio 1
	v_mfma_f32_16x16x32_bf16 v[56:59], v[162:165], v[190:193], v[56:59]
	v_mfma_f32_16x16x32_bf16 v[48:51], v[182:185], v[190:193], v[48:51]
	v_mfma_f32_16x16x32_bf16 v[40:43], v[162:165], v[198:201], v[40:43]
	v_mfma_f32_16x16x32_bf16 v[32:35], v[182:185], v[198:201], v[32:35]
	v_mfma_f32_16x16x32_bf16 v[24:27], v[162:165], v[206:209], v[24:27]
	v_mfma_f32_16x16x32_bf16 v[16:19], v[182:185], v[206:209], v[16:19]
	v_mfma_f32_16x16x32_bf16 v[8:11], v[162:165], v[214:217], v[8:11]
	v_mfma_f32_16x16x32_bf16 v[0:3], v[182:185], v[214:217], v[0:3]
	v_mfma_f32_16x16x32_bf16 v[56:59], v[178:181], v[194:197], v[56:59]
	v_mfma_f32_16x16x32_bf16 v[48:51], v[186:189], v[194:197], v[48:51]
	v_mfma_f32_16x16x32_bf16 v[40:43], v[178:181], v[202:205], v[40:43]
	v_mfma_f32_16x16x32_bf16 v[32:35], v[186:189], v[202:205], v[32:35]
	s_setprio 3
	s_barrier
	v_mfma_f32_16x16x32_bf16 v[24:27], v[178:181], v[210:213], v[24:27]
	v_mfma_f32_16x16x32_bf16 v[16:19], v[186:189], v[210:213], v[16:19]
	v_mfma_f32_16x16x32_bf16 v[8:11], v[178:181], v[218:221], v[8:11]
	v_mfma_f32_16x16x32_bf16 v[0:3], v[186:189], v[218:221], v[0:3]
	s_setprio 0
	s_add_i32 s66, s66, 2
	s_add_u32 s78, s78, 0x100
	s_addc_u32 s79, s79, 0
	s_add_u32 s58, s58, 0x100
	s_addc_u32 s59, s59, 0
	s_cmp_gt_u32 s66, 13
	s_cbranch_scc0 .LBB0_1148
	s_and_b64 vcc, exec, s[44:45]
	s_cbranch_vccz .LBB0_1151
	s_barrier

.LBB0_1299:
	ds_read_b128 v[120:123], v245
	ds_read_b128 v[124:127], v245 offset:1024
	ds_read_b128 v[128:131], v245 offset:2048
	ds_read_b128 v[132:135], v245 offset:3072
	ds_read_b128 v[144:147], v246
	ds_read_b128 v[148:151], v246 offset:1024
	ds_read_b128 v[152:155], v246 offset:2048
	ds_read_b128 v[156:159], v246 offset:3072
	s_add_u32 s66, s76, 0xfff50080
	s_addc_u32 s67, s77, -1
	s_cmp_eq_u32 s59, 40
	s_cselect_b32 s81, s9, s67
	s_cselect_b32 s80, s8, s66
	s_cselect_b32 s79, s53, s58
	s_cselect_b32 s78, s52, s55
	v_lshl_add_u64 v[204:205], s[76:77], 0, v[200:201]
	s_add_i32 m0, s16, 0xc000
	ds_read_b128 v[160:163], v247
	ds_read_b128 v[164:167], v247 offset:1024
	ds_read_b128 v[168:171], v247 offset:2048
	ds_read_b128 v[172:175], v247 offset:3072
	ds_read_b128 v[176:179], v247 offset:4096
	ds_read_b128 v[180:183], v247 offset:5120
	ds_read_b128 v[184:187], v247 offset:6144
	ds_read_b128 v[188:191], v247 offset:7168
	global_load_lds_dwordx4 v[204:205], off
	v_lshl_add_u64 v[204:205], s[76:77], 0, v[202:203]
	s_add_i32 m0, s16, 0xe000
	s_nop 0
	global_load_lds_dwordx4 v[204:205], off
	s_waitcnt vmcnt(8)
	s_waitcnt lgkmcnt(0)
	s_barrier
	s_setprio 1
	s_waitcnt lgkmcnt(0)
	v_mfma_f32_16x16x32_bf16 v[140:143], v[120:123], v[160:163], v[140:143]
	v_mfma_f32_16x16x32_bf16 v[136:139], v[128:131], v[160:163], v[136:139]
	v_mfma_f32_16x16x32_bf16 v[108:111], v[120:123], v[168:171], v[108:111]
	v_mfma_f32_16x16x32_bf16 v[104:107], v[128:131], v[168:171], v[104:107]
	v_mfma_f32_16x16x32_bf16 v[92:95], v[120:123], v[176:179], v[92:95]
	v_mfma_f32_16x16x32_bf16 v[88:91], v[128:131], v[176:179], v[88:91]
	v_mfma_f32_16x16x32_bf16 v[76:79], v[120:123], v[184:187], v[76:79]
	v_mfma_f32_16x16x32_bf16 v[72:75], v[128:131], v[184:187], v[72:75]
	v_mfma_f32_16x16x32_bf16 v[140:143], v[124:127], v[164:167], v[140:143]
	v_mfma_f32_16x16x32_bf16 v[136:139], v[132:135], v[164:167], v[136:139]
	v_mfma_f32_16x16x32_bf16 v[108:111], v[124:127], v[172:175], v[108:111]
	v_mfma_f32_16x16x32_bf16 v[104:107], v[132:135], v[172:175], v[104:107]
	v_mfma_f32_16x16x32_bf16 v[92:95], v[124:127], v[180:183], v[92:95]
	v_mfma_f32_16x16x32_bf16 v[88:91], v[132:135], v[180:183], v[88:91]
	v_mfma_f32_16x16x32_bf16 v[76:79], v[124:127], v[188:191], v[76:79]
	v_mfma_f32_16x16x32_bf16 v[72:75], v[132:135], v[188:191], v[72:75]
	s_setprio 0
	s_setprio 1
	v_mfma_f32_16x16x32_bf16 v[116:119], v[144:147], v[160:163], v[116:119]
	v_mfma_f32_16x16x32_bf16 v[112:115], v[152:155], v[160:163], v[112:115]
	v_mfma_f32_16x16x32_bf16 v[100:103], v[144:147], v[168:171], v[100:103]
	v_mfma_f32_16x16x32_bf16 v[96:99], v[152:155], v[168:171], v[96:99]
	v_mfma_f32_16x16x32_bf16 v[84:87], v[144:147], v[176:179], v[84:87]
	v_mfma_f32_16x16x32_bf16 v[80:83], v[152:155], v[176:179], v[80:83]
	v_mfma_f32_16x16x32_bf16 v[68:71], v[144:147], v[184:187], v[68:71]
	v_mfma_f32_16x16x32_bf16 v[64:67], v[152:155], v[184:187], v[64:67]
	v_mfma_f32_16x16x32_bf16 v[116:119], v[148:151], v[164:167], v[116:119]
	v_mfma_f32_16x16x32_bf16 v[112:115], v[156:159], v[164:167], v[112:115]
	v_mfma_f32_16x16x32_bf16 v[100:103], v[148:151], v[172:175], v[100:103]
	v_mfma_f32_16x16x32_bf16 v[96:99], v[156:159], v[172:175], v[96:99]
	s_setprio 3
	s_barrier
	v_mfma_f32_16x16x32_bf16 v[84:87], v[148:151], v[180:183], v[84:87]
	v_mfma_f32_16x16x32_bf16 v[80:83], v[156:159], v[180:183], v[80:83]
	v_mfma_f32_16x16x32_bf16 v[68:71], v[148:151], v[188:191], v[68:71]
	v_mfma_f32_16x16x32_bf16 v[64:67], v[156:159], v[188:191], v[64:67]
	s_setprio 0
	s_add_i32 s66, s26, s15
	v_lshl_add_u64 v[204:205], s[78:79], 0, v[194:195]
	s_mov_b32 m0, s66
	ds_read_b128 v[160:163], v247 offset:16384
	ds_read_b128 v[164:167], v247 offset:17408
	ds_read_b128 v[168:171], v247 offset:18432
	ds_read_b128 v[172:175], v247 offset:19456
	ds_read_b128 v[176:179], v247 offset:20480
	ds_read_b128 v[180:183], v247 offset:21504
	ds_read_b128 v[184:187], v247 offset:22528
	ds_read_b128 v[188:191], v247 offset:23552
	global_load_lds_dwordx4 v[204:205], off
	s_add_i32 m0, s66, 0x2000
	s_add_u32 s66, s78, 0xb0000
	v_lshl_add_u64 v[206:207], s[78:79], 0, v[198:199]
	s_addc_u32 s67, s79, 0
	s_add_i32 s68, s27, s15
	global_load_lds_dwordx4 v[206:207], off
	v_lshl_add_u64 v[208:209], s[66:67], 0, v[194:195]
	s_mov_b32 m0, s68
	v_lshl_add_u64 v[210:211], s[80:81], 0, v[196:197]
	global_load_lds_dwordx4 v[208:209], off
	v_lshl_add_u64 v[208:209], s[66:67], 0, v[198:199]
	s_add_i32 m0, s68, 0x2000
	s_nop 0
	global_load_lds_dwordx4 v[208:209], off
	v_lshl_add_u64 v[208:209], s[80:81], 0, v[192:193]
	s_mov_b32 m0, s16
	s_nop 0
	global_load_lds_dwordx4 v[208:209], off
	s_mov_b32 m0, s17
	s_nop 0
	global_load_lds_dwordx4 v[210:211], off
	s_waitcnt vmcnt(8)
	s_waitcnt lgkmcnt(0)
	s_barrier
	s_setprio 1
	s_waitcnt lgkmcnt(0)
	v_mfma_f32_16x16x32_bf16 v[60:63], v[120:123], v[160:163], v[60:63]
	v_mfma_f32_16x16x32_bf16 v[56:59], v[128:131], v[160:163], v[56:59]
	v_mfma_f32_16x16x32_bf16 v[44:47], v[120:123], v[168:171], v[44:47]
	v_mfma_f32_16x16x32_bf16 v[40:43], v[128:131], v[168:171], v[40:43]
	v_mfma_f32_16x16x32_bf16 v[28:31], v[120:123], v[176:179], v[28:31]
	v_mfma_f32_16x16x32_bf16 v[24:27], v[128:131], v[176:179], v[24:27]
	v_mfma_f32_16x16x32_bf16 v[12:15], v[120:123], v[184:187], v[12:15]
	v_mfma_f32_16x16x32_bf16 v[8:11], v[128:131], v[184:187], v[8:11]
	v_mfma_f32_16x16x32_bf16 v[60:63], v[124:127], v[164:167], v[60:63]
	v_mfma_f32_16x16x32_bf16 v[56:59], v[132:135], v[164:167], v[56:59]
	v_mfma_f32_16x16x32_bf16 v[44:47], v[124:127], v[172:175], v[44:47]
	v_mfma_f32_16x16x32_bf16 v[40:43], v[132:135], v[172:175], v[40:43]
	v_mfma_f32_16x16x32_bf16 v[28:31], v[124:127], v[180:183], v[28:31]
	v_mfma_f32_16x16x32_bf16 v[24:27], v[132:135], v[180:183], v[24:27]
	v_mfma_f32_16x16x32_bf16 v[12:15], v[124:127], v[188:191], v[12:15]
	v_mfma_f32_16x16x32_bf16 v[8:11], v[132:135], v[188:191], v[8:11]
	s_setprio 0
	s_setprio 1
	v_mfma_f32_16x16x32_bf16 v[52:55], v[144:147], v[160:163], v[52:55]
	v_mfma_f32_16x16x32_bf16 v[48:51], v[152:155], v[160:163], v[48:51]
	v_mfma_f32_16x16x32_bf16 v[36:39], v[144:147], v[168:171], v[36:39]
	v_mfma_f32_16x16x32_bf16 v[32:35], v[152:155], v[168:171], v[32:35]
	v_mfma_f32_16x16x32_bf16 v[20:23], v[144:147], v[176:179], v[20:23]
	v_mfma_f32_16x16x32_bf16 v[16:19], v[152:155], v[176:179], v[16:19]
	v_mfma_f32_16x16x32_bf16 v[4:7], v[144:147], v[184:187], v[4:7]
	v_mfma_f32_16x16x32_bf16 v[0:3], v[152:155], v[184:187], v[0:3]
	v_mfma_f32_16x16x32_bf16 v[52:55], v[148:151], v[164:167], v[52:55]
	v_mfma_f32_16x16x32_bf16 v[48:51], v[156:159], v[164:167], v[48:51]
	v_mfma_f32_16x16x32_bf16 v[36:39], v[148:151], v[172:175], v[36:39]
	v_mfma_f32_16x16x32_bf16 v[32:35], v[156:159], v[172:175], v[32:35]
	s_setprio 3
	s_barrier
	v_mfma_f32_16x16x32_bf16 v[20:23], v[148:151], v[180:183], v[20:23]
	v_mfma_f32_16x16x32_bf16 v[16:19], v[156:159], v[180:183], v[16:19]
	v_mfma_f32_16x16x32_bf16 v[4:7], v[148:151], v[188:191], v[4:7]
	v_mfma_f32_16x16x32_bf16 v[0:3], v[156:159], v[188:191], v[0:3]
	s_setprio 0
	s_add_i32 s68, 0, 0x18000
	s_add_i32 s69, 0, 0x1c000
	v_add_u32_e32 v132, s68, v243
	v_add_u32_e32 v156, s69, v243
	ds_read_b128 v[120:123], v132
	ds_read_b128 v[124:127], v132 offset:1024
	ds_read_b128 v[128:131], v132 offset:2048
	ds_read_b128 v[132:135], v132 offset:3072
	ds_read_b128 v[144:147], v156
	ds_read_b128 v[148:151], v156 offset:1024
	ds_read_b128 v[152:155], v156 offset:2048
	ds_read_b128 v[156:159], v156 offset:3072
	s_add_u32 s66, s80, 0xb0000
	s_addc_u32 s67, s81, 0
	s_mov_b32 m0, s18
	v_lshl_add_u64 v[212:213], s[66:67], 0, v[192:193]
	ds_read_b128 v[160:163], v247 offset:32768
	ds_read_b128 v[164:167], v247 offset:33792
	ds_read_b128 v[168:171], v247 offset:34816
	ds_read_b128 v[172:175], v247 offset:35840
	ds_read_b128 v[176:179], v247 offset:36864
	ds_read_b128 v[180:183], v247 offset:37888
	ds_read_b128 v[184:187], v247 offset:38912
	ds_read_b128 v[188:191], v247 offset:39936
	global_load_lds_dwordx4 v[212:213], off
	v_lshl_add_u64 v[212:213], s[66:67], 0, v[196:197]
	s_mov_b32 m0, s19
	s_nop 0
	global_load_lds_dwordx4 v[212:213], off
	s_waitcnt vmcnt(8)
	s_waitcnt lgkmcnt(0)
	s_barrier
	s_setprio 1
	s_waitcnt lgkmcnt(0)
	v_mfma_f32_16x16x32_bf16 v[140:143], v[120:123], v[160:163], v[140:143]
	v_mfma_f32_16x16x32_bf16 v[136:139], v[128:131], v[160:163], v[136:139]
	v_mfma_f32_16x16x32_bf16 v[108:111], v[120:123], v[168:171], v[108:111]
	v_mfma_f32_16x16x32_bf16 v[104:107], v[128:131], v[168:171], v[104:107]
	v_mfma_f32_16x16x32_bf16 v[92:95], v[120:123], v[176:179], v[92:95]
	v_mfma_f32_16x16x32_bf16 v[88:91], v[128:131], v[176:179], v[88:91]
	v_mfma_f32_16x16x32_bf16 v[76:79], v[120:123], v[184:187], v[76:79]
	v_mfma_f32_16x16x32_bf16 v[72:75], v[128:131], v[184:187], v[72:75]
	v_mfma_f32_16x16x32_bf16 v[140:143], v[124:127], v[164:167], v[140:143]
	v_mfma_f32_16x16x32_bf16 v[136:139], v[132:135], v[164:167], v[136:139]
	v_mfma_f32_16x16x32_bf16 v[108:111], v[124:127], v[172:175], v[108:111]
	v_mfma_f32_16x16x32_bf16 v[104:107], v[132:135], v[172:175], v[104:107]
	v_mfma_f32_16x16x32_bf16 v[92:95], v[124:127], v[180:183], v[92:95]
	v_mfma_f32_16x16x32_bf16 v[88:91], v[132:135], v[180:183], v[88:91]
	v_mfma_f32_16x16x32_bf16 v[76:79], v[124:127], v[188:191], v[76:79]
	v_mfma_f32_16x16x32_bf16 v[72:75], v[132:135], v[188:191], v[72:75]
	s_setprio 0
	s_setprio 1
	v_mfma_f32_16x16x32_bf16 v[116:119], v[144:147], v[160:163], v[116:119]
	v_mfma_f32_16x16x32_bf16 v[112:115], v[152:155], v[160:163], v[112:115]
	v_mfma_f32_16x16x32_bf16 v[100:103], v[144:147], v[168:171], v[100:103]
	v_mfma_f32_16x16x32_bf16 v[96:99], v[152:155], v[168:171], v[96:99]
	v_mfma_f32_16x16x32_bf16 v[84:87], v[144:147], v[176:179], v[84:87]
	v_mfma_f32_16x16x32_bf16 v[80:83], v[152:155], v[176:179], v[80:83]
	v_mfma_f32_16x16x32_bf16 v[68:71], v[144:147], v[184:187], v[68:71]
	v_mfma_f32_16x16x32_bf16 v[64:67], v[152:155], v[184:187], v[64:67]
	v_mfma_f32_16x16x32_bf16 v[116:119], v[148:151], v[164:167], v[116:119]
	v_mfma_f32_16x16x32_bf16 v[112:115], v[156:159], v[164:167], v[112:115]
	v_mfma_f32_16x16x32_bf16 v[100:103], v[148:151], v[172:175], v[100:103]
	v_mfma_f32_16x16x32_bf16 v[96:99], v[156:159], v[172:175], v[96:99]
	s_setprio 3
	s_barrier
	v_mfma_f32_16x16x32_bf16 v[84:87], v[148:151], v[180:183], v[84:87]
	v_mfma_f32_16x16x32_bf16 v[80:83], v[156:159], v[180:183], v[80:83]
	v_mfma_f32_16x16x32_bf16 v[68:71], v[148:151], v[188:191], v[68:71]
	v_mfma_f32_16x16x32_bf16 v[64:67], v[156:159], v[188:191], v[64:67]
	s_setprio 0
	s_add_i32 s66, s68, s15
	v_lshl_add_u64 v[204:205], v[204:205], 0, s[48:49]
	s_mov_b32 m0, s66
	ds_read_b128 v[160:163], v247 offset:49152
	ds_read_b128 v[164:167], v247 offset:50176
	ds_read_b128 v[168:171], v247 offset:51200
	ds_read_b128 v[172:175], v247 offset:52224
	ds_read_b128 v[176:179], v247 offset:53248
	ds_read_b128 v[180:183], v247 offset:54272
	ds_read_b128 v[184:187], v247 offset:55296
	ds_read_b128 v[188:191], v247 offset:56320
	global_load_lds_dwordx4 v[204:205], off
	s_add_i32 m0, s66, 0x2000
	s_add_u32 s66, s78, 0xb0080
	v_lshl_add_u64 v[204:205], v[206:207], 0, s[48:49]
	s_addc_u32 s67, s79, 0
	s_add_i32 s68, s69, s15
	global_load_lds_dwordx4 v[204:205], off
	v_lshl_add_u64 v[204:205], s[66:67], 0, v[194:195]
	s_mov_b32 m0, s68
	s_nop 0
	global_load_lds_dwordx4 v[204:205], off
	v_lshl_add_u64 v[204:205], s[66:67], 0, v[198:199]
	s_add_i32 m0, s68, 0x2000
	s_nop 0
	global_load_lds_dwordx4 v[204:205], off
	v_lshl_add_u64 v[204:205], v[208:209], 0, s[48:49]
	s_mov_b32 m0, s21
	s_nop 0
	global_load_lds_dwordx4 v[204:205], off
	v_lshl_add_u64 v[204:205], v[210:211], 0, s[48:49]
	s_mov_b32 m0, s22
	s_nop 0
	global_load_lds_dwordx4 v[204:205], off
	s_waitcnt vmcnt(8)
	s_waitcnt lgkmcnt(0)
	s_barrier
	s_setprio 1
	s_waitcnt lgkmcnt(0)
	v_mfma_f32_16x16x32_bf16 v[60:63], v[120:123], v[160:163], v[60:63]
	v_mfma_f32_16x16x32_bf16 v[56:59], v[128:131], v[160:163], v[56:59]
	v_mfma_f32_16x16x32_bf16 v[44:47], v[120:123], v[168:171], v[44:47]
	v_mfma_f32_16x16x32_bf16 v[40:43], v[128:131], v[168:171], v[40:43]
	v_mfma_f32_16x16x32_bf16 v[28:31], v[120:123], v[176:179], v[28:31]
	v_mfma_f32_16x16x32_bf16 v[24:27], v[128:131], v[176:179], v[24:27]
	v_mfma_f32_16x16x32_bf16 v[12:15], v[120:123], v[184:187], v[12:15]
	v_mfma_f32_16x16x32_bf16 v[8:11], v[128:131], v[184:187], v[8:11]
	v_mfma_f32_16x16x32_bf16 v[60:63], v[124:127], v[164:167], v[60:63]
	v_mfma_f32_16x16x32_bf16 v[56:59], v[132:135], v[164:167], v[56:59]
	v_mfma_f32_16x16x32_bf16 v[44:47], v[124:127], v[172:175], v[44:47]
	v_mfma_f32_16x16x32_bf16 v[40:43], v[132:135], v[172:175], v[40:43]
	v_mfma_f32_16x16x32_bf16 v[28:31], v[124:127], v[180:183], v[28:31]
	v_mfma_f32_16x16x32_bf16 v[24:27], v[132:135], v[180:183], v[24:27]
	v_mfma_f32_16x16x32_bf16 v[12:15], v[124:127], v[188:191], v[12:15]
	v_mfma_f32_16x16x32_bf16 v[8:11], v[132:135], v[188:191], v[8:11]
	s_setprio 0
	s_setprio 1
	v_mfma_f32_16x16x32_bf16 v[52:55], v[144:147], v[160:163], v[52:55]
	v_mfma_f32_16x16x32_bf16 v[48:51], v[152:155], v[160:163], v[48:51]
	v_mfma_f32_16x16x32_bf16 v[36:39], v[144:147], v[168:171], v[36:39]
	v_mfma_f32_16x16x32_bf16 v[32:35], v[152:155], v[168:171], v[32:35]
	v_mfma_f32_16x16x32_bf16 v[20:23], v[144:147], v[176:179], v[20:23]
	v_mfma_f32_16x16x32_bf16 v[16:19], v[152:155], v[176:179], v[16:19]
	v_mfma_f32_16x16x32_bf16 v[4:7], v[144:147], v[184:187], v[4:7]
	v_mfma_f32_16x16x32_bf16 v[0:3], v[152:155], v[184:187], v[0:3]
	v_mfma_f32_16x16x32_bf16 v[52:55], v[148:151], v[164:167], v[52:55]
	v_mfma_f32_16x16x32_bf16 v[48:51], v[156:159], v[164:167], v[48:51]
	v_mfma_f32_16x16x32_bf16 v[36:39], v[148:151], v[172:175], v[36:39]
	v_mfma_f32_16x16x32_bf16 v[32:35], v[156:159], v[172:175], v[32:35]
	s_setprio 3
	s_barrier
	v_mfma_f32_16x16x32_bf16 v[20:23], v[148:151], v[180:183], v[20:23]
	v_mfma_f32_16x16x32_bf16 v[16:19], v[156:159], v[180:183], v[16:19]
	v_mfma_f32_16x16x32_bf16 v[4:7], v[148:151], v[188:191], v[4:7]
	v_mfma_f32_16x16x32_bf16 v[0:3], v[156:159], v[188:191], v[0:3]
	s_setprio 0
	s_add_i32 s59, s59, 2
	s_add_u32 s76, s76, 0x100
	s_addc_u32 s77, s77, 0
	s_add_u32 s55, s55, 0x100
	s_addc_u32 s58, s58, 0
	s_cmp_gt_u32 s59, 41
	s_cbranch_scc0 .LBB0_1299
	s_and_b64 vcc, exec, s[50:51]
	s_cbranch_vccz .LBB0_1302
	s_barrier

.LBB0_1760:
	ds_read_b128 v[128:131], v181
	ds_read_b128 v[132:135], v181 offset:1024
	ds_read_b128 v[136:139], v181 offset:2048
	ds_read_b128 v[160:163], v181 offset:3072
	ds_read_b128 v[164:167], v182
	ds_read_b128 v[168:171], v182 offset:1024
	ds_read_b128 v[186:189], v182 offset:2048
	ds_read_b128 v[190:193], v182 offset:3072
	s_add_u32 s69, s78, 0xfffc0080
	s_addc_u32 s73, s79, -1
	s_cmp_eq_u32 s68, 12
	s_cselect_b32 s83, s49, s73
	s_cselect_b32 s82, s54, s69
	s_cselect_b32 s81, s47, s67
	s_cselect_b32 s80, s55, s66
	v_lshl_add_u64 v[172:173], s[78:79], 0, v[152:153]
	s_add_i32 m0, s18, 0xc000
	ds_read_b128 v[194:197], v183
	ds_read_b128 v[198:201], v183 offset:1024
	ds_read_b128 v[202:205], v183 offset:2048
	ds_read_b128 v[206:209], v183 offset:3072
	ds_read_b128 v[210:213], v183 offset:4096
	ds_read_b128 v[214:217], v183 offset:5120
	ds_read_b128 v[218:221], v183 offset:6144
	ds_read_b128 v[222:225], v183 offset:7168
	global_load_lds_dwordx4 v[172:173], off
	v_lshl_add_u64 v[172:173], s[78:79], 0, v[154:155]
	s_add_i32 m0, s18, 0xe000
	s_nop 0
	global_load_lds_dwordx4 v[172:173], off
	s_waitcnt vmcnt(8)
	s_waitcnt lgkmcnt(0)
	s_barrier
	s_setprio 1
	s_waitcnt lgkmcnt(0)
	v_mfma_f32_16x16x32_bf16 v[124:127], v[128:131], v[194:197], v[124:127]
	v_mfma_f32_16x16x32_bf16 v[120:123], v[136:139], v[194:197], v[120:123]
	v_mfma_f32_16x16x32_bf16 v[108:111], v[128:131], v[202:205], v[108:111]
	v_mfma_f32_16x16x32_bf16 v[104:107], v[136:139], v[202:205], v[104:107]
	v_mfma_f32_16x16x32_bf16 v[92:95], v[128:131], v[210:213], v[92:95]
	v_mfma_f32_16x16x32_bf16 v[88:91], v[136:139], v[210:213], v[88:91]
	v_mfma_f32_16x16x32_bf16 v[76:79], v[128:131], v[218:221], v[76:79]
	v_mfma_f32_16x16x32_bf16 v[72:75], v[136:139], v[218:221], v[72:75]
	v_mfma_f32_16x16x32_bf16 v[124:127], v[132:135], v[198:201], v[124:127]
	v_mfma_f32_16x16x32_bf16 v[120:123], v[160:163], v[198:201], v[120:123]
	v_mfma_f32_16x16x32_bf16 v[108:111], v[132:135], v[206:209], v[108:111]
	v_mfma_f32_16x16x32_bf16 v[104:107], v[160:163], v[206:209], v[104:107]
	v_mfma_f32_16x16x32_bf16 v[92:95], v[132:135], v[214:217], v[92:95]
	v_mfma_f32_16x16x32_bf16 v[88:91], v[160:163], v[214:217], v[88:91]
	v_mfma_f32_16x16x32_bf16 v[76:79], v[132:135], v[222:225], v[76:79]
	v_mfma_f32_16x16x32_bf16 v[72:75], v[160:163], v[222:225], v[72:75]
	s_setprio 0
	s_setprio 1
	v_mfma_f32_16x16x32_bf16 v[116:119], v[164:167], v[194:197], v[116:119]
	v_mfma_f32_16x16x32_bf16 v[112:115], v[186:189], v[194:197], v[112:115]
	v_mfma_f32_16x16x32_bf16 v[100:103], v[164:167], v[202:205], v[100:103]
	v_mfma_f32_16x16x32_bf16 v[96:99], v[186:189], v[202:205], v[96:99]
	v_mfma_f32_16x16x32_bf16 v[84:87], v[164:167], v[210:213], v[84:87]
	v_mfma_f32_16x16x32_bf16 v[80:83], v[186:189], v[210:213], v[80:83]
	v_mfma_f32_16x16x32_bf16 v[68:71], v[164:167], v[218:221], v[68:71]
	v_mfma_f32_16x16x32_bf16 v[64:67], v[186:189], v[218:221], v[64:67]
	v_mfma_f32_16x16x32_bf16 v[116:119], v[168:171], v[198:201], v[116:119]
	v_mfma_f32_16x16x32_bf16 v[112:115], v[190:193], v[198:201], v[112:115]
	v_mfma_f32_16x16x32_bf16 v[100:103], v[168:171], v[206:209], v[100:103]
	v_mfma_f32_16x16x32_bf16 v[96:99], v[190:193], v[206:209], v[96:99]
	s_setprio 3
	s_barrier
	v_mfma_f32_16x16x32_bf16 v[84:87], v[168:171], v[214:217], v[84:87]
	v_mfma_f32_16x16x32_bf16 v[80:83], v[190:193], v[214:217], v[80:83]
	v_mfma_f32_16x16x32_bf16 v[68:71], v[168:171], v[222:225], v[68:71]
	v_mfma_f32_16x16x32_bf16 v[64:67], v[190:193], v[222:225], v[64:67]
	s_setprio 0
	s_add_i32 s69, s25, s17
	v_lshl_add_u64 v[172:173], s[80:81], 0, v[142:143]
	s_mov_b32 m0, s69
	ds_read_b128 v[194:197], v183 offset:16384
	ds_read_b128 v[198:201], v183 offset:17408
	ds_read_b128 v[202:205], v183 offset:18432
	ds_read_b128 v[206:209], v183 offset:19456
	ds_read_b128 v[210:213], v183 offset:20480
	ds_read_b128 v[214:217], v183 offset:21504
	ds_read_b128 v[218:221], v183 offset:22528
	ds_read_b128 v[222:225], v183 offset:23552
	global_load_lds_dwordx4 v[172:173], off
	s_add_i32 m0, s69, 0x2000
	s_add_u32 s84, s80, 0x40000
	v_lshl_add_u64 v[226:227], s[80:81], 0, v[146:147]
	s_addc_u32 s85, s81, 0
	s_add_i32 s69, s26, s17
	global_load_lds_dwordx4 v[226:227], off
	v_lshl_add_u64 v[228:229], s[84:85], 0, v[142:143]
	s_mov_b32 m0, s69
	v_lshl_add_u64 v[230:231], s[82:83], 0, v[144:145]
	global_load_lds_dwordx4 v[228:229], off
	v_lshl_add_u64 v[228:229], s[84:85], 0, v[146:147]
	s_add_i32 m0, s69, 0x2000
	s_nop 0
	global_load_lds_dwordx4 v[228:229], off
	v_lshl_add_u64 v[228:229], s[82:83], 0, v[140:141]
	s_mov_b32 m0, s18
	s_nop 0
	global_load_lds_dwordx4 v[228:229], off
	s_mov_b32 m0, s19
	s_nop 0
	global_load_lds_dwordx4 v[230:231], off
	s_waitcnt vmcnt(8)
	s_waitcnt lgkmcnt(0)
	s_barrier
	s_setprio 1
	s_waitcnt lgkmcnt(0)
	v_mfma_f32_16x16x32_bf16 v[60:63], v[128:131], v[194:197], v[60:63]
	v_mfma_f32_16x16x32_bf16 v[56:59], v[136:139], v[194:197], v[56:59]
	v_mfma_f32_16x16x32_bf16 v[44:47], v[128:131], v[202:205], v[44:47]
	v_mfma_f32_16x16x32_bf16 v[40:43], v[136:139], v[202:205], v[40:43]
	v_mfma_f32_16x16x32_bf16 v[28:31], v[128:131], v[210:213], v[28:31]
	v_mfma_f32_16x16x32_bf16 v[24:27], v[136:139], v[210:213], v[24:27]
	v_mfma_f32_16x16x32_bf16 v[12:15], v[128:131], v[218:221], v[12:15]
	v_mfma_f32_16x16x32_bf16 v[8:11], v[136:139], v[218:221], v[8:11]
	v_mfma_f32_16x16x32_bf16 v[60:63], v[132:135], v[198:201], v[60:63]
	v_mfma_f32_16x16x32_bf16 v[56:59], v[160:163], v[198:201], v[56:59]
	v_mfma_f32_16x16x32_bf16 v[44:47], v[132:135], v[206:209], v[44:47]
	v_mfma_f32_16x16x32_bf16 v[40:43], v[160:163], v[206:209], v[40:43]
	v_mfma_f32_16x16x32_bf16 v[28:31], v[132:135], v[214:217], v[28:31]
	v_mfma_f32_16x16x32_bf16 v[24:27], v[160:163], v[214:217], v[24:27]
	v_mfma_f32_16x16x32_bf16 v[12:15], v[132:135], v[222:225], v[12:15]
	v_mfma_f32_16x16x32_bf16 v[8:11], v[160:163], v[222:225], v[8:11]
	s_setprio 0
	s_setprio 1
	v_mfma_f32_16x16x32_bf16 v[52:55], v[164:167], v[194:197], v[52:55]
	v_mfma_f32_16x16x32_bf16 v[48:51], v[186:189], v[194:197], v[48:51]
	v_mfma_f32_16x16x32_bf16 v[36:39], v[164:167], v[202:205], v[36:39]
	v_mfma_f32_16x16x32_bf16 v[32:35], v[186:189], v[202:205], v[32:35]
	v_mfma_f32_16x16x32_bf16 v[20:23], v[164:167], v[210:213], v[20:23]
	v_mfma_f32_16x16x32_bf16 v[16:19], v[186:189], v[210:213], v[16:19]
	v_mfma_f32_16x16x32_bf16 v[4:7], v[164:167], v[218:221], v[4:7]
	v_mfma_f32_16x16x32_bf16 v[0:3], v[186:189], v[218:221], v[0:3]
	v_mfma_f32_16x16x32_bf16 v[52:55], v[168:171], v[198:201], v[52:55]
	v_mfma_f32_16x16x32_bf16 v[48:51], v[190:193], v[198:201], v[48:51]
	v_mfma_f32_16x16x32_bf16 v[36:39], v[168:171], v[206:209], v[36:39]
	v_mfma_f32_16x16x32_bf16 v[32:35], v[190:193], v[206:209], v[32:35]
	s_setprio 3
	s_barrier
	v_mfma_f32_16x16x32_bf16 v[20:23], v[168:171], v[214:217], v[20:23]
	v_mfma_f32_16x16x32_bf16 v[16:19], v[190:193], v[214:217], v[16:19]
	v_mfma_f32_16x16x32_bf16 v[4:7], v[168:171], v[222:225], v[4:7]
	v_mfma_f32_16x16x32_bf16 v[0:3], v[190:193], v[222:225], v[0:3]
	s_setprio 0
	s_add_i32 s69, 0, 0x18000
	v_add_u32_e32 v148, s69, v177
	s_add_i32 s73, 0, 0x1c000
	ds_read_b128 v[128:131], v148
	ds_read_b128 v[132:135], v148 offset:1024
	ds_read_b128 v[136:139], v148 offset:2048
	ds_read_b128 v[160:163], v148 offset:3072
	v_add_u32_e32 v148, s73, v177
	ds_read_b128 v[164:167], v148
	ds_read_b128 v[168:171], v148 offset:1024
	ds_read_b128 v[186:189], v148 offset:2048
	ds_read_b128 v[190:193], v148 offset:3072
	s_add_u32 s82, s82, 0x40000
	s_addc_u32 s83, s83, 0
	s_mov_b32 m0, s20
	v_lshl_add_u64 v[232:233], s[82:83], 0, v[140:141]
	ds_read_b128 v[194:197], v183 offset:32768
	ds_read_b128 v[198:201], v183 offset:33792
	ds_read_b128 v[202:205], v183 offset:34816
	ds_read_b128 v[206:209], v183 offset:35840
	ds_read_b128 v[210:213], v183 offset:36864
	ds_read_b128 v[214:217], v183 offset:37888
	ds_read_b128 v[218:221], v183 offset:38912
	ds_read_b128 v[222:225], v183 offset:39936
	global_load_lds_dwordx4 v[232:233], off
	v_lshl_add_u64 v[232:233], s[82:83], 0, v[144:145]
	s_mov_b32 m0, s21
	s_nop 0
	global_load_lds_dwordx4 v[232:233], off
	s_waitcnt vmcnt(8)
	s_waitcnt lgkmcnt(0)
	s_barrier
	s_setprio 1
	s_waitcnt lgkmcnt(0)
	v_mfma_f32_16x16x32_bf16 v[124:127], v[128:131], v[194:197], v[124:127]
	v_mfma_f32_16x16x32_bf16 v[120:123], v[136:139], v[194:197], v[120:123]
	v_mfma_f32_16x16x32_bf16 v[108:111], v[128:131], v[202:205], v[108:111]
	v_mfma_f32_16x16x32_bf16 v[104:107], v[136:139], v[202:205], v[104:107]
	v_mfma_f32_16x16x32_bf16 v[92:95], v[128:131], v[210:213], v[92:95]
	v_mfma_f32_16x16x32_bf16 v[88:91], v[136:139], v[210:213], v[88:91]
	v_mfma_f32_16x16x32_bf16 v[76:79], v[128:131], v[218:221], v[76:79]
	v_mfma_f32_16x16x32_bf16 v[72:75], v[136:139], v[218:221], v[72:75]
	v_mfma_f32_16x16x32_bf16 v[124:127], v[132:135], v[198:201], v[124:127]
	v_mfma_f32_16x16x32_bf16 v[120:123], v[160:163], v[198:201], v[120:123]
	v_mfma_f32_16x16x32_bf16 v[108:111], v[132:135], v[206:209], v[108:111]
	v_mfma_f32_16x16x32_bf16 v[104:107], v[160:163], v[206:209], v[104:107]
	v_mfma_f32_16x16x32_bf16 v[92:95], v[132:135], v[214:217], v[92:95]
	v_mfma_f32_16x16x32_bf16 v[88:91], v[160:163], v[214:217], v[88:91]
	v_mfma_f32_16x16x32_bf16 v[76:79], v[132:135], v[222:225], v[76:79]
	v_mfma_f32_16x16x32_bf16 v[72:75], v[160:163], v[222:225], v[72:75]
	s_setprio 0
	s_setprio 1
	v_mfma_f32_16x16x32_bf16 v[116:119], v[164:167], v[194:197], v[116:119]
	v_mfma_f32_16x16x32_bf16 v[112:115], v[186:189], v[194:197], v[112:115]
	v_mfma_f32_16x16x32_bf16 v[100:103], v[164:167], v[202:205], v[100:103]
	v_mfma_f32_16x16x32_bf16 v[96:99], v[186:189], v[202:205], v[96:99]
	v_mfma_f32_16x16x32_bf16 v[84:87], v[164:167], v[210:213], v[84:87]
	v_mfma_f32_16x16x32_bf16 v[80:83], v[186:189], v[210:213], v[80:83]
	v_mfma_f32_16x16x32_bf16 v[68:71], v[164:167], v[218:221], v[68:71]
	v_mfma_f32_16x16x32_bf16 v[64:67], v[186:189], v[218:221], v[64:67]
	v_mfma_f32_16x16x32_bf16 v[116:119], v[168:171], v[198:201], v[116:119]
	v_mfma_f32_16x16x32_bf16 v[112:115], v[190:193], v[198:201], v[112:115]
	v_mfma_f32_16x16x32_bf16 v[100:103], v[168:171], v[206:209], v[100:103]
	v_mfma_f32_16x16x32_bf16 v[96:99], v[190:193], v[206:209], v[96:99]
	s_setprio 3
	s_barrier
	v_mfma_f32_16x16x32_bf16 v[84:87], v[168:171], v[214:217], v[84:87]
	v_mfma_f32_16x16x32_bf16 v[80:83], v[190:193], v[214:217], v[80:83]
	v_mfma_f32_16x16x32_bf16 v[68:71], v[168:171], v[222:225], v[68:71]
	v_mfma_f32_16x16x32_bf16 v[64:67], v[190:193], v[222:225], v[64:67]
	s_setprio 0
	s_add_i32 s69, s69, s17
	v_lshl_add_u64 v[172:173], v[172:173], 0, s[10:11]
	s_mov_b32 m0, s69
	ds_read_b128 v[194:197], v183 offset:49152
	ds_read_b128 v[198:201], v183 offset:50176
	ds_read_b128 v[202:205], v183 offset:51200
	ds_read_b128 v[206:209], v183 offset:52224
	ds_read_b128 v[210:213], v183 offset:53248
	ds_read_b128 v[214:217], v183 offset:54272
	ds_read_b128 v[218:221], v183 offset:55296
	ds_read_b128 v[222:225], v183 offset:56320
	global_load_lds_dwordx4 v[172:173], off
	s_add_i32 m0, s69, 0x2000
	s_add_u32 s80, s80, 0x40080
	v_lshl_add_u64 v[172:173], v[226:227], 0, s[10:11]
	s_addc_u32 s81, s81, 0
	s_add_i32 s69, s73, s17
	global_load_lds_dwordx4 v[172:173], off
	v_lshl_add_u64 v[172:173], s[80:81], 0, v[142:143]
	s_mov_b32 m0, s69
	s_nop 0
	global_load_lds_dwordx4 v[172:173], off
	v_lshl_add_u64 v[172:173], s[80:81], 0, v[146:147]
	s_add_i32 m0, s69, 0x2000
	s_nop 0
	global_load_lds_dwordx4 v[172:173], off
	v_lshl_add_u64 v[172:173], v[228:229], 0, s[10:11]
	s_mov_b32 m0, s23
	s_nop 0
	global_load_lds_dwordx4 v[172:173], off
	v_lshl_add_u64 v[172:173], v[230:231], 0, s[10:11]
	s_mov_b32 m0, s24
	s_nop 0
	global_load_lds_dwordx4 v[172:173], off
	s_waitcnt vmcnt(8)
	s_waitcnt lgkmcnt(0)
	s_barrier
	s_setprio 1
	s_waitcnt lgkmcnt(0)
	v_mfma_f32_16x16x32_bf16 v[60:63], v[128:131], v[194:197], v[60:63]
	v_mfma_f32_16x16x32_bf16 v[56:59], v[136:139], v[194:197], v[56:59]
	v_mfma_f32_16x16x32_bf16 v[44:47], v[128:131], v[202:205], v[44:47]
	v_mfma_f32_16x16x32_bf16 v[40:43], v[136:139], v[202:205], v[40:43]
	v_mfma_f32_16x16x32_bf16 v[28:31], v[128:131], v[210:213], v[28:31]
	v_mfma_f32_16x16x32_bf16 v[24:27], v[136:139], v[210:213], v[24:27]
	v_mfma_f32_16x16x32_bf16 v[12:15], v[128:131], v[218:221], v[12:15]
	v_mfma_f32_16x16x32_bf16 v[8:11], v[136:139], v[218:221], v[8:11]
	v_mfma_f32_16x16x32_bf16 v[60:63], v[132:135], v[198:201], v[60:63]
	v_mfma_f32_16x16x32_bf16 v[56:59], v[160:163], v[198:201], v[56:59]
	v_mfma_f32_16x16x32_bf16 v[44:47], v[132:135], v[206:209], v[44:47]
	v_mfma_f32_16x16x32_bf16 v[40:43], v[160:163], v[206:209], v[40:43]
	v_mfma_f32_16x16x32_bf16 v[28:31], v[132:135], v[214:217], v[28:31]
	v_mfma_f32_16x16x32_bf16 v[24:27], v[160:163], v[214:217], v[24:27]
	v_mfma_f32_16x16x32_bf16 v[12:15], v[132:135], v[222:225], v[12:15]
	v_mfma_f32_16x16x32_bf16 v[8:11], v[160:163], v[222:225], v[8:11]
	s_setprio 0
	s_setprio 1
	v_mfma_f32_16x16x32_bf16 v[52:55], v[164:167], v[194:197], v[52:55]
	v_mfma_f32_16x16x32_bf16 v[48:51], v[186:189], v[194:197], v[48:51]
	v_mfma_f32_16x16x32_bf16 v[36:39], v[164:167], v[202:205], v[36:39]
	v_mfma_f32_16x16x32_bf16 v[32:35], v[186:189], v[202:205], v[32:35]
	v_mfma_f32_16x16x32_bf16 v[20:23], v[164:167], v[210:213], v[20:23]
	v_mfma_f32_16x16x32_bf16 v[16:19], v[186:189], v[210:213], v[16:19]
	v_mfma_f32_16x16x32_bf16 v[4:7], v[164:167], v[218:221], v[4:7]
	v_mfma_f32_16x16x32_bf16 v[0:3], v[186:189], v[218:221], v[0:3]
	v_mfma_f32_16x16x32_bf16 v[52:55], v[168:171], v[198:201], v[52:55]
	v_mfma_f32_16x16x32_bf16 v[48:51], v[190:193], v[198:201], v[48:51]
	v_mfma_f32_16x16x32_bf16 v[36:39], v[168:171], v[206:209], v[36:39]
	v_mfma_f32_16x16x32_bf16 v[32:35], v[190:193], v[206:209], v[32:35]
	s_setprio 3
	s_barrier
	v_mfma_f32_16x16x32_bf16 v[20:23], v[168:171], v[214:217], v[20:23]
	v_mfma_f32_16x16x32_bf16 v[16:19], v[190:193], v[214:217], v[16:19]
	v_mfma_f32_16x16x32_bf16 v[4:7], v[168:171], v[222:225], v[4:7]
	v_mfma_f32_16x16x32_bf16 v[0:3], v[190:193], v[222:225], v[0:3]
	s_setprio 0
	s_add_i32 s68, s68, 2
	s_add_u32 s78, s78, 0x100
	s_addc_u32 s79, s79, 0
	s_add_u32 s66, s66, 0x100
	s_addc_u32 s67, s67, 0
	s_cmp_gt_u32 s68, 13
	s_cbranch_scc0 .LBB0_1760
	s_and_b64 vcc, exec, s[44:45]
	s_cbranch_vccz .LBB0_1763
	s_barrier

.LBB0_2037:
	ds_read_b128 v[120:123], v245
	ds_read_b128 v[124:127], v245 offset:1024
	ds_read_b128 v[128:131], v245 offset:2048
	ds_read_b128 v[132:135], v245 offset:3072
	ds_read_b128 v[144:147], v246
	ds_read_b128 v[148:151], v246 offset:1024
	ds_read_b128 v[152:155], v246 offset:2048
	ds_read_b128 v[156:159], v246 offset:3072
	s_add_u32 s67, s76, 0xfffc0080
	s_addc_u32 s68, s77, -1
	s_cmp_eq_u32 s66, 12
	s_cselect_b32 s81, s53, s68
	s_cselect_b32 s80, s54, s67
	s_cselect_b32 s79, s51, s57
	s_cselect_b32 s78, s55, s56
	v_lshl_add_u64 v[204:205], s[76:77], 0, v[200:201]
	s_add_i32 m0, s16, 0xc000
	ds_read_b128 v[160:163], v247
	ds_read_b128 v[164:167], v247 offset:1024
	ds_read_b128 v[168:171], v247 offset:2048
	ds_read_b128 v[172:175], v247 offset:3072
	ds_read_b128 v[176:179], v247 offset:4096
	ds_read_b128 v[180:183], v247 offset:5120
	ds_read_b128 v[184:187], v247 offset:6144
	ds_read_b128 v[188:191], v247 offset:7168
	global_load_lds_dwordx4 v[204:205], off
	v_lshl_add_u64 v[204:205], s[76:77], 0, v[202:203]
	s_add_i32 m0, s16, 0xe000
	s_nop 0
	global_load_lds_dwordx4 v[204:205], off
	s_waitcnt vmcnt(8)
	s_waitcnt lgkmcnt(0)
	s_barrier
	s_setprio 1
	s_waitcnt lgkmcnt(0)
	v_mfma_f32_16x16x32_bf16 v[140:143], v[120:123], v[160:163], v[140:143]
	v_mfma_f32_16x16x32_bf16 v[136:139], v[128:131], v[160:163], v[136:139]
	v_mfma_f32_16x16x32_bf16 v[108:111], v[120:123], v[168:171], v[108:111]
	v_mfma_f32_16x16x32_bf16 v[104:107], v[128:131], v[168:171], v[104:107]
	v_mfma_f32_16x16x32_bf16 v[92:95], v[120:123], v[176:179], v[92:95]
	v_mfma_f32_16x16x32_bf16 v[88:91], v[128:131], v[176:179], v[88:91]
	v_mfma_f32_16x16x32_bf16 v[76:79], v[120:123], v[184:187], v[76:79]
	v_mfma_f32_16x16x32_bf16 v[72:75], v[128:131], v[184:187], v[72:75]
	v_mfma_f32_16x16x32_bf16 v[140:143], v[124:127], v[164:167], v[140:143]
	v_mfma_f32_16x16x32_bf16 v[136:139], v[132:135], v[164:167], v[136:139]
	v_mfma_f32_16x16x32_bf16 v[108:111], v[124:127], v[172:175], v[108:111]
	v_mfma_f32_16x16x32_bf16 v[104:107], v[132:135], v[172:175], v[104:107]
	v_mfma_f32_16x16x32_bf16 v[92:95], v[124:127], v[180:183], v[92:95]
	v_mfma_f32_16x16x32_bf16 v[88:91], v[132:135], v[180:183], v[88:91]
	v_mfma_f32_16x16x32_bf16 v[76:79], v[124:127], v[188:191], v[76:79]
	v_mfma_f32_16x16x32_bf16 v[72:75], v[132:135], v[188:191], v[72:75]
	s_setprio 0
	s_setprio 1
	v_mfma_f32_16x16x32_bf16 v[116:119], v[144:147], v[160:163], v[116:119]
	v_mfma_f32_16x16x32_bf16 v[112:115], v[152:155], v[160:163], v[112:115]
	v_mfma_f32_16x16x32_bf16 v[100:103], v[144:147], v[168:171], v[100:103]
	v_mfma_f32_16x16x32_bf16 v[96:99], v[152:155], v[168:171], v[96:99]
	v_mfma_f32_16x16x32_bf16 v[84:87], v[144:147], v[176:179], v[84:87]
	v_mfma_f32_16x16x32_bf16 v[80:83], v[152:155], v[176:179], v[80:83]
	v_mfma_f32_16x16x32_bf16 v[68:71], v[144:147], v[184:187], v[68:71]
	v_mfma_f32_16x16x32_bf16 v[64:67], v[152:155], v[184:187], v[64:67]
	v_mfma_f32_16x16x32_bf16 v[116:119], v[148:151], v[164:167], v[116:119]
	v_mfma_f32_16x16x32_bf16 v[112:115], v[156:159], v[164:167], v[112:115]
	v_mfma_f32_16x16x32_bf16 v[100:103], v[148:151], v[172:175], v[100:103]
	v_mfma_f32_16x16x32_bf16 v[96:99], v[156:159], v[172:175], v[96:99]
	s_setprio 3
	s_barrier
	v_mfma_f32_16x16x32_bf16 v[84:87], v[148:151], v[180:183], v[84:87]
	v_mfma_f32_16x16x32_bf16 v[80:83], v[156:159], v[180:183], v[80:83]
	v_mfma_f32_16x16x32_bf16 v[68:71], v[148:151], v[188:191], v[68:71]
	v_mfma_f32_16x16x32_bf16 v[64:67], v[156:159], v[188:191], v[64:67]
	s_setprio 0
	s_add_i32 s67, s26, s15
	v_lshl_add_u64 v[204:205], s[78:79], 0, v[194:195]
	s_mov_b32 m0, s67
	ds_read_b128 v[160:163], v247 offset:16384
	ds_read_b128 v[164:167], v247 offset:17408
	ds_read_b128 v[168:171], v247 offset:18432
	ds_read_b128 v[172:175], v247 offset:19456
	ds_read_b128 v[176:179], v247 offset:20480
	ds_read_b128 v[180:183], v247 offset:21504
	ds_read_b128 v[184:187], v247 offset:22528
	ds_read_b128 v[188:191], v247 offset:23552
	global_load_lds_dwordx4 v[204:205], off
	s_add_i32 m0, s67, 0x2000
	s_add_u32 s68, s78, 0x40000
	v_lshl_add_u64 v[206:207], s[78:79], 0, v[198:199]
	s_addc_u32 s69, s79, 0
	s_add_i32 s67, s27, s15
	global_load_lds_dwordx4 v[206:207], off
	v_lshl_add_u64 v[208:209], s[68:69], 0, v[194:195]
	s_mov_b32 m0, s67
	v_lshl_add_u64 v[210:211], s[80:81], 0, v[196:197]
	global_load_lds_dwordx4 v[208:209], off
	v_lshl_add_u64 v[208:209], s[68:69], 0, v[198:199]
	s_add_i32 m0, s67, 0x2000
	s_nop 0
	global_load_lds_dwordx4 v[208:209], off
	v_lshl_add_u64 v[208:209], s[80:81], 0, v[192:193]
	s_mov_b32 m0, s16
	s_nop 0
	global_load_lds_dwordx4 v[208:209], off
	s_mov_b32 m0, s17
	s_nop 0
	global_load_lds_dwordx4 v[210:211], off
	s_waitcnt vmcnt(8)
	s_waitcnt lgkmcnt(0)
	s_barrier
	s_setprio 1
	s_waitcnt lgkmcnt(0)
	v_mfma_f32_16x16x32_bf16 v[60:63], v[120:123], v[160:163], v[60:63]
	v_mfma_f32_16x16x32_bf16 v[56:59], v[128:131], v[160:163], v[56:59]
	v_mfma_f32_16x16x32_bf16 v[44:47], v[120:123], v[168:171], v[44:47]
	v_mfma_f32_16x16x32_bf16 v[40:43], v[128:131], v[168:171], v[40:43]
	v_mfma_f32_16x16x32_bf16 v[28:31], v[120:123], v[176:179], v[28:31]
	v_mfma_f32_16x16x32_bf16 v[24:27], v[128:131], v[176:179], v[24:27]
	v_mfma_f32_16x16x32_bf16 v[12:15], v[120:123], v[184:187], v[12:15]
	v_mfma_f32_16x16x32_bf16 v[8:11], v[128:131], v[184:187], v[8:11]
	v_mfma_f32_16x16x32_bf16 v[60:63], v[124:127], v[164:167], v[60:63]
	v_mfma_f32_16x16x32_bf16 v[56:59], v[132:135], v[164:167], v[56:59]
	v_mfma_f32_16x16x32_bf16 v[44:47], v[124:127], v[172:175], v[44:47]
	v_mfma_f32_16x16x32_bf16 v[40:43], v[132:135], v[172:175], v[40:43]
	v_mfma_f32_16x16x32_bf16 v[28:31], v[124:127], v[180:183], v[28:31]
	v_mfma_f32_16x16x32_bf16 v[24:27], v[132:135], v[180:183], v[24:27]
	v_mfma_f32_16x16x32_bf16 v[12:15], v[124:127], v[188:191], v[12:15]
	v_mfma_f32_16x16x32_bf16 v[8:11], v[132:135], v[188:191], v[8:11]
	s_setprio 0
	s_setprio 1
	v_mfma_f32_16x16x32_bf16 v[52:55], v[144:147], v[160:163], v[52:55]
	v_mfma_f32_16x16x32_bf16 v[48:51], v[152:155], v[160:163], v[48:51]
	v_mfma_f32_16x16x32_bf16 v[36:39], v[144:147], v[168:171], v[36:39]
	v_mfma_f32_16x16x32_bf16 v[32:35], v[152:155], v[168:171], v[32:35]
	v_mfma_f32_16x16x32_bf16 v[20:23], v[144:147], v[176:179], v[20:23]
	v_mfma_f32_16x16x32_bf16 v[16:19], v[152:155], v[176:179], v[16:19]
	v_mfma_f32_16x16x32_bf16 v[4:7], v[144:147], v[184:187], v[4:7]
	v_mfma_f32_16x16x32_bf16 v[0:3], v[152:155], v[184:187], v[0:3]
	v_mfma_f32_16x16x32_bf16 v[52:55], v[148:151], v[164:167], v[52:55]
	v_mfma_f32_16x16x32_bf16 v[48:51], v[156:159], v[164:167], v[48:51]
	v_mfma_f32_16x16x32_bf16 v[36:39], v[148:151], v[172:175], v[36:39]
	v_mfma_f32_16x16x32_bf16 v[32:35], v[156:159], v[172:175], v[32:35]
	s_setprio 3
	s_barrier
	v_mfma_f32_16x16x32_bf16 v[20:23], v[148:151], v[180:183], v[20:23]
	v_mfma_f32_16x16x32_bf16 v[16:19], v[156:159], v[180:183], v[16:19]
	v_mfma_f32_16x16x32_bf16 v[4:7], v[148:151], v[188:191], v[4:7]
	v_mfma_f32_16x16x32_bf16 v[0:3], v[156:159], v[188:191], v[0:3]
	s_setprio 0
	s_add_i32 s67, 0, 0x18000
	s_add_i32 s75, 0, 0x1c000
	v_add_u32_e32 v132, s67, v243
	v_add_u32_e32 v156, s75, v243
	ds_read_b128 v[120:123], v132
	ds_read_b128 v[124:127], v132 offset:1024
	ds_read_b128 v[128:131], v132 offset:2048
	ds_read_b128 v[132:135], v132 offset:3072
	ds_read_b128 v[144:147], v156
	ds_read_b128 v[148:151], v156 offset:1024
	ds_read_b128 v[152:155], v156 offset:2048
	ds_read_b128 v[156:159], v156 offset:3072
	s_add_u32 s68, s80, 0x40000
	s_addc_u32 s69, s81, 0
	s_mov_b32 m0, s18
	v_lshl_add_u64 v[212:213], s[68:69], 0, v[192:193]
	ds_read_b128 v[160:163], v247 offset:32768
	ds_read_b128 v[164:167], v247 offset:33792
	ds_read_b128 v[168:171], v247 offset:34816
	ds_read_b128 v[172:175], v247 offset:35840
	ds_read_b128 v[176:179], v247 offset:36864
	ds_read_b128 v[180:183], v247 offset:37888
	ds_read_b128 v[184:187], v247 offset:38912
	ds_read_b128 v[188:191], v247 offset:39936
	global_load_lds_dwordx4 v[212:213], off
	v_lshl_add_u64 v[212:213], s[68:69], 0, v[196:197]
	s_mov_b32 m0, s19
	s_nop 0
	global_load_lds_dwordx4 v[212:213], off
	s_waitcnt vmcnt(8)
	s_waitcnt lgkmcnt(0)
	s_barrier
	s_setprio 1
	s_waitcnt lgkmcnt(0)
	v_mfma_f32_16x16x32_bf16 v[140:143], v[120:123], v[160:163], v[140:143]
	v_mfma_f32_16x16x32_bf16 v[136:139], v[128:131], v[160:163], v[136:139]
	v_mfma_f32_16x16x32_bf16 v[108:111], v[120:123], v[168:171], v[108:111]
	v_mfma_f32_16x16x32_bf16 v[104:107], v[128:131], v[168:171], v[104:107]
	v_mfma_f32_16x16x32_bf16 v[92:95], v[120:123], v[176:179], v[92:95]
	v_mfma_f32_16x16x32_bf16 v[88:91], v[128:131], v[176:179], v[88:91]
	v_mfma_f32_16x16x32_bf16 v[76:79], v[120:123], v[184:187], v[76:79]
	v_mfma_f32_16x16x32_bf16 v[72:75], v[128:131], v[184:187], v[72:75]
	v_mfma_f32_16x16x32_bf16 v[140:143], v[124:127], v[164:167], v[140:143]
	v_mfma_f32_16x16x32_bf16 v[136:139], v[132:135], v[164:167], v[136:139]
	v_mfma_f32_16x16x32_bf16 v[108:111], v[124:127], v[172:175], v[108:111]
	v_mfma_f32_16x16x32_bf16 v[104:107], v[132:135], v[172:175], v[104:107]
	v_mfma_f32_16x16x32_bf16 v[92:95], v[124:127], v[180:183], v[92:95]
	v_mfma_f32_16x16x32_bf16 v[88:91], v[132:135], v[180:183], v[88:91]
	v_mfma_f32_16x16x32_bf16 v[76:79], v[124:127], v[188:191], v[76:79]
	v_mfma_f32_16x16x32_bf16 v[72:75], v[132:135], v[188:191], v[72:75]
	s_setprio 0
	s_setprio 1
	v_mfma_f32_16x16x32_bf16 v[116:119], v[144:147], v[160:163], v[116:119]
	v_mfma_f32_16x16x32_bf16 v[112:115], v[152:155], v[160:163], v[112:115]
	v_mfma_f32_16x16x32_bf16 v[100:103], v[144:147], v[168:171], v[100:103]
	v_mfma_f32_16x16x32_bf16 v[96:99], v[152:155], v[168:171], v[96:99]
	v_mfma_f32_16x16x32_bf16 v[84:87], v[144:147], v[176:179], v[84:87]
	v_mfma_f32_16x16x32_bf16 v[80:83], v[152:155], v[176:179], v[80:83]
	v_mfma_f32_16x16x32_bf16 v[68:71], v[144:147], v[184:187], v[68:71]
	v_mfma_f32_16x16x32_bf16 v[64:67], v[152:155], v[184:187], v[64:67]
	v_mfma_f32_16x16x32_bf16 v[116:119], v[148:151], v[164:167], v[116:119]
	v_mfma_f32_16x16x32_bf16 v[112:115], v[156:159], v[164:167], v[112:115]
	v_mfma_f32_16x16x32_bf16 v[100:103], v[148:151], v[172:175], v[100:103]
	v_mfma_f32_16x16x32_bf16 v[96:99], v[156:159], v[172:175], v[96:99]
	s_setprio 3
	s_barrier
	v_mfma_f32_16x16x32_bf16 v[84:87], v[148:151], v[180:183], v[84:87]
	v_mfma_f32_16x16x32_bf16 v[80:83], v[156:159], v[180:183], v[80:83]
	v_mfma_f32_16x16x32_bf16 v[68:71], v[148:151], v[188:191], v[68:71]
	v_mfma_f32_16x16x32_bf16 v[64:67], v[156:159], v[188:191], v[64:67]
	s_setprio 0
	s_add_i32 s67, s67, s15
	v_lshl_add_u64 v[204:205], v[204:205], 0, s[46:47]
	s_mov_b32 m0, s67
	ds_read_b128 v[160:163], v247 offset:49152
	ds_read_b128 v[164:167], v247 offset:50176
	ds_read_b128 v[168:171], v247 offset:51200
	ds_read_b128 v[172:175], v247 offset:52224
	ds_read_b128 v[176:179], v247 offset:53248
	ds_read_b128 v[180:183], v247 offset:54272
	ds_read_b128 v[184:187], v247 offset:55296
	ds_read_b128 v[188:191], v247 offset:56320
	global_load_lds_dwordx4 v[204:205], off
	s_add_i32 m0, s67, 0x2000
	s_add_u32 s68, s78, 0x40080
	v_lshl_add_u64 v[204:205], v[206:207], 0, s[46:47]
	s_addc_u32 s69, s79, 0
	s_add_i32 s67, s75, s15
	global_load_lds_dwordx4 v[204:205], off
	v_lshl_add_u64 v[204:205], s[68:69], 0, v[194:195]
	s_mov_b32 m0, s67
	s_nop 0
	global_load_lds_dwordx4 v[204:205], off
	v_lshl_add_u64 v[204:205], s[68:69], 0, v[198:199]
	s_add_i32 m0, s67, 0x2000
	s_nop 0
	global_load_lds_dwordx4 v[204:205], off
	v_lshl_add_u64 v[204:205], v[208:209], 0, s[46:47]
	s_mov_b32 m0, s21
	s_nop 0
	global_load_lds_dwordx4 v[204:205], off
	v_lshl_add_u64 v[204:205], v[210:211], 0, s[46:47]
	s_mov_b32 m0, s22
	s_nop 0
	global_load_lds_dwordx4 v[204:205], off
	s_waitcnt vmcnt(8)
	s_waitcnt lgkmcnt(0)
	s_barrier
	s_setprio 1
	s_waitcnt lgkmcnt(0)
	v_mfma_f32_16x16x32_bf16 v[60:63], v[120:123], v[160:163], v[60:63]
	v_mfma_f32_16x16x32_bf16 v[56:59], v[128:131], v[160:163], v[56:59]
	v_mfma_f32_16x16x32_bf16 v[44:47], v[120:123], v[168:171], v[44:47]
	v_mfma_f32_16x16x32_bf16 v[40:43], v[128:131], v[168:171], v[40:43]
	v_mfma_f32_16x16x32_bf16 v[28:31], v[120:123], v[176:179], v[28:31]
	v_mfma_f32_16x16x32_bf16 v[24:27], v[128:131], v[176:179], v[24:27]
	v_mfma_f32_16x16x32_bf16 v[12:15], v[120:123], v[184:187], v[12:15]
	v_mfma_f32_16x16x32_bf16 v[8:11], v[128:131], v[184:187], v[8:11]
	v_mfma_f32_16x16x32_bf16 v[60:63], v[124:127], v[164:167], v[60:63]
	v_mfma_f32_16x16x32_bf16 v[56:59], v[132:135], v[164:167], v[56:59]
	v_mfma_f32_16x16x32_bf16 v[44:47], v[124:127], v[172:175], v[44:47]
	v_mfma_f32_16x16x32_bf16 v[40:43], v[132:135], v[172:175], v[40:43]
	v_mfma_f32_16x16x32_bf16 v[28:31], v[124:127], v[180:183], v[28:31]
	v_mfma_f32_16x16x32_bf16 v[24:27], v[132:135], v[180:183], v[24:27]
	v_mfma_f32_16x16x32_bf16 v[12:15], v[124:127], v[188:191], v[12:15]
	v_mfma_f32_16x16x32_bf16 v[8:11], v[132:135], v[188:191], v[8:11]
	s_setprio 0
	s_setprio 1
	v_mfma_f32_16x16x32_bf16 v[52:55], v[144:147], v[160:163], v[52:55]
	v_mfma_f32_16x16x32_bf16 v[48:51], v[152:155], v[160:163], v[48:51]
	v_mfma_f32_16x16x32_bf16 v[36:39], v[144:147], v[168:171], v[36:39]
	v_mfma_f32_16x16x32_bf16 v[32:35], v[152:155], v[168:171], v[32:35]
	v_mfma_f32_16x16x32_bf16 v[20:23], v[144:147], v[176:179], v[20:23]
	v_mfma_f32_16x16x32_bf16 v[16:19], v[152:155], v[176:179], v[16:19]
	v_mfma_f32_16x16x32_bf16 v[4:7], v[144:147], v[184:187], v[4:7]
	v_mfma_f32_16x16x32_bf16 v[0:3], v[152:155], v[184:187], v[0:3]
	v_mfma_f32_16x16x32_bf16 v[52:55], v[148:151], v[164:167], v[52:55]
	v_mfma_f32_16x16x32_bf16 v[48:51], v[156:159], v[164:167], v[48:51]
	v_mfma_f32_16x16x32_bf16 v[36:39], v[148:151], v[172:175], v[36:39]
	v_mfma_f32_16x16x32_bf16 v[32:35], v[156:159], v[172:175], v[32:35]
	s_setprio 3
	s_barrier
	v_mfma_f32_16x16x32_bf16 v[20:23], v[148:151], v[180:183], v[20:23]
	v_mfma_f32_16x16x32_bf16 v[16:19], v[156:159], v[180:183], v[16:19]
	v_mfma_f32_16x16x32_bf16 v[4:7], v[148:151], v[188:191], v[4:7]
	v_mfma_f32_16x16x32_bf16 v[0:3], v[156:159], v[188:191], v[0:3]
	s_setprio 0
	s_add_i32 s66, s66, 2
	s_add_u32 s76, s76, 0x100
	s_addc_u32 s77, s77, 0
	s_add_u32 s56, s56, 0x100
	s_addc_u32 s57, s57, 0
	s_cmp_gt_u32 s66, 13
	s_cbranch_scc0 .LBB0_2037
	s_and_b64 vcc, exec, s[48:49]
	s_cbranch_vccz .LBB0_2040
	s_barrier

.LBB0_2192:
	ds_read_b128 v[146:149], v174
	ds_read_b128 v[150:153], v174 offset:1024
	ds_read_b128 v[154:157], v174 offset:2048
	ds_read_b128 v[158:161], v174 offset:3072
	ds_read_b128 v[162:165], v175
	ds_read_b128 v[178:181], v175 offset:1024
	ds_read_b128 v[182:185], v175 offset:2048
	ds_read_b128 v[186:189], v175 offset:3072
	s_add_u32 s70, s58, 0xfffc0080
	s_addc_u32 s71, s59, -1
	s_cmp_eq_u32 s69, 12
	s_cselect_b32 s73, s47, s71
	s_cselect_b32 s72, s53, s70
	s_cselect_b32 s71, s45, s68
	s_cselect_b32 s70, s66, s67
	v_lshl_add_u64 v[166:167], s[58:59], 0, v[136:137]
	s_add_i32 m0, s17, 0xc000
	ds_read_b128 v[190:193], v176
	ds_read_b128 v[194:197], v176 offset:1024
	ds_read_b128 v[198:201], v176 offset:2048
	ds_read_b128 v[202:205], v176 offset:3072
	ds_read_b128 v[206:209], v176 offset:4096
	ds_read_b128 v[210:213], v176 offset:5120
	ds_read_b128 v[214:217], v176 offset:6144
	ds_read_b128 v[218:221], v176 offset:7168
	global_load_lds_dwordx4 v[166:167], off
	v_lshl_add_u64 v[166:167], s[58:59], 0, v[140:141]
	s_add_i32 m0, s17, 0xe000
	s_nop 0
	global_load_lds_dwordx4 v[166:167], off
	s_waitcnt vmcnt(8)
	s_waitcnt lgkmcnt(0)
	s_barrier
	s_setprio 1
	s_waitcnt lgkmcnt(0)
	v_mfma_f32_16x16x32_bf16 v[124:127], v[146:149], v[190:193], v[124:127]
	v_mfma_f32_16x16x32_bf16 v[116:119], v[154:157], v[190:193], v[116:119]
	v_mfma_f32_16x16x32_bf16 v[108:111], v[146:149], v[198:201], v[108:111]
	v_mfma_f32_16x16x32_bf16 v[100:103], v[154:157], v[198:201], v[100:103]
	v_mfma_f32_16x16x32_bf16 v[92:95], v[146:149], v[206:209], v[92:95]
	v_mfma_f32_16x16x32_bf16 v[84:87], v[154:157], v[206:209], v[84:87]
	v_mfma_f32_16x16x32_bf16 v[76:79], v[146:149], v[214:217], v[76:79]
	v_mfma_f32_16x16x32_bf16 v[68:71], v[154:157], v[214:217], v[68:71]
	v_mfma_f32_16x16x32_bf16 v[124:127], v[150:153], v[194:197], v[124:127]
	v_mfma_f32_16x16x32_bf16 v[116:119], v[158:161], v[194:197], v[116:119]
	v_mfma_f32_16x16x32_bf16 v[108:111], v[150:153], v[202:205], v[108:111]
	v_mfma_f32_16x16x32_bf16 v[100:103], v[158:161], v[202:205], v[100:103]
	v_mfma_f32_16x16x32_bf16 v[92:95], v[150:153], v[210:213], v[92:95]
	v_mfma_f32_16x16x32_bf16 v[84:87], v[158:161], v[210:213], v[84:87]
	v_mfma_f32_16x16x32_bf16 v[76:79], v[150:153], v[218:221], v[76:79]
	v_mfma_f32_16x16x32_bf16 v[68:71], v[158:161], v[218:221], v[68:71]
	s_setprio 0
	s_setprio 1
	v_mfma_f32_16x16x32_bf16 v[120:123], v[162:165], v[190:193], v[120:123]
	v_mfma_f32_16x16x32_bf16 v[112:115], v[182:185], v[190:193], v[112:115]
	v_mfma_f32_16x16x32_bf16 v[104:107], v[162:165], v[198:201], v[104:107]
	v_mfma_f32_16x16x32_bf16 v[96:99], v[182:185], v[198:201], v[96:99]
	v_mfma_f32_16x16x32_bf16 v[88:91], v[162:165], v[206:209], v[88:91]
	v_mfma_f32_16x16x32_bf16 v[80:83], v[182:185], v[206:209], v[80:83]
	v_mfma_f32_16x16x32_bf16 v[72:75], v[162:165], v[214:217], v[72:75]
	v_mfma_f32_16x16x32_bf16 v[64:67], v[182:185], v[214:217], v[64:67]
	v_mfma_f32_16x16x32_bf16 v[120:123], v[178:181], v[194:197], v[120:123]
	v_mfma_f32_16x16x32_bf16 v[112:115], v[186:189], v[194:197], v[112:115]
	v_mfma_f32_16x16x32_bf16 v[104:107], v[178:181], v[202:205], v[104:107]
	v_mfma_f32_16x16x32_bf16 v[96:99], v[186:189], v[202:205], v[96:99]
	s_setprio 3
	s_barrier
	v_mfma_f32_16x16x32_bf16 v[88:91], v[178:181], v[210:213], v[88:91]
	v_mfma_f32_16x16x32_bf16 v[80:83], v[186:189], v[210:213], v[80:83]
	v_mfma_f32_16x16x32_bf16 v[72:75], v[178:181], v[218:221], v[72:75]
	v_mfma_f32_16x16x32_bf16 v[64:67], v[186:189], v[218:221], v[64:67]
	s_setprio 0
	s_add_i32 s74, s26, s16
	v_lshl_add_u64 v[166:167], s[70:71], 0, v[132:133]
	s_mov_b32 m0, s74
	ds_read_b128 v[190:193], v176 offset:16384
	ds_read_b128 v[194:197], v176 offset:17408
	ds_read_b128 v[198:201], v176 offset:18432
	ds_read_b128 v[202:205], v176 offset:19456
	ds_read_b128 v[206:209], v176 offset:20480
	ds_read_b128 v[210:213], v176 offset:21504
	ds_read_b128 v[214:217], v176 offset:22528
	ds_read_b128 v[218:221], v176 offset:23552
	global_load_lds_dwordx4 v[166:167], off
	s_add_i32 m0, s74, 0x2000
	s_add_u32 s74, s70, 0x40000
	v_lshl_add_u64 v[222:223], s[70:71], 0, v[128:129]
	s_addc_u32 s75, s71, 0
	s_add_i32 s76, s27, s16
	global_load_lds_dwordx4 v[222:223], off
	v_lshl_add_u64 v[224:225], s[74:75], 0, v[132:133]
	s_mov_b32 m0, s76
	v_lshl_add_u64 v[226:227], s[72:73], 0, v[130:131]
	global_load_lds_dwordx4 v[224:225], off
	v_lshl_add_u64 v[224:225], s[74:75], 0, v[128:129]
	s_add_i32 m0, s76, 0x2000
	s_nop 0
	global_load_lds_dwordx4 v[224:225], off
	v_lshl_add_u64 v[224:225], s[72:73], 0, v[134:135]
	s_mov_b32 m0, s17
	s_nop 0
	global_load_lds_dwordx4 v[224:225], off
	s_mov_b32 m0, s18
	s_nop 0
	global_load_lds_dwordx4 v[226:227], off
	s_waitcnt vmcnt(8)
	s_waitcnt lgkmcnt(0)
	s_barrier
	s_setprio 1
	s_waitcnt lgkmcnt(0)
	v_mfma_f32_16x16x32_bf16 v[60:63], v[146:149], v[190:193], v[60:63]
	v_mfma_f32_16x16x32_bf16 v[52:55], v[154:157], v[190:193], v[52:55]
	v_mfma_f32_16x16x32_bf16 v[44:47], v[146:149], v[198:201], v[44:47]
	v_mfma_f32_16x16x32_bf16 v[36:39], v[154:157], v[198:201], v[36:39]
	v_mfma_f32_16x16x32_bf16 v[28:31], v[146:149], v[206:209], v[28:31]
	v_mfma_f32_16x16x32_bf16 v[20:23], v[154:157], v[206:209], v[20:23]
	v_mfma_f32_16x16x32_bf16 v[12:15], v[146:149], v[214:217], v[12:15]
	v_mfma_f32_16x16x32_bf16 v[4:7], v[154:157], v[214:217], v[4:7]
	v_mfma_f32_16x16x32_bf16 v[60:63], v[150:153], v[194:197], v[60:63]
	v_mfma_f32_16x16x32_bf16 v[52:55], v[158:161], v[194:197], v[52:55]
	v_mfma_f32_16x16x32_bf16 v[44:47], v[150:153], v[202:205], v[44:47]
	v_mfma_f32_16x16x32_bf16 v[36:39], v[158:161], v[202:205], v[36:39]
	v_mfma_f32_16x16x32_bf16 v[28:31], v[150:153], v[210:213], v[28:31]
	v_mfma_f32_16x16x32_bf16 v[20:23], v[158:161], v[210:213], v[20:23]
	v_mfma_f32_16x16x32_bf16 v[12:15], v[150:153], v[218:221], v[12:15]
	v_mfma_f32_16x16x32_bf16 v[4:7], v[158:161], v[218:221], v[4:7]
	s_setprio 0
	s_setprio 1
	v_mfma_f32_16x16x32_bf16 v[56:59], v[162:165], v[190:193], v[56:59]
	v_mfma_f32_16x16x32_bf16 v[48:51], v[182:185], v[190:193], v[48:51]
	v_mfma_f32_16x16x32_bf16 v[40:43], v[162:165], v[198:201], v[40:43]
	v_mfma_f32_16x16x32_bf16 v[32:35], v[182:185], v[198:201], v[32:35]
	v_mfma_f32_16x16x32_bf16 v[24:27], v[162:165], v[206:209], v[24:27]
	v_mfma_f32_16x16x32_bf16 v[16:19], v[182:185], v[206:209], v[16:19]
	v_mfma_f32_16x16x32_bf16 v[8:11], v[162:165], v[214:217], v[8:11]
	v_mfma_f32_16x16x32_bf16 v[0:3], v[182:185], v[214:217], v[0:3]
	v_mfma_f32_16x16x32_bf16 v[56:59], v[178:181], v[194:197], v[56:59]
	v_mfma_f32_16x16x32_bf16 v[48:51], v[186:189], v[194:197], v[48:51]
	v_mfma_f32_16x16x32_bf16 v[40:43], v[178:181], v[202:205], v[40:43]
	v_mfma_f32_16x16x32_bf16 v[32:35], v[186:189], v[202:205], v[32:35]
	s_setprio 3
	s_barrier
	v_mfma_f32_16x16x32_bf16 v[24:27], v[178:181], v[210:213], v[24:27]
	v_mfma_f32_16x16x32_bf16 v[16:19], v[186:189], v[210:213], v[16:19]
	v_mfma_f32_16x16x32_bf16 v[8:11], v[178:181], v[218:221], v[8:11]
	v_mfma_f32_16x16x32_bf16 v[0:3], v[186:189], v[218:221], v[0:3]
	s_setprio 0
	s_add_i32 s74, 0, 0x18000
	s_add_i32 s75, 0, 0x1c000
	v_add_u32_e32 v158, s74, v171
	v_add_u32_e32 v186, s75, v171
	ds_read_b128 v[146:149], v158
	ds_read_b128 v[150:153], v158 offset:1024
	ds_read_b128 v[154:157], v158 offset:2048
	ds_read_b128 v[158:161], v158 offset:3072
	ds_read_b128 v[162:165], v186
	ds_read_b128 v[178:181], v186 offset:1024
	ds_read_b128 v[182:185], v186 offset:2048
	ds_read_b128 v[186:189], v186 offset:3072
	s_add_u32 s72, s72, 0x40000
	s_addc_u32 s73, s73, 0
	s_mov_b32 m0, s19
	v_lshl_add_u64 v[228:229], s[72:73], 0, v[134:135]
	ds_read_b128 v[190:193], v176 offset:32768
	ds_read_b128 v[194:197], v176 offset:33792
	ds_read_b128 v[198:201], v176 offset:34816
	ds_read_b128 v[202:205], v176 offset:35840
	ds_read_b128 v[206:209], v176 offset:36864
	ds_read_b128 v[210:213], v176 offset:37888
	ds_read_b128 v[214:217], v176 offset:38912
	ds_read_b128 v[218:221], v176 offset:39936
	global_load_lds_dwordx4 v[228:229], off
	v_lshl_add_u64 v[228:229], s[72:73], 0, v[130:131]
	s_mov_b32 m0, s20
	s_nop 0
	global_load_lds_dwordx4 v[228:229], off
	s_waitcnt vmcnt(8)
	s_waitcnt lgkmcnt(0)
	s_barrier
	s_setprio 1
	s_waitcnt lgkmcnt(0)
	v_mfma_f32_16x16x32_bf16 v[124:127], v[146:149], v[190:193], v[124:127]
	v_mfma_f32_16x16x32_bf16 v[116:119], v[154:157], v[190:193], v[116:119]
	v_mfma_f32_16x16x32_bf16 v[108:111], v[146:149], v[198:201], v[108:111]
	v_mfma_f32_16x16x32_bf16 v[100:103], v[154:157], v[198:201], v[100:103]
	v_mfma_f32_16x16x32_bf16 v[92:95], v[146:149], v[206:209], v[92:95]
	v_mfma_f32_16x16x32_bf16 v[84:87], v[154:157], v[206:209], v[84:87]
	v_mfma_f32_16x16x32_bf16 v[76:79], v[146:149], v[214:217], v[76:79]
	v_mfma_f32_16x16x32_bf16 v[68:71], v[154:157], v[214:217], v[68:71]
	v_mfma_f32_16x16x32_bf16 v[124:127], v[150:153], v[194:197], v[124:127]
	v_mfma_f32_16x16x32_bf16 v[116:119], v[158:161], v[194:197], v[116:119]
	v_mfma_f32_16x16x32_bf16 v[108:111], v[150:153], v[202:205], v[108:111]
	v_mfma_f32_16x16x32_bf16 v[100:103], v[158:161], v[202:205], v[100:103]
	v_mfma_f32_16x16x32_bf16 v[92:95], v[150:153], v[210:213], v[92:95]
	v_mfma_f32_16x16x32_bf16 v[84:87], v[158:161], v[210:213], v[84:87]
	v_mfma_f32_16x16x32_bf16 v[76:79], v[150:153], v[218:221], v[76:79]
	v_mfma_f32_16x16x32_bf16 v[68:71], v[158:161], v[218:221], v[68:71]
	s_setprio 0
	s_setprio 1
	v_mfma_f32_16x16x32_bf16 v[120:123], v[162:165], v[190:193], v[120:123]
	v_mfma_f32_16x16x32_bf16 v[112:115], v[182:185], v[190:193], v[112:115]
	v_mfma_f32_16x16x32_bf16 v[104:107], v[162:165], v[198:201], v[104:107]
	v_mfma_f32_16x16x32_bf16 v[96:99], v[182:185], v[198:201], v[96:99]
	v_mfma_f32_16x16x32_bf16 v[88:91], v[162:165], v[206:209], v[88:91]
	v_mfma_f32_16x16x32_bf16 v[80:83], v[182:185], v[206:209], v[80:83]
	v_mfma_f32_16x16x32_bf16 v[72:75], v[162:165], v[214:217], v[72:75]
	v_mfma_f32_16x16x32_bf16 v[64:67], v[182:185], v[214:217], v[64:67]
	v_mfma_f32_16x16x32_bf16 v[120:123], v[178:181], v[194:197], v[120:123]
	v_mfma_f32_16x16x32_bf16 v[112:115], v[186:189], v[194:197], v[112:115]
	v_mfma_f32_16x16x32_bf16 v[104:107], v[178:181], v[202:205], v[104:107]
	v_mfma_f32_16x16x32_bf16 v[96:99], v[186:189], v[202:205], v[96:99]
	s_setprio 3
	s_barrier
	v_mfma_f32_16x16x32_bf16 v[88:91], v[178:181], v[210:213], v[88:91]
	v_mfma_f32_16x16x32_bf16 v[80:83], v[186:189], v[210:213], v[80:83]
	v_mfma_f32_16x16x32_bf16 v[72:75], v[178:181], v[218:221], v[72:75]
	v_mfma_f32_16x16x32_bf16 v[64:67], v[186:189], v[218:221], v[64:67]
	s_setprio 0
	s_add_i32 s72, s74, s16
	v_lshl_add_u64 v[166:167], v[166:167], 0, s[10:11]
	s_mov_b32 m0, s72
	ds_read_b128 v[190:193], v176 offset:49152
	ds_read_b128 v[194:197], v176 offset:50176
	ds_read_b128 v[198:201], v176 offset:51200
	ds_read_b128 v[202:205], v176 offset:52224
	ds_read_b128 v[206:209], v176 offset:53248
	ds_read_b128 v[210:213], v176 offset:54272
	ds_read_b128 v[214:217], v176 offset:55296
	ds_read_b128 v[218:221], v176 offset:56320
	global_load_lds_dwordx4 v[166:167], off
	s_add_i32 m0, s72, 0x2000
	s_add_u32 s70, s70, 0x40080
	v_lshl_add_u64 v[166:167], v[222:223], 0, s[10:11]
	s_addc_u32 s71, s71, 0
	s_add_i32 s72, s75, s16
	global_load_lds_dwordx4 v[166:167], off
	v_lshl_add_u64 v[166:167], s[70:71], 0, v[132:133]
	s_mov_b32 m0, s72
	s_nop 0
	global_load_lds_dwordx4 v[166:167], off
	v_lshl_add_u64 v[166:167], s[70:71], 0, v[128:129]
	s_add_i32 m0, s72, 0x2000
	s_nop 0
	global_load_lds_dwordx4 v[166:167], off
	v_lshl_add_u64 v[166:167], v[224:225], 0, s[10:11]
	s_mov_b32 m0, s23
	s_nop 0
	global_load_lds_dwordx4 v[166:167], off
	v_lshl_add_u64 v[166:167], v[226:227], 0, s[10:11]
	s_mov_b32 m0, s24
	s_nop 0
	global_load_lds_dwordx4 v[166:167], off
	s_waitcnt vmcnt(8)
	s_waitcnt lgkmcnt(0)
	s_barrier
	s_setprio 1
	s_waitcnt lgkmcnt(0)
	v_mfma_f32_16x16x32_bf16 v[60:63], v[146:149], v[190:193], v[60:63]
	v_mfma_f32_16x16x32_bf16 v[52:55], v[154:157], v[190:193], v[52:55]
	v_mfma_f32_16x16x32_bf16 v[44:47], v[146:149], v[198:201], v[44:47]
	v_mfma_f32_16x16x32_bf16 v[36:39], v[154:157], v[198:201], v[36:39]
	v_mfma_f32_16x16x32_bf16 v[28:31], v[146:149], v[206:209], v[28:31]
	v_mfma_f32_16x16x32_bf16 v[20:23], v[154:157], v[206:209], v[20:23]
	v_mfma_f32_16x16x32_bf16 v[12:15], v[146:149], v[214:217], v[12:15]
	v_mfma_f32_16x16x32_bf16 v[4:7], v[154:157], v[214:217], v[4:7]
	v_mfma_f32_16x16x32_bf16 v[60:63], v[150:153], v[194:197], v[60:63]
	v_mfma_f32_16x16x32_bf16 v[52:55], v[158:161], v[194:197], v[52:55]
	v_mfma_f32_16x16x32_bf16 v[44:47], v[150:153], v[202:205], v[44:47]
	v_mfma_f32_16x16x32_bf16 v[36:39], v[158:161], v[202:205], v[36:39]
	v_mfma_f32_16x16x32_bf16 v[28:31], v[150:153], v[210:213], v[28:31]
	v_mfma_f32_16x16x32_bf16 v[20:23], v[158:161], v[210:213], v[20:23]
	v_mfma_f32_16x16x32_bf16 v[12:15], v[150:153], v[218:221], v[12:15]
	v_mfma_f32_16x16x32_bf16 v[4:7], v[158:161], v[218:221], v[4:7]
	s_setprio 0
	s_setprio 1
	v_mfma_f32_16x16x32_bf16 v[56:59], v[162:165], v[190:193], v[56:59]
	v_mfma_f32_16x16x32_bf16 v[48:51], v[182:185], v[190:193], v[48:51]
	v_mfma_f32_16x16x32_bf16 v[40:43], v[162:165], v[198:201], v[40:43]
	v_mfma_f32_16x16x32_bf16 v[32:35], v[182:185], v[198:201], v[32:35]
	v_mfma_f32_16x16x32_bf16 v[24:27], v[162:165], v[206:209], v[24:27]
	v_mfma_f32_16x16x32_bf16 v[16:19], v[182:185], v[206:209], v[16:19]
	v_mfma_f32_16x16x32_bf16 v[8:11], v[162:165], v[214:217], v[8:11]
	v_mfma_f32_16x16x32_bf16 v[0:3], v[182:185], v[214:217], v[0:3]
	v_mfma_f32_16x16x32_bf16 v[56:59], v[178:181], v[194:197], v[56:59]
	v_mfma_f32_16x16x32_bf16 v[48:51], v[186:189], v[194:197], v[48:51]
	v_mfma_f32_16x16x32_bf16 v[40:43], v[178:181], v[202:205], v[40:43]
	v_mfma_f32_16x16x32_bf16 v[32:35], v[186:189], v[202:205], v[32:35]
	s_setprio 3
	s_barrier
	v_mfma_f32_16x16x32_bf16 v[24:27], v[178:181], v[210:213], v[24:27]
	v_mfma_f32_16x16x32_bf16 v[16:19], v[186:189], v[210:213], v[16:19]
	v_mfma_f32_16x16x32_bf16 v[8:11], v[178:181], v[218:221], v[8:11]
	v_mfma_f32_16x16x32_bf16 v[0:3], v[186:189], v[218:221], v[0:3]
	s_setprio 0
	s_add_i32 s69, s69, 2
	s_add_u32 s58, s58, 0x100
	s_addc_u32 s59, s59, 0
	s_add_u32 s67, s67, 0x100
	s_addc_u32 s68, s68, 0
	s_cmp_gt_u32 s69, 13
	s_cbranch_scc0 .LBB0_2192
	s_and_b64 vcc, exec, s[42:43]
	s_cbranch_vccz .LBB0_2195
	s_barrier

.LBB0_2341:
	ds_read_b128 v[128:131], v197
	ds_read_b128 v[132:135], v197 offset:1024
	ds_read_b128 v[136:139], v197 offset:2048
	ds_read_b128 v[140:143], v197 offset:3072
	ds_read_b128 v[144:147], v198
	ds_read_b128 v[148:151], v198 offset:1024
	ds_read_b128 v[152:155], v198 offset:2048
	ds_read_b128 v[156:159], v198 offset:3072
	s_add_u32 s18, s16, 0xfff50080
	s_addc_u32 s19, s17, -1
	s_cmp_eq_u32 s45, 40
	s_cselect_b32 s21, s5, s19
	s_cselect_b32 s20, s4, s18
	s_cselect_b32 s19, s15, s44
	s_cselect_b32 s18, s14, s43
	v_lshl_add_u64 v[192:193], s[16:17], 0, v[172:173]
	s_add_i32 m0, s25, 0xc000
	ds_read_b128 v[160:163], v199
	ds_read_b128 v[180:183], v199 offset:1024
	ds_read_b128 v[184:187], v199 offset:2048
	ds_read_b128 v[188:191], v199 offset:3072
	ds_read_b128 v[200:203], v199 offset:4096
	ds_read_b128 v[204:207], v199 offset:5120
	ds_read_b128 v[208:211], v199 offset:6144
	ds_read_b128 v[212:215], v199 offset:7168
	global_load_lds_dwordx4 v[192:193], off
	v_lshl_add_u64 v[192:193], s[16:17], 0, v[174:175]
	s_add_i32 m0, s25, 0xe000
	s_nop 0
	global_load_lds_dwordx4 v[192:193], off
	s_waitcnt vmcnt(8)
	s_waitcnt lgkmcnt(0)
	s_barrier
	s_setprio 1
	s_waitcnt lgkmcnt(0)
	v_mfma_f32_16x16x32_bf16 v[124:127], v[128:131], v[160:163], v[124:127]
	v_mfma_f32_16x16x32_bf16 v[120:123], v[136:139], v[160:163], v[120:123]
	v_mfma_f32_16x16x32_bf16 v[108:111], v[128:131], v[184:187], v[108:111]
	v_mfma_f32_16x16x32_bf16 v[104:107], v[136:139], v[184:187], v[104:107]
	v_mfma_f32_16x16x32_bf16 v[96:99], v[128:131], v[200:203], v[96:99]
	v_mfma_f32_16x16x32_bf16 v[88:91], v[136:139], v[200:203], v[88:91]
	v_mfma_f32_16x16x32_bf16 v[80:83], v[128:131], v[208:211], v[80:83]
	v_mfma_f32_16x16x32_bf16 v[72:75], v[136:139], v[208:211], v[72:75]
	v_mfma_f32_16x16x32_bf16 v[124:127], v[132:135], v[180:183], v[124:127]
	v_mfma_f32_16x16x32_bf16 v[120:123], v[140:143], v[180:183], v[120:123]
	v_mfma_f32_16x16x32_bf16 v[108:111], v[132:135], v[188:191], v[108:111]
	v_mfma_f32_16x16x32_bf16 v[104:107], v[140:143], v[188:191], v[104:107]
	v_mfma_f32_16x16x32_bf16 v[96:99], v[132:135], v[204:207], v[96:99]
	v_mfma_f32_16x16x32_bf16 v[88:91], v[140:143], v[204:207], v[88:91]
	v_mfma_f32_16x16x32_bf16 v[80:83], v[132:135], v[212:215], v[80:83]
	v_mfma_f32_16x16x32_bf16 v[72:75], v[140:143], v[212:215], v[72:75]
	s_setprio 0
	s_setprio 1
	v_mfma_f32_16x16x32_bf16 v[116:119], v[144:147], v[160:163], v[116:119]
	v_mfma_f32_16x16x32_bf16 v[112:115], v[152:155], v[160:163], v[112:115]
	v_mfma_f32_16x16x32_bf16 v[100:103], v[144:147], v[184:187], v[100:103]
	v_mfma_f32_16x16x32_bf16 v[92:95], v[152:155], v[184:187], v[92:95]
	v_mfma_f32_16x16x32_bf16 v[84:87], v[144:147], v[200:203], v[84:87]
	v_mfma_f32_16x16x32_bf16 v[76:79], v[152:155], v[200:203], v[76:79]
	v_mfma_f32_16x16x32_bf16 v[68:71], v[144:147], v[208:211], v[68:71]
	v_mfma_f32_16x16x32_bf16 v[64:67], v[152:155], v[208:211], v[64:67]
	v_mfma_f32_16x16x32_bf16 v[116:119], v[148:151], v[180:183], v[116:119]
	v_mfma_f32_16x16x32_bf16 v[112:115], v[156:159], v[180:183], v[112:115]
	v_mfma_f32_16x16x32_bf16 v[100:103], v[148:151], v[188:191], v[100:103]
	v_mfma_f32_16x16x32_bf16 v[92:95], v[156:159], v[188:191], v[92:95]
	s_setprio 3
	s_barrier
	v_mfma_f32_16x16x32_bf16 v[84:87], v[148:151], v[204:207], v[84:87]
	v_mfma_f32_16x16x32_bf16 v[76:79], v[156:159], v[204:207], v[76:79]
	v_mfma_f32_16x16x32_bf16 v[68:71], v[148:151], v[212:215], v[68:71]
	v_mfma_f32_16x16x32_bf16 v[64:67], v[156:159], v[212:215], v[64:67]
	s_setprio 0
	s_add_i32 s46, s37, s24
	v_lshl_add_u64 v[192:193], s[18:19], 0, v[166:167]
	s_mov_b32 m0, s46
	ds_read_b128 v[160:163], v199 offset:16384
	ds_read_b128 v[180:183], v199 offset:17408
	ds_read_b128 v[184:187], v199 offset:18432
	ds_read_b128 v[188:191], v199 offset:19456
	ds_read_b128 v[200:203], v199 offset:20480
	ds_read_b128 v[204:207], v199 offset:21504
	ds_read_b128 v[208:211], v199 offset:22528
	ds_read_b128 v[212:215], v199 offset:23552
	global_load_lds_dwordx4 v[192:193], off
	s_add_i32 m0, s46, 0x2000
	s_add_u32 s46, s18, 0xb0000
	v_lshl_add_u64 v[216:217], s[18:19], 0, v[170:171]
	s_addc_u32 s47, s19, 0
	s_add_i32 s48, s38, s24
	global_load_lds_dwordx4 v[216:217], off
	v_lshl_add_u64 v[218:219], s[46:47], 0, v[166:167]
	s_mov_b32 m0, s48
	v_lshl_add_u64 v[220:221], s[20:21], 0, v[168:169]
	global_load_lds_dwordx4 v[218:219], off
	v_lshl_add_u64 v[218:219], s[46:47], 0, v[170:171]
	s_add_i32 m0, s48, 0x2000
	s_nop 0
	global_load_lds_dwordx4 v[218:219], off
	v_lshl_add_u64 v[218:219], s[20:21], 0, v[164:165]
	s_mov_b32 m0, s25
	s_nop 0
	global_load_lds_dwordx4 v[218:219], off
	s_mov_b32 m0, s26
	s_nop 0
	global_load_lds_dwordx4 v[220:221], off
	s_waitcnt vmcnt(8)
	s_waitcnt lgkmcnt(0)
	s_barrier
	s_setprio 1
	s_waitcnt lgkmcnt(0)
	v_mfma_f32_16x16x32_bf16 v[60:63], v[128:131], v[160:163], v[60:63]
	v_mfma_f32_16x16x32_bf16 v[56:59], v[136:139], v[160:163], v[56:59]
	v_mfma_f32_16x16x32_bf16 v[48:51], v[128:131], v[184:187], v[48:51]
	v_mfma_f32_16x16x32_bf16 v[40:43], v[136:139], v[184:187], v[40:43]
	v_mfma_f32_16x16x32_bf16 v[32:35], v[128:131], v[200:203], v[32:35]
	v_mfma_f32_16x16x32_bf16 v[24:27], v[136:139], v[200:203], v[24:27]
	v_mfma_f32_16x16x32_bf16 v[16:19], v[128:131], v[208:211], v[16:19]
	v_mfma_f32_16x16x32_bf16 v[8:11], v[136:139], v[208:211], v[8:11]
	v_mfma_f32_16x16x32_bf16 v[60:63], v[132:135], v[180:183], v[60:63]
	v_mfma_f32_16x16x32_bf16 v[56:59], v[140:143], v[180:183], v[56:59]
	v_mfma_f32_16x16x32_bf16 v[48:51], v[132:135], v[188:191], v[48:51]
	v_mfma_f32_16x16x32_bf16 v[40:43], v[140:143], v[188:191], v[40:43]
	v_mfma_f32_16x16x32_bf16 v[32:35], v[132:135], v[204:207], v[32:35]
	v_mfma_f32_16x16x32_bf16 v[24:27], v[140:143], v[204:207], v[24:27]
	v_mfma_f32_16x16x32_bf16 v[16:19], v[132:135], v[212:215], v[16:19]
	v_mfma_f32_16x16x32_bf16 v[8:11], v[140:143], v[212:215], v[8:11]
	s_setprio 0
	s_setprio 1
	v_mfma_f32_16x16x32_bf16 v[52:55], v[144:147], v[160:163], v[52:55]
	v_mfma_f32_16x16x32_bf16 v[44:47], v[152:155], v[160:163], v[44:47]
	v_mfma_f32_16x16x32_bf16 v[36:39], v[144:147], v[184:187], v[36:39]
	v_mfma_f32_16x16x32_bf16 v[28:31], v[152:155], v[184:187], v[28:31]
	v_mfma_f32_16x16x32_bf16 v[20:23], v[144:147], v[200:203], v[20:23]
	v_mfma_f32_16x16x32_bf16 v[12:15], v[152:155], v[200:203], v[12:15]
	v_mfma_f32_16x16x32_bf16 v[4:7], v[144:147], v[208:211], v[4:7]
	v_mfma_f32_16x16x32_bf16 v[0:3], v[152:155], v[208:211], v[0:3]
	v_mfma_f32_16x16x32_bf16 v[52:55], v[148:151], v[180:183], v[52:55]
	v_mfma_f32_16x16x32_bf16 v[44:47], v[156:159], v[180:183], v[44:47]
	v_mfma_f32_16x16x32_bf16 v[36:39], v[148:151], v[188:191], v[36:39]
	v_mfma_f32_16x16x32_bf16 v[28:31], v[156:159], v[188:191], v[28:31]
	s_setprio 3
	s_barrier
	v_mfma_f32_16x16x32_bf16 v[20:23], v[148:151], v[204:207], v[20:23]
	v_mfma_f32_16x16x32_bf16 v[12:15], v[156:159], v[204:207], v[12:15]
	v_mfma_f32_16x16x32_bf16 v[4:7], v[148:151], v[212:215], v[4:7]
	v_mfma_f32_16x16x32_bf16 v[0:3], v[156:159], v[212:215], v[0:3]
	s_setprio 0
	s_add_i32 s46, 0, 0x18000
	s_add_i32 s47, 0, 0x1c000
	v_add_u32_e32 v140, s46, v195
	v_add_u32_e32 v156, s47, v195
	ds_read_b128 v[128:131], v140
	ds_read_b128 v[132:135], v140 offset:1024
	ds_read_b128 v[136:139], v140 offset:2048
	ds_read_b128 v[140:143], v140 offset:3072
	ds_read_b128 v[144:147], v156
	ds_read_b128 v[148:151], v156 offset:1024
	ds_read_b128 v[152:155], v156 offset:2048
	ds_read_b128 v[156:159], v156 offset:3072
	s_add_u32 s20, s20, 0xb0000
	s_addc_u32 s21, s21, 0
	s_mov_b32 m0, s27
	v_lshl_add_u64 v[222:223], s[20:21], 0, v[164:165]
	ds_read_b128 v[160:163], v199 offset:32768
	ds_read_b128 v[180:183], v199 offset:33792
	ds_read_b128 v[184:187], v199 offset:34816
	ds_read_b128 v[188:191], v199 offset:35840
	ds_read_b128 v[200:203], v199 offset:36864
	ds_read_b128 v[204:207], v199 offset:37888
	ds_read_b128 v[208:211], v199 offset:38912
	ds_read_b128 v[212:215], v199 offset:39936
	global_load_lds_dwordx4 v[222:223], off
	v_lshl_add_u64 v[222:223], s[20:21], 0, v[168:169]
	s_mov_b32 m0, s28
	s_nop 0
	global_load_lds_dwordx4 v[222:223], off
	s_waitcnt vmcnt(8)
	s_waitcnt lgkmcnt(0)
	s_barrier
	s_setprio 1
	s_waitcnt lgkmcnt(0)
	v_mfma_f32_16x16x32_bf16 v[124:127], v[128:131], v[160:163], v[124:127]
	v_mfma_f32_16x16x32_bf16 v[120:123], v[136:139], v[160:163], v[120:123]
	v_mfma_f32_16x16x32_bf16 v[108:111], v[128:131], v[184:187], v[108:111]
	v_mfma_f32_16x16x32_bf16 v[104:107], v[136:139], v[184:187], v[104:107]
	v_mfma_f32_16x16x32_bf16 v[96:99], v[128:131], v[200:203], v[96:99]
	v_mfma_f32_16x16x32_bf16 v[88:91], v[136:139], v[200:203], v[88:91]
	v_mfma_f32_16x16x32_bf16 v[80:83], v[128:131], v[208:211], v[80:83]
	v_mfma_f32_16x16x32_bf16 v[72:75], v[136:139], v[208:211], v[72:75]
	v_mfma_f32_16x16x32_bf16 v[124:127], v[132:135], v[180:183], v[124:127]
	v_mfma_f32_16x16x32_bf16 v[120:123], v[140:143], v[180:183], v[120:123]
	v_mfma_f32_16x16x32_bf16 v[108:111], v[132:135], v[188:191], v[108:111]
	v_mfma_f32_16x16x32_bf16 v[104:107], v[140:143], v[188:191], v[104:107]
	v_mfma_f32_16x16x32_bf16 v[96:99], v[132:135], v[204:207], v[96:99]
	v_mfma_f32_16x16x32_bf16 v[88:91], v[140:143], v[204:207], v[88:91]
	v_mfma_f32_16x16x32_bf16 v[80:83], v[132:135], v[212:215], v[80:83]
	v_mfma_f32_16x16x32_bf16 v[72:75], v[140:143], v[212:215], v[72:75]
	s_setprio 0
	s_setprio 1
	v_mfma_f32_16x16x32_bf16 v[116:119], v[144:147], v[160:163], v[116:119]
	v_mfma_f32_16x16x32_bf16 v[112:115], v[152:155], v[160:163], v[112:115]
	v_mfma_f32_16x16x32_bf16 v[100:103], v[144:147], v[184:187], v[100:103]
	v_mfma_f32_16x16x32_bf16 v[92:95], v[152:155], v[184:187], v[92:95]
	v_mfma_f32_16x16x32_bf16 v[84:87], v[144:147], v[200:203], v[84:87]
	v_mfma_f32_16x16x32_bf16 v[76:79], v[152:155], v[200:203], v[76:79]
	v_mfma_f32_16x16x32_bf16 v[68:71], v[144:147], v[208:211], v[68:71]
	v_mfma_f32_16x16x32_bf16 v[64:67], v[152:155], v[208:211], v[64:67]
	v_mfma_f32_16x16x32_bf16 v[116:119], v[148:151], v[180:183], v[116:119]
	v_mfma_f32_16x16x32_bf16 v[112:115], v[156:159], v[180:183], v[112:115]
	v_mfma_f32_16x16x32_bf16 v[100:103], v[148:151], v[188:191], v[100:103]
	v_mfma_f32_16x16x32_bf16 v[92:95], v[156:159], v[188:191], v[92:95]
	s_setprio 3
	s_barrier
	v_mfma_f32_16x16x32_bf16 v[84:87], v[148:151], v[204:207], v[84:87]
	v_mfma_f32_16x16x32_bf16 v[76:79], v[156:159], v[204:207], v[76:79]
	v_mfma_f32_16x16x32_bf16 v[68:71], v[148:151], v[212:215], v[68:71]
	v_mfma_f32_16x16x32_bf16 v[64:67], v[156:159], v[212:215], v[64:67]
	s_setprio 0
	s_add_i32 s20, s46, s24
	v_lshl_add_u64 v[192:193], v[192:193], 0, s[8:9]
	s_mov_b32 m0, s20
	ds_read_b128 v[160:163], v199 offset:49152
	ds_read_b128 v[180:183], v199 offset:50176
	ds_read_b128 v[184:187], v199 offset:51200
	ds_read_b128 v[188:191], v199 offset:52224
	ds_read_b128 v[200:203], v199 offset:53248
	ds_read_b128 v[204:207], v199 offset:54272
	ds_read_b128 v[208:211], v199 offset:55296
	ds_read_b128 v[212:215], v199 offset:56320
	global_load_lds_dwordx4 v[192:193], off
	s_add_i32 m0, s20, 0x2000
	s_add_u32 s18, s18, 0xb0080
	v_lshl_add_u64 v[192:193], v[216:217], 0, s[8:9]
	s_addc_u32 s19, s19, 0
	s_add_i32 s20, s47, s24
	global_load_lds_dwordx4 v[192:193], off
	v_lshl_add_u64 v[192:193], s[18:19], 0, v[166:167]
	s_mov_b32 m0, s20
	s_nop 0
	global_load_lds_dwordx4 v[192:193], off
	v_lshl_add_u64 v[192:193], s[18:19], 0, v[170:171]
	s_add_i32 m0, s20, 0x2000
	s_nop 0
	global_load_lds_dwordx4 v[192:193], off
	v_lshl_add_u64 v[192:193], v[218:219], 0, s[8:9]
	s_mov_b32 m0, s33
	s_nop 0
	global_load_lds_dwordx4 v[192:193], off
	v_lshl_add_u64 v[192:193], v[220:221], 0, s[8:9]
	s_mov_b32 m0, s35
	s_nop 0
	global_load_lds_dwordx4 v[192:193], off
	s_waitcnt vmcnt(8)
	s_waitcnt lgkmcnt(0)
	s_barrier
	s_setprio 1
	s_waitcnt lgkmcnt(0)
	v_mfma_f32_16x16x32_bf16 v[60:63], v[128:131], v[160:163], v[60:63]
	v_mfma_f32_16x16x32_bf16 v[56:59], v[136:139], v[160:163], v[56:59]
	v_mfma_f32_16x16x32_bf16 v[48:51], v[128:131], v[184:187], v[48:51]
	v_mfma_f32_16x16x32_bf16 v[40:43], v[136:139], v[184:187], v[40:43]
	v_mfma_f32_16x16x32_bf16 v[32:35], v[128:131], v[200:203], v[32:35]
	v_mfma_f32_16x16x32_bf16 v[24:27], v[136:139], v[200:203], v[24:27]
	v_mfma_f32_16x16x32_bf16 v[16:19], v[128:131], v[208:211], v[16:19]
	v_mfma_f32_16x16x32_bf16 v[8:11], v[136:139], v[208:211], v[8:11]
	v_mfma_f32_16x16x32_bf16 v[60:63], v[132:135], v[180:183], v[60:63]
	v_mfma_f32_16x16x32_bf16 v[56:59], v[140:143], v[180:183], v[56:59]
	v_mfma_f32_16x16x32_bf16 v[48:51], v[132:135], v[188:191], v[48:51]
	v_mfma_f32_16x16x32_bf16 v[40:43], v[140:143], v[188:191], v[40:43]
	v_mfma_f32_16x16x32_bf16 v[32:35], v[132:135], v[204:207], v[32:35]
	v_mfma_f32_16x16x32_bf16 v[24:27], v[140:143], v[204:207], v[24:27]
	v_mfma_f32_16x16x32_bf16 v[16:19], v[132:135], v[212:215], v[16:19]
	v_mfma_f32_16x16x32_bf16 v[8:11], v[140:143], v[212:215], v[8:11]
	s_setprio 0
	s_setprio 1
	v_mfma_f32_16x16x32_bf16 v[52:55], v[144:147], v[160:163], v[52:55]
	v_mfma_f32_16x16x32_bf16 v[44:47], v[152:155], v[160:163], v[44:47]
	v_mfma_f32_16x16x32_bf16 v[36:39], v[144:147], v[184:187], v[36:39]
	v_mfma_f32_16x16x32_bf16 v[28:31], v[152:155], v[184:187], v[28:31]
	v_mfma_f32_16x16x32_bf16 v[20:23], v[144:147], v[200:203], v[20:23]
	v_mfma_f32_16x16x32_bf16 v[12:15], v[152:155], v[200:203], v[12:15]
	v_mfma_f32_16x16x32_bf16 v[4:7], v[144:147], v[208:211], v[4:7]
	v_mfma_f32_16x16x32_bf16 v[0:3], v[152:155], v[208:211], v[0:3]
	v_mfma_f32_16x16x32_bf16 v[52:55], v[148:151], v[180:183], v[52:55]
	v_mfma_f32_16x16x32_bf16 v[44:47], v[156:159], v[180:183], v[44:47]
	v_mfma_f32_16x16x32_bf16 v[36:39], v[148:151], v[188:191], v[36:39]
	v_mfma_f32_16x16x32_bf16 v[28:31], v[156:159], v[188:191], v[28:31]
	s_setprio 3
	s_barrier
	v_mfma_f32_16x16x32_bf16 v[20:23], v[148:151], v[204:207], v[20:23]
	v_mfma_f32_16x16x32_bf16 v[12:15], v[156:159], v[204:207], v[12:15]
	v_mfma_f32_16x16x32_bf16 v[4:7], v[148:151], v[212:215], v[4:7]
	v_mfma_f32_16x16x32_bf16 v[0:3], v[156:159], v[212:215], v[0:3]
	s_setprio 0
	s_add_i32 s45, s45, 2
	s_add_u32 s16, s16, 0x100
	s_addc_u32 s17, s17, 0
	s_add_u32 s43, s43, 0x100
	s_addc_u32 s44, s44, 0
	s_cmp_gt_u32 s45, 41
	s_cbranch_scc0 .LBB0_2341
	s_and_b64 vcc, exec, s[10:11]
	s_cbranch_vccz .LBB0_2344
	s_barrier
